# GEMM main loops: all per-segment s_setprio toggling removed (no priority changes in the K loops)
# baseline (speedup 1.0000x reference)
; #define PG8_STAGE(bufoff, gbase, voff) do { _Pragma("unroll") for (int _i = 0; _i < 2; ++_i) \
;         __builtin_amdgcn_global_load_lds((const unsigned*)((const char*)(gbase) + (voff)[_i]), (LAS unsigned*)(lds + (bufoff) + ldsw + _i * 8192), 16, 0, 0); } while (0)
; #define PG8_LDA(dst, b, h) do { _Pragma("unroll") for (int m = 0; m < 4; ++m) _Pragma("unroll") for (int k = 0; k < 2; ++k) dst[m][k] = *(const LAS bf16x8*)(lds + PG8_SA(b, h) + aoff + m * 2048 + k * 1024); } while (0)
; #define PG8_LDB(dst, b, h) do { _Pragma("unroll") for (int n = 0; n < 2; ++n) _Pragma("unroll") for (int k = 0; k < 2; ++k) dst[n][k] = *(const LAS bf16x8*)(lds + PG8_SB(b, h) + boff + n * 2048 + k * 1024); } while (0)
; #define PG8_MMA(ai, bj, At, Bt) do { __builtin_amdgcn_s_setprio(1); _Pragma("unroll") for (int m = 0; m < 4; ++m) _Pragma("unroll") for (int n = 0; n < 2; ++n) _Pragma("unroll") for (int k = 0; k < 2; ++k) \
;         acc[ai][bj][m][n] = __builtin_amdgcn_mfma_f32_16x16x32_bf16(Bt[n][k], At[m][k], acc[ai][bj][m][n], 0, 0, 0); __builtin_amdgcn_s_setprio(0); } while (0)
; #define PG8_WAIT_V(n) asm volatile("s_waitcnt vmcnt(" #n ")" ::: "memory")
; #define PG8_WAIT_L(n) asm volatile("s_waitcnt lgkmcnt(" #n ")" ::: "memory")
; #define PG8_BAR __builtin_amdgcn_s_barrier()
; template <class Epi>
; __device__ __forceinline__ void gemm_phase(LAS unsigned char* lds, const Gemm g, const Sched& S, const Epi& E, const int tid) {
;     ...
;         const char* nA = cA; const char* nB = cB; if (has_next) S.ptrs(nxt, nA, nB);
;         for (int t = 0; t < nt; t += 2) {
;             const bool last = (t == nt - 2);
;             const char* a1 = cA + (size_t)(t + 1) * kstep;
;             const char* a2 = last ? nA : cA + (size_t)(t + 2) * kstep; const char* b2 = last ? nB : cB + (size_t)(t + 2) * kstep;
;             const char* a3 = a2 + kstep; const char* b3 = b2 + kstep;
;             PG8_LDB(B0, 0, 0); PG8_LDB(B1, 0, 1); PG8_SCHED; PG8_LDA(At, 0, 0); PG8_STAGE(PG8_SA(1, 1), a1 + hA, voffA);
;             PG8_WAIT_V(8); PG8_WAIT_L(0); PG8_BAR; PG8_MMA(0, 0, At, B0); PG8_MMA(0, 1, At, B1); PG8_BAR; PG8_SCHED;
;             PG8_LDA(At, 0, 1); PG8_STAGE(PG8_SB(0, 0), b2, voffB); PG8_STAGE(PG8_SB(0, 1), b2 + hB, voffB); PG8_STAGE(PG8_SA(0, 0), a2, voffA);
;             PG8_WAIT_V(8); PG8_WAIT_L(0); PG8_BAR; PG8_MMA(1, 0, At, B0); PG8_MMA(1, 1, At, B1); PG8_BAR; PG8_SCHED;
.LBB0_332:
	s_add_u32 s10, s10, 0x40080
	s_addc_u32 s11, s11, 0
	s_add_u32 s9, s74, 0x100
	s_addc_u32 s19, s75, 0
	s_mov_b32 s21, -2
	s_add_u32 s35, s10, 0xfffc0080
	s_addc_u32 s37, s11, -1
	s_add_i32 vcc_lo, 0, 0x10000
	s_cmp_eq_u32 s21, 12
	s_cselect_b32 s77, s23, s37
	s_cselect_b32 s76, s22, s35
	s_cselect_b32 s75, s73, s19
	s_cselect_b32 s74, s72, s9
	s_add_i32 s35, 0, 0x14000
	v_add_u32_e32 v156, vcc_lo, v145
	v_add_u32_e32 v172, s35, v145
	ds_read_b128 v[140:143], v156
	ds_read_b128 v[148:151], v156 offset:1024
	ds_read_b128 v[152:155], v156 offset:2048
	ds_read_b128 v[156:159], v156 offset:3072
	ds_read_b128 v[160:163], v172
	ds_read_b128 v[164:167], v172 offset:1024
	ds_read_b128 v[168:171], v172 offset:2048
	ds_read_b128 v[172:175], v172 offset:3072
	v_lshl_add_u64 v[190:191], s[10:11], 0, v[136:137]
	s_add_i32 m0, s13, 0xc000
	ds_read_b128 v[178:181], v147
	ds_read_b128 v[182:185], v147 offset:1024
	ds_read_b128 v[186:189], v147 offset:2048
	ds_read_b128 v[194:197], v147 offset:3072
	ds_read_b128 v[198:201], v147 offset:4096
	ds_read_b128 v[202:205], v147 offset:5120
	ds_read_b128 v[206:209], v147 offset:6144
	ds_read_b128 v[210:213], v147 offset:7168
	global_load_lds_dwordx4 v[190:191], off
	v_lshl_add_u64 v[190:191], s[10:11], 0, v[138:139]
	s_add_i32 m0, s13, 0xe000
	s_nop 0
	global_load_lds_dwordx4 v[190:191], off
	s_waitcnt vmcnt(8)
	s_waitcnt lgkmcnt(0)
	s_barrier
	s_waitcnt lgkmcnt(0)
	v_mfma_f32_16x16x32_bf16 v[124:127], v[140:143], v[178:181], 0
	v_mfma_f32_16x16x32_bf16 v[120:123], v[152:155], v[178:181], 0
	v_mfma_f32_16x16x32_bf16 v[116:119], v[140:143], v[186:189], 0
	v_mfma_f32_16x16x32_bf16 v[108:111], v[152:155], v[186:189], 0
	v_mfma_f32_16x16x32_bf16 v[92:95], v[140:143], v[198:201], 0
	v_mfma_f32_16x16x32_bf16 v[88:91], v[152:155], v[198:201], 0
	v_mfma_f32_16x16x32_bf16 v[84:87], v[140:143], v[206:209], 0
	v_mfma_f32_16x16x32_bf16 v[76:79], v[152:155], v[206:209], 0
	v_mfma_f32_16x16x32_bf16 v[124:127], v[148:151], v[182:185], v[124:127]
	v_mfma_f32_16x16x32_bf16 v[120:123], v[156:159], v[182:185], v[120:123]
	v_mfma_f32_16x16x32_bf16 v[116:119], v[148:151], v[194:197], v[116:119]
	v_mfma_f32_16x16x32_bf16 v[108:111], v[156:159], v[194:197], v[108:111]
	v_mfma_f32_16x16x32_bf16 v[92:95], v[148:151], v[202:205], v[92:95]
	v_mfma_f32_16x16x32_bf16 v[88:91], v[156:159], v[202:205], v[88:91]
	v_mfma_f32_16x16x32_bf16 v[84:87], v[148:151], v[210:213], v[84:87]
	v_mfma_f32_16x16x32_bf16 v[76:79], v[156:159], v[210:213], v[76:79]
	v_mfma_f32_16x16x32_bf16 v[112:115], v[160:163], v[178:181], 0
	v_mfma_f32_16x16x32_bf16 v[104:107], v[168:171], v[178:181], 0
	v_mfma_f32_16x16x32_bf16 v[100:103], v[160:163], v[186:189], 0
	v_mfma_f32_16x16x32_bf16 v[96:99], v[168:171], v[186:189], 0
	v_mfma_f32_16x16x32_bf16 v[80:83], v[160:163], v[198:201], 0
	v_mfma_f32_16x16x32_bf16 v[72:75], v[168:171], v[198:201], 0
	v_mfma_f32_16x16x32_bf16 v[68:71], v[160:163], v[206:209], 0
	v_mfma_f32_16x16x32_bf16 v[64:67], v[168:171], v[206:209], 0
	v_mfma_f32_16x16x32_bf16 v[112:115], v[164:167], v[182:185], v[112:115]
	v_mfma_f32_16x16x32_bf16 v[104:107], v[172:175], v[182:185], v[104:107]
	v_mfma_f32_16x16x32_bf16 v[100:103], v[164:167], v[194:197], v[100:103]
	v_mfma_f32_16x16x32_bf16 v[96:99], v[172:175], v[194:197], v[96:99]
	v_mfma_f32_16x16x32_bf16 v[80:83], v[164:167], v[202:205], v[80:83]
	v_mfma_f32_16x16x32_bf16 v[72:75], v[172:175], v[202:205], v[72:75]
	v_mfma_f32_16x16x32_bf16 v[68:71], v[164:167], v[210:213], v[68:71]
	v_mfma_f32_16x16x32_bf16 v[64:67], v[172:175], v[210:213], v[64:67]
	s_barrier
	s_add_i32 s37, vcc_lo, s39
	v_lshl_add_u64 v[190:191], s[74:75], 0, v[192:193]
	s_mov_b32 m0, s37
	ds_read_b128 v[178:181], v147 offset:16384
	ds_read_b128 v[182:185], v147 offset:17408
	ds_read_b128 v[186:189], v147 offset:18432
	ds_read_b128 v[194:197], v147 offset:19456
	ds_read_b128 v[198:201], v147 offset:20480
	ds_read_b128 v[202:205], v147 offset:21504
	ds_read_b128 v[206:209], v147 offset:22528
	ds_read_b128 v[210:213], v147 offset:23552
	global_load_lds_dwordx4 v[190:191], off
	s_add_i32 m0, s37, 0x2000
	s_add_u32 vcc_lo, s74, 0x40000
	v_lshl_add_u64 v[214:215], s[74:75], 0, v[132:133]
	s_addc_u32 vcc_hi, s75, 0
	s_add_i32 s35, s35, s39
	global_load_lds_dwordx4 v[214:215], off
	v_lshl_add_u64 v[216:217], vcc, 0, v[192:193]
	s_mov_b32 m0, s35
	v_lshl_add_u64 v[218:219], s[76:77], 0, v[130:131]
	global_load_lds_dwordx4 v[216:217], off
	v_lshl_add_u64 v[216:217], vcc, 0, v[132:133]
	s_add_i32 m0, s35, 0x2000
	s_nop 0
	global_load_lds_dwordx4 v[216:217], off
	v_lshl_add_u64 v[216:217], s[76:77], 0, v[128:129]
	s_mov_b32 m0, s13
	s_nop 0
	global_load_lds_dwordx4 v[216:217], off
	s_mov_b32 m0, s40
	s_nop 0
	global_load_lds_dwordx4 v[218:219], off
	s_waitcnt vmcnt(8)
	s_waitcnt lgkmcnt(0)
	s_barrier
; #define PG8_STAGE(bufoff, gbase, voff) do { _Pragma("unroll") for (int _i = 0; _i < 2; ++_i) \
;         __builtin_amdgcn_global_load_lds((const unsigned*)((const char*)(gbase) + (voff)[_i]), (LAS unsigned*)(lds + (bufoff) + ldsw + _i * 8192), 16, 0, 0); } while (0)
; #define PG8_LDA(dst, b, h) do { _Pragma("unroll") for (int m = 0; m < 4; ++m) _Pragma("unroll") for (int k = 0; k < 2; ++k) dst[m][k] = *(const LAS bf16x8*)(lds + PG8_SA(b, h) + aoff + m * 2048 + k * 1024); } while (0)
; #define PG8_LDB(dst, b, h) do { _Pragma("unroll") for (int n = 0; n < 2; ++n) _Pragma("unroll") for (int k = 0; k < 2; ++k) dst[n][k] = *(const LAS bf16x8*)(lds + PG8_SB(b, h) + boff + n * 2048 + k * 1024); } while (0)
; #define PG8_MMA(ai, bj, At, Bt) do { __builtin_amdgcn_s_setprio(1); _Pragma("unroll") for (int m = 0; m < 4; ++m) _Pragma("unroll") for (int n = 0; n < 2; ++n) _Pragma("unroll") for (int k = 0; k < 2; ++k) \
;         acc[ai][bj][m][n] = __builtin_amdgcn_mfma_f32_16x16x32_bf16(Bt[n][k], At[m][k], acc[ai][bj][m][n], 0, 0, 0); __builtin_amdgcn_s_setprio(0); } while (0)
; #define PG8_WAIT_V(n) asm volatile("s_waitcnt vmcnt(" #n ")" ::: "memory")
; #define PG8_WAIT_L(n) asm volatile("s_waitcnt lgkmcnt(" #n ")" ::: "memory")
; #define PG8_BAR __builtin_amdgcn_s_barrier()
; #define PG8_SCHED __builtin_amdgcn_sched_barrier(0)
; template <class Epi>
; __device__ __forceinline__ void gemm_phase(LAS unsigned char* lds, const Gemm g, const Sched& S, const Epi& E, const int tid) {
;     ...
;             PG8_WAIT_V(8); PG8_WAIT_L(0); PG8_BAR; PG8_MMA(1, 0, At, B0); PG8_MMA(1, 1, At, B1); PG8_BAR; PG8_SCHED;
;             PG8_LDB(B0, 1, 0); PG8_LDB(B1, 1, 1); PG8_SCHED; PG8_LDA(At, 1, 0); PG8_STAGE(PG8_SA(0, 1), a2 + hA, voffA);
;             PG8_WAIT_V(8); PG8_WAIT_L(0); PG8_BAR; PG8_MMA(0, 0, At, B0); PG8_MMA(0, 1, At, B1); PG8_BAR; PG8_SCHED;
	s_waitcnt lgkmcnt(0)
	v_mfma_f32_16x16x32_bf16 v[60:63], v[140:143], v[178:181], 0
	v_mfma_f32_16x16x32_bf16 v[56:59], v[152:155], v[178:181], 0
	v_mfma_f32_16x16x32_bf16 v[52:55], v[140:143], v[186:189], 0
	v_mfma_f32_16x16x32_bf16 v[44:47], v[152:155], v[186:189], 0
	v_mfma_f32_16x16x32_bf16 v[28:31], v[140:143], v[198:201], 0
	v_mfma_f32_16x16x32_bf16 v[24:27], v[152:155], v[198:201], 0
	v_mfma_f32_16x16x32_bf16 v[20:23], v[140:143], v[206:209], 0
	v_mfma_f32_16x16x32_bf16 v[12:15], v[152:155], v[206:209], 0
	v_mfma_f32_16x16x32_bf16 v[60:63], v[148:151], v[182:185], v[60:63]
	v_mfma_f32_16x16x32_bf16 v[56:59], v[156:159], v[182:185], v[56:59]
	v_mfma_f32_16x16x32_bf16 v[52:55], v[148:151], v[194:197], v[52:55]
	v_mfma_f32_16x16x32_bf16 v[44:47], v[156:159], v[194:197], v[44:47]
	v_mfma_f32_16x16x32_bf16 v[28:31], v[148:151], v[202:205], v[28:31]
	v_mfma_f32_16x16x32_bf16 v[24:27], v[156:159], v[202:205], v[24:27]
	v_mfma_f32_16x16x32_bf16 v[20:23], v[148:151], v[210:213], v[20:23]
	v_mfma_f32_16x16x32_bf16 v[12:15], v[156:159], v[210:213], v[12:15]
	v_mfma_f32_16x16x32_bf16 v[48:51], v[160:163], v[178:181], 0
	v_mfma_f32_16x16x32_bf16 v[40:43], v[168:171], v[178:181], 0
	v_mfma_f32_16x16x32_bf16 v[36:39], v[160:163], v[186:189], 0
	v_mfma_f32_16x16x32_bf16 v[32:35], v[168:171], v[186:189], 0
	v_mfma_f32_16x16x32_bf16 v[16:19], v[160:163], v[198:201], 0
	v_mfma_f32_16x16x32_bf16 v[8:11], v[168:171], v[198:201], 0
	v_mfma_f32_16x16x32_bf16 v[4:7], v[160:163], v[206:209], 0
	v_mfma_f32_16x16x32_bf16 v[0:3], v[168:171], v[206:209], 0
	v_mfma_f32_16x16x32_bf16 v[48:51], v[164:167], v[182:185], v[48:51]
	v_mfma_f32_16x16x32_bf16 v[40:43], v[172:175], v[182:185], v[40:43]
	v_mfma_f32_16x16x32_bf16 v[36:39], v[164:167], v[194:197], v[36:39]
	v_mfma_f32_16x16x32_bf16 v[32:35], v[172:175], v[194:197], v[32:35]
	v_mfma_f32_16x16x32_bf16 v[16:19], v[164:167], v[202:205], v[16:19]
	v_mfma_f32_16x16x32_bf16 v[8:11], v[172:175], v[202:205], v[8:11]
	v_mfma_f32_16x16x32_bf16 v[4:7], v[164:167], v[210:213], v[4:7]
	v_mfma_f32_16x16x32_bf16 v[0:3], v[172:175], v[210:213], v[0:3]
	s_barrier
	s_add_i32 s35, 0, 0x18000
	s_add_i32 s37, 0, 0x1c000
	v_add_u32_e32 v156, s35, v145
	v_add_u32_e32 v172, s37, v145
	ds_read_b128 v[140:143], v156
	ds_read_b128 v[148:151], v156 offset:1024
	ds_read_b128 v[152:155], v156 offset:2048
	ds_read_b128 v[156:159], v156 offset:3072
	ds_read_b128 v[160:163], v172
	ds_read_b128 v[164:167], v172 offset:1024
	ds_read_b128 v[168:171], v172 offset:2048
	ds_read_b128 v[172:175], v172 offset:3072
	s_add_u32 s76, s76, 0x40000
	s_addc_u32 s77, s77, 0
	s_mov_b32 m0, s45
	v_lshl_add_u64 v[224:225], s[76:77], 0, v[128:129]
	ds_read_b128 v[178:181], v147 offset:32768
	ds_read_b128 v[182:185], v147 offset:33792
	ds_read_b128 v[186:189], v147 offset:34816
	ds_read_b128 v[194:197], v147 offset:35840
	ds_read_b128 v[198:201], v147 offset:36864
	ds_read_b128 v[202:205], v147 offset:37888
	ds_read_b128 v[206:209], v147 offset:38912
	ds_read_b128 v[210:213], v147 offset:39936
	global_load_lds_dwordx4 v[224:225], off
	v_lshl_add_u64 v[224:225], s[76:77], 0, v[130:131]
	s_mov_b32 m0, s47
	s_nop 0
	global_load_lds_dwordx4 v[224:225], off
	s_waitcnt vmcnt(8)
	s_waitcnt lgkmcnt(0)
	s_barrier
	s_waitcnt lgkmcnt(0)
	v_mfma_f32_16x16x32_bf16 v[124:127], v[140:143], v[178:181], v[124:127]
	v_mfma_f32_16x16x32_bf16 v[120:123], v[152:155], v[178:181], v[120:123]
	v_mfma_f32_16x16x32_bf16 v[116:119], v[140:143], v[186:189], v[116:119]
	v_mfma_f32_16x16x32_bf16 v[108:111], v[152:155], v[186:189], v[108:111]
	v_mfma_f32_16x16x32_bf16 v[92:95], v[140:143], v[198:201], v[92:95]
	v_mfma_f32_16x16x32_bf16 v[88:91], v[152:155], v[198:201], v[88:91]
	v_mfma_f32_16x16x32_bf16 v[84:87], v[140:143], v[206:209], v[84:87]
	v_mfma_f32_16x16x32_bf16 v[76:79], v[152:155], v[206:209], v[76:79]
	v_mfma_f32_16x16x32_bf16 v[124:127], v[148:151], v[182:185], v[124:127]
	v_mfma_f32_16x16x32_bf16 v[120:123], v[156:159], v[182:185], v[120:123]
	v_mfma_f32_16x16x32_bf16 v[116:119], v[148:151], v[194:197], v[116:119]
	v_mfma_f32_16x16x32_bf16 v[108:111], v[156:159], v[194:197], v[108:111]
	v_mfma_f32_16x16x32_bf16 v[92:95], v[148:151], v[202:205], v[92:95]
	v_mfma_f32_16x16x32_bf16 v[88:91], v[156:159], v[202:205], v[88:91]
	v_mfma_f32_16x16x32_bf16 v[84:87], v[148:151], v[210:213], v[84:87]
	v_mfma_f32_16x16x32_bf16 v[76:79], v[156:159], v[210:213], v[76:79]
	v_mfma_f32_16x16x32_bf16 v[112:115], v[160:163], v[178:181], v[112:115]
	v_mfma_f32_16x16x32_bf16 v[104:107], v[168:171], v[178:181], v[104:107]
	v_mfma_f32_16x16x32_bf16 v[100:103], v[160:163], v[186:189], v[100:103]
	v_mfma_f32_16x16x32_bf16 v[96:99], v[168:171], v[186:189], v[96:99]
	v_mfma_f32_16x16x32_bf16 v[80:83], v[160:163], v[198:201], v[80:83]
	v_mfma_f32_16x16x32_bf16 v[72:75], v[168:171], v[198:201], v[72:75]
	v_mfma_f32_16x16x32_bf16 v[68:71], v[160:163], v[206:209], v[68:71]
	v_mfma_f32_16x16x32_bf16 v[64:67], v[168:171], v[206:209], v[64:67]
	v_mfma_f32_16x16x32_bf16 v[112:115], v[164:167], v[182:185], v[112:115]
	v_mfma_f32_16x16x32_bf16 v[104:107], v[172:175], v[182:185], v[104:107]
	v_mfma_f32_16x16x32_bf16 v[100:103], v[164:167], v[194:197], v[100:103]
	v_mfma_f32_16x16x32_bf16 v[96:99], v[172:175], v[194:197], v[96:99]
	v_mfma_f32_16x16x32_bf16 v[80:83], v[164:167], v[202:205], v[80:83]
	v_mfma_f32_16x16x32_bf16 v[72:75], v[172:175], v[202:205], v[72:75]
	v_mfma_f32_16x16x32_bf16 v[68:71], v[164:167], v[210:213], v[68:71]
	v_mfma_f32_16x16x32_bf16 v[64:67], v[172:175], v[210:213], v[64:67]
	s_barrier
; #define PG8_STAGE(bufoff, gbase, voff) do { _Pragma("unroll") for (int _i = 0; _i < 2; ++_i) \
;         __builtin_amdgcn_global_load_lds((const unsigned*)((const char*)(gbase) + (voff)[_i]), (LAS unsigned*)(lds + (bufoff) + ldsw + _i * 8192), 16, 0, 0); } while (0)
; #define PG8_LDA(dst, b, h) do { _Pragma("unroll") for (int m = 0; m < 4; ++m) _Pragma("unroll") for (int k = 0; k < 2; ++k) dst[m][k] = *(const LAS bf16x8*)(lds + PG8_SA(b, h) + aoff + m * 2048 + k * 1024); } while (0)
; #define PG8_LDB(dst, b, h) do { _Pragma("unroll") for (int n = 0; n < 2; ++n) _Pragma("unroll") for (int k = 0; k < 2; ++k) dst[n][k] = *(const LAS bf16x8*)(lds + PG8_SB(b, h) + boff + n * 2048 + k * 1024); } while (0)
; #define PG8_WAIT_V(n) asm volatile("s_waitcnt vmcnt(" #n ")" ::: "memory")
; #define PG8_WAIT_L(n) asm volatile("s_waitcnt lgkmcnt(" #n ")" ::: "memory")
; template <class Epi>
; __device__ __forceinline__ void gemm_phase(LAS unsigned char* lds, const Gemm g, const Sched& S, const Epi& E, const int tid) {
;     ...
;         for (int t = 0; t < nt; t += 2) {
;             const bool last = (t == nt - 2);
;             const char* a1 = cA + (size_t)(t + 1) * kstep;
;             const char* a2 = last ? nA : cA + (size_t)(t + 2) * kstep; const char* b2 = last ? nB : cB + (size_t)(t + 2) * kstep;
;             const char* a3 = a2 + kstep; const char* b3 = b2 + kstep;
;             PG8_LDB(B0, 0, 0); PG8_LDB(B1, 0, 1); PG8_SCHED; PG8_LDA(At, 0, 0); PG8_STAGE(PG8_SA(1, 1), a1 + hA, voffA);
;             PG8_WAIT_V(8); PG8_WAIT_L(0); PG8_BAR; PG8_MMA(0, 0, At, B0); PG8_MMA(0, 1, At, B1); PG8_BAR; PG8_SCHED;
;             PG8_LDA(At, 0, 1); PG8_STAGE(PG8_SB(0, 0), b2, voffB); PG8_STAGE(PG8_SB(0, 1), b2 + hB, voffB); PG8_STAGE(PG8_SA(0, 0), a2, voffA);
;             PG8_WAIT_V(8); PG8_WAIT_L(0); PG8_BAR; PG8_MMA(1, 0, At, B0); PG8_MMA(1, 1, At, B1); PG8_BAR; PG8_SCHED;
;             PG8_LDB(B0, 1, 0); PG8_LDB(B1, 1, 1); PG8_SCHED; PG8_LDA(At, 1, 0); PG8_STAGE(PG8_SA(0, 1), a2 + hA, voffA);
;             PG8_WAIT_V(8); PG8_WAIT_L(0); PG8_BAR; PG8_MMA(0, 0, At, B0); PG8_MMA(0, 1, At, B1); PG8_BAR; PG8_SCHED;
;             PG8_LDA(At, 1, 1); PG8_STAGE(PG8_SB(1, 0), b3, voffB); PG8_STAGE(PG8_SB(1, 1), b3 + hB, voffB); PG8_STAGE(PG8_SA(1, 0), a3, voffA);
;             PG8_WAIT_V(8); PG8_WAIT_L(0); PG8_BAR; PG8_MMA(1, 0, At, B0); PG8_MMA(1, 1, At, B1); PG8_BAR; PG8_SCHED;
	s_add_i32 s35, s35, s39
	v_lshl_add_u64 v[190:191], v[190:191], 0, s[94:95]
	s_mov_b32 m0, s35
	ds_read_b128 v[178:181], v147 offset:49152
	ds_read_b128 v[182:185], v147 offset:50176
	ds_read_b128 v[186:189], v147 offset:51200
	ds_read_b128 v[194:197], v147 offset:52224
	ds_read_b128 v[198:201], v147 offset:53248
	ds_read_b128 v[202:205], v147 offset:54272
	ds_read_b128 v[206:209], v147 offset:55296
	ds_read_b128 v[210:213], v147 offset:56320
	global_load_lds_dwordx4 v[190:191], off
	s_add_i32 m0, s35, 0x2000
	s_add_u32 s74, s74, 0x40080
	v_lshl_add_u64 v[190:191], v[214:215], 0, s[94:95]
	s_addc_u32 s75, s75, 0
	s_add_i32 s35, s37, s39
	global_load_lds_dwordx4 v[190:191], off
	v_lshl_add_u64 v[190:191], s[74:75], 0, v[192:193]
	s_mov_b32 m0, s35
	s_nop 0
	global_load_lds_dwordx4 v[190:191], off
	v_lshl_add_u64 v[190:191], s[74:75], 0, v[132:133]
	s_add_i32 m0, s35, 0x2000
	s_nop 0
	global_load_lds_dwordx4 v[190:191], off
	v_lshl_add_u64 v[190:191], v[216:217], 0, s[94:95]
	s_mov_b32 m0, s78
	s_nop 0
	global_load_lds_dwordx4 v[190:191], off
	v_lshl_add_u64 v[190:191], v[218:219], 0, s[94:95]
	s_mov_b32 m0, s80
	s_nop 0
	global_load_lds_dwordx4 v[190:191], off
	s_waitcnt vmcnt(8)
	s_waitcnt lgkmcnt(0)
	s_barrier
	s_waitcnt lgkmcnt(0)
	v_mfma_f32_16x16x32_bf16 v[60:63], v[140:143], v[178:181], v[60:63]
	v_mfma_f32_16x16x32_bf16 v[56:59], v[152:155], v[178:181], v[56:59]
	v_mfma_f32_16x16x32_bf16 v[52:55], v[140:143], v[186:189], v[52:55]
	v_mfma_f32_16x16x32_bf16 v[44:47], v[152:155], v[186:189], v[44:47]
	v_mfma_f32_16x16x32_bf16 v[28:31], v[140:143], v[198:201], v[28:31]
	v_mfma_f32_16x16x32_bf16 v[24:27], v[152:155], v[198:201], v[24:27]
	v_mfma_f32_16x16x32_bf16 v[20:23], v[140:143], v[206:209], v[20:23]
	v_mfma_f32_16x16x32_bf16 v[12:15], v[152:155], v[206:209], v[12:15]
	v_mfma_f32_16x16x32_bf16 v[60:63], v[148:151], v[182:185], v[60:63]
	v_mfma_f32_16x16x32_bf16 v[56:59], v[156:159], v[182:185], v[56:59]
	v_mfma_f32_16x16x32_bf16 v[52:55], v[148:151], v[194:197], v[52:55]
	v_mfma_f32_16x16x32_bf16 v[44:47], v[156:159], v[194:197], v[44:47]
	v_mfma_f32_16x16x32_bf16 v[28:31], v[148:151], v[202:205], v[28:31]
	v_mfma_f32_16x16x32_bf16 v[24:27], v[156:159], v[202:205], v[24:27]
	v_mfma_f32_16x16x32_bf16 v[20:23], v[148:151], v[210:213], v[20:23]
	v_mfma_f32_16x16x32_bf16 v[12:15], v[156:159], v[210:213], v[12:15]
	v_mfma_f32_16x16x32_bf16 v[48:51], v[160:163], v[178:181], v[48:51]
	v_mfma_f32_16x16x32_bf16 v[40:43], v[168:171], v[178:181], v[40:43]
	v_mfma_f32_16x16x32_bf16 v[36:39], v[160:163], v[186:189], v[36:39]
	v_mfma_f32_16x16x32_bf16 v[32:35], v[168:171], v[186:189], v[32:35]
	v_mfma_f32_16x16x32_bf16 v[16:19], v[160:163], v[198:201], v[16:19]
	v_mfma_f32_16x16x32_bf16 v[8:11], v[168:171], v[198:201], v[8:11]
	v_mfma_f32_16x16x32_bf16 v[4:7], v[160:163], v[206:209], v[4:7]
	v_mfma_f32_16x16x32_bf16 v[0:3], v[168:171], v[206:209], v[0:3]
	v_mfma_f32_16x16x32_bf16 v[48:51], v[164:167], v[182:185], v[48:51]
	v_mfma_f32_16x16x32_bf16 v[40:43], v[172:175], v[182:185], v[40:43]
	v_mfma_f32_16x16x32_bf16 v[36:39], v[164:167], v[194:197], v[36:39]
	v_mfma_f32_16x16x32_bf16 v[32:35], v[172:175], v[194:197], v[32:35]
	v_mfma_f32_16x16x32_bf16 v[16:19], v[164:167], v[202:205], v[16:19]
	v_mfma_f32_16x16x32_bf16 v[8:11], v[172:175], v[202:205], v[8:11]
	v_mfma_f32_16x16x32_bf16 v[4:7], v[164:167], v[210:213], v[4:7]
	v_mfma_f32_16x16x32_bf16 v[0:3], v[172:175], v[210:213], v[0:3]
	s_barrier
	s_add_i32 s21, s21, 2
	s_add_u32 s10, s10, 0x100
	s_addc_u32 s11, s11, 0
	s_add_u32 s9, s9, 0x100
	s_addc_u32 s19, s19, 0
	s_cmp_gt_u32 s21, 13
	s_cbranch_scc1 .Lgk_exit_0
.LBB0_333:
	s_add_u32 s35, s10, 0xfffc0080
	s_addc_u32 s37, s11, -1
	s_add_i32 vcc_lo, 0, 0x10000
	s_cmp_eq_u32 s21, 12
	s_cselect_b32 s77, s23, s37
	s_cselect_b32 s76, s22, s35
	s_cselect_b32 s75, s73, s19
	s_cselect_b32 s74, s72, s9
	s_add_i32 s35, 0, 0x14000
	v_add_u32_e32 v156, vcc_lo, v145
	v_add_u32_e32 v172, s35, v145
	ds_read_b128 v[140:143], v156
	ds_read_b128 v[148:151], v156 offset:1024
	ds_read_b128 v[152:155], v156 offset:2048
	ds_read_b128 v[156:159], v156 offset:3072
	ds_read_b128 v[160:163], v172
	ds_read_b128 v[164:167], v172 offset:1024
	ds_read_b128 v[168:171], v172 offset:2048
	ds_read_b128 v[172:175], v172 offset:3072
	v_lshl_add_u64 v[190:191], s[10:11], 0, v[136:137]
	s_add_i32 m0, s13, 0xc000
	ds_read_b128 v[178:181], v147
	ds_read_b128 v[182:185], v147 offset:1024
	ds_read_b128 v[186:189], v147 offset:2048
	ds_read_b128 v[194:197], v147 offset:3072
	ds_read_b128 v[198:201], v147 offset:4096
	ds_read_b128 v[202:205], v147 offset:5120
	ds_read_b128 v[206:209], v147 offset:6144
	ds_read_b128 v[210:213], v147 offset:7168
	global_load_lds_dwordx4 v[190:191], off
	v_lshl_add_u64 v[190:191], s[10:11], 0, v[138:139]
	s_add_i32 m0, s13, 0xe000
	s_nop 0
	global_load_lds_dwordx4 v[190:191], off
	s_waitcnt vmcnt(8)
	s_waitcnt lgkmcnt(0)
	s_barrier
; #define PG8_STAGE(bufoff, gbase, voff) do { _Pragma("unroll") for (int _i = 0; _i < 2; ++_i) \
;         __builtin_amdgcn_global_load_lds((const unsigned*)((const char*)(gbase) + (voff)[_i]), (LAS unsigned*)(lds + (bufoff) + ldsw + _i * 8192), 16, 0, 0); } while (0)
; #define PG8_LDA(dst, b, h) do { _Pragma("unroll") for (int m = 0; m < 4; ++m) _Pragma("unroll") for (int k = 0; k < 2; ++k) dst[m][k] = *(const LAS bf16x8*)(lds + PG8_SA(b, h) + aoff + m * 2048 + k * 1024); } while (0)
; #define PG8_MMA(ai, bj, At, Bt) do { __builtin_amdgcn_s_setprio(1); _Pragma("unroll") for (int m = 0; m < 4; ++m) _Pragma("unroll") for (int n = 0; n < 2; ++n) _Pragma("unroll") for (int k = 0; k < 2; ++k) \
;         acc[ai][bj][m][n] = __builtin_amdgcn_mfma_f32_16x16x32_bf16(Bt[n][k], At[m][k], acc[ai][bj][m][n], 0, 0, 0); __builtin_amdgcn_s_setprio(0); } while (0)
; #define PG8_WAIT_V(n) asm volatile("s_waitcnt vmcnt(" #n ")" ::: "memory")
; #define PG8_WAIT_L(n) asm volatile("s_waitcnt lgkmcnt(" #n ")" ::: "memory")
; #define PG8_BAR __builtin_amdgcn_s_barrier()
; #define PG8_SCHED __builtin_amdgcn_sched_barrier(0)
; template <class Epi>
; __device__ __forceinline__ void gemm_phase(LAS unsigned char* lds, const Gemm g, const Sched& S, const Epi& E, const int tid) {
;     ...
;             PG8_WAIT_V(8); PG8_WAIT_L(0); PG8_BAR; PG8_MMA(0, 0, At, B0); PG8_MMA(0, 1, At, B1); PG8_BAR; PG8_SCHED;
;             PG8_LDA(At, 0, 1); PG8_STAGE(PG8_SB(0, 0), b2, voffB); PG8_STAGE(PG8_SB(0, 1), b2 + hB, voffB); PG8_STAGE(PG8_SA(0, 0), a2, voffA);
;             PG8_WAIT_V(8); PG8_WAIT_L(0); PG8_BAR; PG8_MMA(1, 0, At, B0); PG8_MMA(1, 1, At, B1); PG8_BAR; PG8_SCHED;
	s_waitcnt lgkmcnt(0)
	v_mfma_f32_16x16x32_bf16 v[124:127], v[140:143], v[178:181], v[124:127]
	v_mfma_f32_16x16x32_bf16 v[120:123], v[152:155], v[178:181], v[120:123]
	v_mfma_f32_16x16x32_bf16 v[116:119], v[140:143], v[186:189], v[116:119]
	v_mfma_f32_16x16x32_bf16 v[108:111], v[152:155], v[186:189], v[108:111]
	v_mfma_f32_16x16x32_bf16 v[92:95], v[140:143], v[198:201], v[92:95]
	v_mfma_f32_16x16x32_bf16 v[88:91], v[152:155], v[198:201], v[88:91]
	v_mfma_f32_16x16x32_bf16 v[84:87], v[140:143], v[206:209], v[84:87]
	v_mfma_f32_16x16x32_bf16 v[76:79], v[152:155], v[206:209], v[76:79]
	v_mfma_f32_16x16x32_bf16 v[124:127], v[148:151], v[182:185], v[124:127]
	v_mfma_f32_16x16x32_bf16 v[120:123], v[156:159], v[182:185], v[120:123]
	v_mfma_f32_16x16x32_bf16 v[116:119], v[148:151], v[194:197], v[116:119]
	v_mfma_f32_16x16x32_bf16 v[108:111], v[156:159], v[194:197], v[108:111]
	v_mfma_f32_16x16x32_bf16 v[92:95], v[148:151], v[202:205], v[92:95]
	v_mfma_f32_16x16x32_bf16 v[88:91], v[156:159], v[202:205], v[88:91]
	v_mfma_f32_16x16x32_bf16 v[84:87], v[148:151], v[210:213], v[84:87]
	v_mfma_f32_16x16x32_bf16 v[76:79], v[156:159], v[210:213], v[76:79]
	v_mfma_f32_16x16x32_bf16 v[112:115], v[160:163], v[178:181], v[112:115]
	v_mfma_f32_16x16x32_bf16 v[104:107], v[168:171], v[178:181], v[104:107]
	v_mfma_f32_16x16x32_bf16 v[100:103], v[160:163], v[186:189], v[100:103]
	v_mfma_f32_16x16x32_bf16 v[96:99], v[168:171], v[186:189], v[96:99]
	v_mfma_f32_16x16x32_bf16 v[80:83], v[160:163], v[198:201], v[80:83]
	v_mfma_f32_16x16x32_bf16 v[72:75], v[168:171], v[198:201], v[72:75]
	v_mfma_f32_16x16x32_bf16 v[68:71], v[160:163], v[206:209], v[68:71]
	v_mfma_f32_16x16x32_bf16 v[64:67], v[168:171], v[206:209], v[64:67]
	v_mfma_f32_16x16x32_bf16 v[112:115], v[164:167], v[182:185], v[112:115]
	v_mfma_f32_16x16x32_bf16 v[104:107], v[172:175], v[182:185], v[104:107]
	v_mfma_f32_16x16x32_bf16 v[100:103], v[164:167], v[194:197], v[100:103]
	v_mfma_f32_16x16x32_bf16 v[96:99], v[172:175], v[194:197], v[96:99]
	v_mfma_f32_16x16x32_bf16 v[80:83], v[164:167], v[202:205], v[80:83]
	v_mfma_f32_16x16x32_bf16 v[72:75], v[172:175], v[202:205], v[72:75]
	v_mfma_f32_16x16x32_bf16 v[68:71], v[164:167], v[210:213], v[68:71]
	v_mfma_f32_16x16x32_bf16 v[64:67], v[172:175], v[210:213], v[64:67]
	s_barrier
	s_add_i32 s37, vcc_lo, s39
	v_lshl_add_u64 v[190:191], s[74:75], 0, v[192:193]
	s_mov_b32 m0, s37
	ds_read_b128 v[178:181], v147 offset:16384
	ds_read_b128 v[182:185], v147 offset:17408
	ds_read_b128 v[186:189], v147 offset:18432
	ds_read_b128 v[194:197], v147 offset:19456
	ds_read_b128 v[198:201], v147 offset:20480
	ds_read_b128 v[202:205], v147 offset:21504
	ds_read_b128 v[206:209], v147 offset:22528
	ds_read_b128 v[210:213], v147 offset:23552
	global_load_lds_dwordx4 v[190:191], off
	s_add_i32 m0, s37, 0x2000
	s_add_u32 vcc_lo, s74, 0x40000
	v_lshl_add_u64 v[214:215], s[74:75], 0, v[132:133]
	s_addc_u32 vcc_hi, s75, 0
	s_add_i32 s35, s35, s39
	global_load_lds_dwordx4 v[214:215], off
	v_lshl_add_u64 v[216:217], vcc, 0, v[192:193]
	s_mov_b32 m0, s35
	v_lshl_add_u64 v[218:219], s[76:77], 0, v[130:131]
	global_load_lds_dwordx4 v[216:217], off
	v_lshl_add_u64 v[216:217], vcc, 0, v[132:133]
	s_add_i32 m0, s35, 0x2000
	s_nop 0
	global_load_lds_dwordx4 v[216:217], off
	v_lshl_add_u64 v[216:217], s[76:77], 0, v[128:129]
	s_mov_b32 m0, s13
	s_nop 0
	global_load_lds_dwordx4 v[216:217], off
	s_mov_b32 m0, s40
	s_nop 0
	global_load_lds_dwordx4 v[218:219], off
	s_waitcnt vmcnt(8)
	s_waitcnt lgkmcnt(0)
	s_barrier
	s_waitcnt lgkmcnt(0)
	v_mfma_f32_16x16x32_bf16 v[60:63], v[140:143], v[178:181], v[60:63]
	v_mfma_f32_16x16x32_bf16 v[56:59], v[152:155], v[178:181], v[56:59]
	v_mfma_f32_16x16x32_bf16 v[52:55], v[140:143], v[186:189], v[52:55]
	v_mfma_f32_16x16x32_bf16 v[44:47], v[152:155], v[186:189], v[44:47]
	v_mfma_f32_16x16x32_bf16 v[28:31], v[140:143], v[198:201], v[28:31]
	v_mfma_f32_16x16x32_bf16 v[24:27], v[152:155], v[198:201], v[24:27]
	v_mfma_f32_16x16x32_bf16 v[20:23], v[140:143], v[206:209], v[20:23]
	v_mfma_f32_16x16x32_bf16 v[12:15], v[152:155], v[206:209], v[12:15]
	v_mfma_f32_16x16x32_bf16 v[60:63], v[148:151], v[182:185], v[60:63]
	v_mfma_f32_16x16x32_bf16 v[56:59], v[156:159], v[182:185], v[56:59]
	v_mfma_f32_16x16x32_bf16 v[52:55], v[148:151], v[194:197], v[52:55]
	v_mfma_f32_16x16x32_bf16 v[44:47], v[156:159], v[194:197], v[44:47]
	v_mfma_f32_16x16x32_bf16 v[28:31], v[148:151], v[202:205], v[28:31]
	v_mfma_f32_16x16x32_bf16 v[24:27], v[156:159], v[202:205], v[24:27]
	v_mfma_f32_16x16x32_bf16 v[20:23], v[148:151], v[210:213], v[20:23]
	v_mfma_f32_16x16x32_bf16 v[12:15], v[156:159], v[210:213], v[12:15]
	v_mfma_f32_16x16x32_bf16 v[48:51], v[160:163], v[178:181], v[48:51]
	v_mfma_f32_16x16x32_bf16 v[40:43], v[168:171], v[178:181], v[40:43]
	v_mfma_f32_16x16x32_bf16 v[36:39], v[160:163], v[186:189], v[36:39]
	v_mfma_f32_16x16x32_bf16 v[32:35], v[168:171], v[186:189], v[32:35]
	v_mfma_f32_16x16x32_bf16 v[16:19], v[160:163], v[198:201], v[16:19]
	v_mfma_f32_16x16x32_bf16 v[8:11], v[168:171], v[198:201], v[8:11]
	v_mfma_f32_16x16x32_bf16 v[4:7], v[160:163], v[206:209], v[4:7]
	v_mfma_f32_16x16x32_bf16 v[0:3], v[168:171], v[206:209], v[0:3]
	v_mfma_f32_16x16x32_bf16 v[48:51], v[164:167], v[182:185], v[48:51]
	v_mfma_f32_16x16x32_bf16 v[40:43], v[172:175], v[182:185], v[40:43]
	v_mfma_f32_16x16x32_bf16 v[36:39], v[164:167], v[194:197], v[36:39]
	v_mfma_f32_16x16x32_bf16 v[32:35], v[172:175], v[194:197], v[32:35]
	v_mfma_f32_16x16x32_bf16 v[16:19], v[164:167], v[202:205], v[16:19]
	v_mfma_f32_16x16x32_bf16 v[8:11], v[172:175], v[202:205], v[8:11]
	v_mfma_f32_16x16x32_bf16 v[4:7], v[164:167], v[210:213], v[4:7]
	v_mfma_f32_16x16x32_bf16 v[0:3], v[172:175], v[210:213], v[0:3]
	s_barrier
; #define PG8_STAGE(bufoff, gbase, voff) do { _Pragma("unroll") for (int _i = 0; _i < 2; ++_i) \
;         __builtin_amdgcn_global_load_lds((const unsigned*)((const char*)(gbase) + (voff)[_i]), (LAS unsigned*)(lds + (bufoff) + ldsw + _i * 8192), 16, 0, 0); } while (0)
; #define PG8_LDA(dst, b, h) do { _Pragma("unroll") for (int m = 0; m < 4; ++m) _Pragma("unroll") for (int k = 0; k < 2; ++k) dst[m][k] = *(const LAS bf16x8*)(lds + PG8_SA(b, h) + aoff + m * 2048 + k * 1024); } while (0)
; #define PG8_LDB(dst, b, h) do { _Pragma("unroll") for (int n = 0; n < 2; ++n) _Pragma("unroll") for (int k = 0; k < 2; ++k) dst[n][k] = *(const LAS bf16x8*)(lds + PG8_SB(b, h) + boff + n * 2048 + k * 1024); } while (0)
; #define PG8_MMA(ai, bj, At, Bt) do { __builtin_amdgcn_s_setprio(1); _Pragma("unroll") for (int m = 0; m < 4; ++m) _Pragma("unroll") for (int n = 0; n < 2; ++n) _Pragma("unroll") for (int k = 0; k < 2; ++k) \
;         acc[ai][bj][m][n] = __builtin_amdgcn_mfma_f32_16x16x32_bf16(Bt[n][k], At[m][k], acc[ai][bj][m][n], 0, 0, 0); __builtin_amdgcn_s_setprio(0); } while (0)
; #define PG8_WAIT_V(n) asm volatile("s_waitcnt vmcnt(" #n ")" ::: "memory")
; #define PG8_WAIT_L(n) asm volatile("s_waitcnt lgkmcnt(" #n ")" ::: "memory")
; #define PG8_BAR __builtin_amdgcn_s_barrier()
; #define PG8_SCHED __builtin_amdgcn_sched_barrier(0)
; template <class Epi>
; __device__ __forceinline__ void gemm_phase(LAS unsigned char* lds, const Gemm g, const Sched& S, const Epi& E, const int tid) {
;     ...
;             PG8_LDB(B0, 1, 0); PG8_LDB(B1, 1, 1); PG8_SCHED; PG8_LDA(At, 1, 0); PG8_STAGE(PG8_SA(0, 1), a2 + hA, voffA);
;             PG8_WAIT_V(8); PG8_WAIT_L(0); PG8_BAR; PG8_MMA(0, 0, At, B0); PG8_MMA(0, 1, At, B1); PG8_BAR; PG8_SCHED;
;             PG8_LDA(At, 1, 1); PG8_STAGE(PG8_SB(1, 0), b3, voffB); PG8_STAGE(PG8_SB(1, 1), b3 + hB, voffB); PG8_STAGE(PG8_SA(1, 0), a3, voffA);
;             PG8_WAIT_V(8); PG8_WAIT_L(0); PG8_BAR; PG8_MMA(1, 0, At, B0); PG8_MMA(1, 1, At, B1); PG8_BAR; PG8_SCHED;
;         }
	s_add_i32 s35, 0, 0x18000
	s_add_i32 s37, 0, 0x1c000
	v_add_u32_e32 v156, s35, v145
	v_add_u32_e32 v172, s37, v145
	ds_read_b128 v[140:143], v156
	ds_read_b128 v[148:151], v156 offset:1024
	ds_read_b128 v[152:155], v156 offset:2048
	ds_read_b128 v[156:159], v156 offset:3072
	ds_read_b128 v[160:163], v172
	ds_read_b128 v[164:167], v172 offset:1024
	ds_read_b128 v[168:171], v172 offset:2048
	ds_read_b128 v[172:175], v172 offset:3072
	s_add_u32 s76, s76, 0x40000
	s_addc_u32 s77, s77, 0
	s_mov_b32 m0, s45
	v_lshl_add_u64 v[224:225], s[76:77], 0, v[128:129]
	ds_read_b128 v[178:181], v147 offset:32768
	ds_read_b128 v[182:185], v147 offset:33792
	ds_read_b128 v[186:189], v147 offset:34816
	ds_read_b128 v[194:197], v147 offset:35840
	ds_read_b128 v[198:201], v147 offset:36864
	ds_read_b128 v[202:205], v147 offset:37888
	ds_read_b128 v[206:209], v147 offset:38912
	ds_read_b128 v[210:213], v147 offset:39936
	global_load_lds_dwordx4 v[224:225], off
	v_lshl_add_u64 v[224:225], s[76:77], 0, v[130:131]
	s_mov_b32 m0, s47
	s_nop 0
	global_load_lds_dwordx4 v[224:225], off
	s_waitcnt vmcnt(8)
	s_waitcnt lgkmcnt(0)
	s_barrier
	s_waitcnt lgkmcnt(0)
	v_mfma_f32_16x16x32_bf16 v[124:127], v[140:143], v[178:181], v[124:127]
	v_mfma_f32_16x16x32_bf16 v[120:123], v[152:155], v[178:181], v[120:123]
	v_mfma_f32_16x16x32_bf16 v[116:119], v[140:143], v[186:189], v[116:119]
	v_mfma_f32_16x16x32_bf16 v[108:111], v[152:155], v[186:189], v[108:111]
	v_mfma_f32_16x16x32_bf16 v[92:95], v[140:143], v[198:201], v[92:95]
	v_mfma_f32_16x16x32_bf16 v[88:91], v[152:155], v[198:201], v[88:91]
	v_mfma_f32_16x16x32_bf16 v[84:87], v[140:143], v[206:209], v[84:87]
	v_mfma_f32_16x16x32_bf16 v[76:79], v[152:155], v[206:209], v[76:79]
	v_mfma_f32_16x16x32_bf16 v[124:127], v[148:151], v[182:185], v[124:127]
	v_mfma_f32_16x16x32_bf16 v[120:123], v[156:159], v[182:185], v[120:123]
	v_mfma_f32_16x16x32_bf16 v[116:119], v[148:151], v[194:197], v[116:119]
	v_mfma_f32_16x16x32_bf16 v[108:111], v[156:159], v[194:197], v[108:111]
	v_mfma_f32_16x16x32_bf16 v[92:95], v[148:151], v[202:205], v[92:95]
	v_mfma_f32_16x16x32_bf16 v[88:91], v[156:159], v[202:205], v[88:91]
	v_mfma_f32_16x16x32_bf16 v[84:87], v[148:151], v[210:213], v[84:87]
	v_mfma_f32_16x16x32_bf16 v[76:79], v[156:159], v[210:213], v[76:79]
	v_mfma_f32_16x16x32_bf16 v[112:115], v[160:163], v[178:181], v[112:115]
	v_mfma_f32_16x16x32_bf16 v[104:107], v[168:171], v[178:181], v[104:107]
	v_mfma_f32_16x16x32_bf16 v[100:103], v[160:163], v[186:189], v[100:103]
	v_mfma_f32_16x16x32_bf16 v[96:99], v[168:171], v[186:189], v[96:99]
	v_mfma_f32_16x16x32_bf16 v[80:83], v[160:163], v[198:201], v[80:83]
	v_mfma_f32_16x16x32_bf16 v[72:75], v[168:171], v[198:201], v[72:75]
	v_mfma_f32_16x16x32_bf16 v[68:71], v[160:163], v[206:209], v[68:71]
	v_mfma_f32_16x16x32_bf16 v[64:67], v[168:171], v[206:209], v[64:67]
	v_mfma_f32_16x16x32_bf16 v[112:115], v[164:167], v[182:185], v[112:115]
	v_mfma_f32_16x16x32_bf16 v[104:107], v[172:175], v[182:185], v[104:107]
	v_mfma_f32_16x16x32_bf16 v[100:103], v[164:167], v[194:197], v[100:103]
	v_mfma_f32_16x16x32_bf16 v[96:99], v[172:175], v[194:197], v[96:99]
	v_mfma_f32_16x16x32_bf16 v[80:83], v[164:167], v[202:205], v[80:83]
	v_mfma_f32_16x16x32_bf16 v[72:75], v[172:175], v[202:205], v[72:75]
	v_mfma_f32_16x16x32_bf16 v[68:71], v[164:167], v[210:213], v[68:71]
	v_mfma_f32_16x16x32_bf16 v[64:67], v[172:175], v[210:213], v[64:67]
	s_barrier
	s_add_i32 s35, s35, s39
	v_lshl_add_u64 v[190:191], v[190:191], 0, s[94:95]
	s_mov_b32 m0, s35
	ds_read_b128 v[178:181], v147 offset:49152
	ds_read_b128 v[182:185], v147 offset:50176
	ds_read_b128 v[186:189], v147 offset:51200
	ds_read_b128 v[194:197], v147 offset:52224
	ds_read_b128 v[198:201], v147 offset:53248
	ds_read_b128 v[202:205], v147 offset:54272
	ds_read_b128 v[206:209], v147 offset:55296
	ds_read_b128 v[210:213], v147 offset:56320
	global_load_lds_dwordx4 v[190:191], off
	s_add_i32 m0, s35, 0x2000
	s_add_u32 s74, s74, 0x40080
	v_lshl_add_u64 v[190:191], v[214:215], 0, s[94:95]
	s_addc_u32 s75, s75, 0
	s_add_i32 s35, s37, s39
	global_load_lds_dwordx4 v[190:191], off
	v_lshl_add_u64 v[190:191], s[74:75], 0, v[192:193]
	s_mov_b32 m0, s35
	s_nop 0
	global_load_lds_dwordx4 v[190:191], off
	v_lshl_add_u64 v[190:191], s[74:75], 0, v[132:133]
	s_add_i32 m0, s35, 0x2000
	s_nop 0
	global_load_lds_dwordx4 v[190:191], off
	v_lshl_add_u64 v[190:191], v[216:217], 0, s[94:95]
	s_mov_b32 m0, s78
	s_nop 0
	global_load_lds_dwordx4 v[190:191], off
	v_lshl_add_u64 v[190:191], v[218:219], 0, s[94:95]
	s_mov_b32 m0, s80
	s_nop 0
	global_load_lds_dwordx4 v[190:191], off
	s_waitcnt vmcnt(8)
	s_waitcnt lgkmcnt(0)
	s_barrier
	s_waitcnt lgkmcnt(0)
	v_mfma_f32_16x16x32_bf16 v[60:63], v[140:143], v[178:181], v[60:63]
	v_mfma_f32_16x16x32_bf16 v[56:59], v[152:155], v[178:181], v[56:59]
	v_mfma_f32_16x16x32_bf16 v[52:55], v[140:143], v[186:189], v[52:55]
	v_mfma_f32_16x16x32_bf16 v[44:47], v[152:155], v[186:189], v[44:47]
	v_mfma_f32_16x16x32_bf16 v[28:31], v[140:143], v[198:201], v[28:31]
	v_mfma_f32_16x16x32_bf16 v[24:27], v[152:155], v[198:201], v[24:27]
	v_mfma_f32_16x16x32_bf16 v[20:23], v[140:143], v[206:209], v[20:23]
	v_mfma_f32_16x16x32_bf16 v[12:15], v[152:155], v[206:209], v[12:15]
	v_mfma_f32_16x16x32_bf16 v[60:63], v[148:151], v[182:185], v[60:63]
	v_mfma_f32_16x16x32_bf16 v[56:59], v[156:159], v[182:185], v[56:59]
	v_mfma_f32_16x16x32_bf16 v[52:55], v[148:151], v[194:197], v[52:55]
	v_mfma_f32_16x16x32_bf16 v[44:47], v[156:159], v[194:197], v[44:47]
	v_mfma_f32_16x16x32_bf16 v[28:31], v[148:151], v[202:205], v[28:31]
	v_mfma_f32_16x16x32_bf16 v[24:27], v[156:159], v[202:205], v[24:27]
	v_mfma_f32_16x16x32_bf16 v[20:23], v[148:151], v[210:213], v[20:23]
	v_mfma_f32_16x16x32_bf16 v[12:15], v[156:159], v[210:213], v[12:15]
	v_mfma_f32_16x16x32_bf16 v[48:51], v[160:163], v[178:181], v[48:51]
	v_mfma_f32_16x16x32_bf16 v[40:43], v[168:171], v[178:181], v[40:43]
	v_mfma_f32_16x16x32_bf16 v[36:39], v[160:163], v[186:189], v[36:39]
	v_mfma_f32_16x16x32_bf16 v[32:35], v[168:171], v[186:189], v[32:35]
	v_mfma_f32_16x16x32_bf16 v[16:19], v[160:163], v[198:201], v[16:19]
	v_mfma_f32_16x16x32_bf16 v[8:11], v[168:171], v[198:201], v[8:11]
	v_mfma_f32_16x16x32_bf16 v[4:7], v[160:163], v[206:209], v[4:7]
	v_mfma_f32_16x16x32_bf16 v[0:3], v[168:171], v[206:209], v[0:3]
	v_mfma_f32_16x16x32_bf16 v[48:51], v[164:167], v[182:185], v[48:51]
	v_mfma_f32_16x16x32_bf16 v[40:43], v[172:175], v[182:185], v[40:43]
	v_mfma_f32_16x16x32_bf16 v[36:39], v[164:167], v[194:197], v[36:39]
	v_mfma_f32_16x16x32_bf16 v[32:35], v[172:175], v[194:197], v[32:35]
	v_mfma_f32_16x16x32_bf16 v[16:19], v[164:167], v[202:205], v[16:19]
	v_mfma_f32_16x16x32_bf16 v[8:11], v[172:175], v[202:205], v[8:11]
	v_mfma_f32_16x16x32_bf16 v[4:7], v[164:167], v[210:213], v[4:7]
	v_mfma_f32_16x16x32_bf16 v[0:3], v[172:175], v[210:213], v[0:3]
	s_barrier
	s_add_i32 s21, s21, 2
	s_add_u32 s10, s10, 0x100
	s_addc_u32 s11, s11, 0
	s_add_u32 s9, s9, 0x100
	s_addc_u32 s19, s19, 0
	s_cmp_gt_u32 s21, 13
	s_cbranch_scc0 .LBB0_333

; #define PG8_STAGE(bufoff, gbase, voff) do { _Pragma("unroll") for (int _i = 0; _i < 2; ++_i) \
;         __builtin_amdgcn_global_load_lds((const unsigned*)((const char*)(gbase) + (voff)[_i]), (LAS unsigned*)(lds + (bufoff) + ldsw + _i * 8192), 16, 0, 0); } while (0)
; #define PG8_LDA(dst, b, h) do { _Pragma("unroll") for (int m = 0; m < 4; ++m) _Pragma("unroll") for (int k = 0; k < 2; ++k) dst[m][k] = *(const LAS bf16x8*)(lds + PG8_SA(b, h) + aoff + m * 2048 + k * 1024); } while (0)
; #define PG8_LDB(dst, b, h) do { _Pragma("unroll") for (int n = 0; n < 2; ++n) _Pragma("unroll") for (int k = 0; k < 2; ++k) dst[n][k] = *(const LAS bf16x8*)(lds + PG8_SB(b, h) + boff + n * 2048 + k * 1024); } while (0)
; #define PG8_MMA(ai, bj, At, Bt) do { __builtin_amdgcn_s_setprio(1); _Pragma("unroll") for (int m = 0; m < 4; ++m) _Pragma("unroll") for (int n = 0; n < 2; ++n) _Pragma("unroll") for (int k = 0; k < 2; ++k) \
;         acc[ai][bj][m][n] = __builtin_amdgcn_mfma_f32_16x16x32_bf16(Bt[n][k], At[m][k], acc[ai][bj][m][n], 0, 0, 0); __builtin_amdgcn_s_setprio(0); } while (0)
; #define PG8_WAIT_V(n) asm volatile("s_waitcnt vmcnt(" #n ")" ::: "memory")
; #define PG8_WAIT_L(n) asm volatile("s_waitcnt lgkmcnt(" #n ")" ::: "memory")
; #define PG8_BAR __builtin_amdgcn_s_barrier()
; template <class Epi>
; __device__ __forceinline__ void gemm_phase(LAS unsigned char* lds, const Gemm g, const Sched& S, const Epi& E, const int tid) {
;     ...
;         const char* nA = cA; const char* nB = cB; if (has_next) S.ptrs(nxt, nA, nB);
;         for (int t = 0; t < nt; t += 2) {
;             const bool last = (t == nt - 2);
;             const char* a1 = cA + (size_t)(t + 1) * kstep;
;             const char* a2 = last ? nA : cA + (size_t)(t + 2) * kstep; const char* b2 = last ? nB : cB + (size_t)(t + 2) * kstep;
;             const char* a3 = a2 + kstep; const char* b3 = b2 + kstep;
;             PG8_LDB(B0, 0, 0); PG8_LDB(B1, 0, 1); PG8_SCHED; PG8_LDA(At, 0, 0); PG8_STAGE(PG8_SA(1, 1), a1 + hA, voffA);
;             PG8_WAIT_V(8); PG8_WAIT_L(0); PG8_BAR; PG8_MMA(0, 0, At, B0); PG8_MMA(0, 1, At, B1); PG8_BAR; PG8_SCHED;
;             PG8_LDA(At, 0, 1); PG8_STAGE(PG8_SB(0, 0), b2, voffB); PG8_STAGE(PG8_SB(0, 1), b2 + hB, voffB); PG8_STAGE(PG8_SA(0, 0), a2, voffA);
;             PG8_WAIT_V(8); PG8_WAIT_L(0); PG8_BAR; PG8_MMA(1, 0, At, B0); PG8_MMA(1, 1, At, B1); PG8_BAR; PG8_SCHED;
.LBB0_993:
	s_add_u32 s13, s18, 0x100
	s_addc_u32 s40, s19, 0
	s_mov_b32 s42, -2
	s_add_u32 s18, s16, 0x100
	s_addc_u32 s19, s17, 0
	s_add_i32 s45, 0, 0x10000
	s_cmp_eq_u32 s42, 4
	s_cselect_b32 s23, s7, s19
	s_cselect_b32 s22, s6, s18
	s_cselect_b32 s21, s15, s40
	s_cselect_b32 s20, s14, s13
	s_add_i32 s51, 0, 0x14000
	v_add_u32_e32 v128, s45, v183
	v_add_u32_e32 v156, s51, v183
	ds_read_b128 v[104:107], v128
	ds_read_b128 v[112:115], v128 offset:1024
	ds_read_b128 v[124:127], v128 offset:2048
	ds_read_b128 v[128:131], v128 offset:3072
	ds_read_b128 v[136:139], v156
	ds_read_b128 v[144:147], v156 offset:1024
	ds_read_b128 v[152:155], v156 offset:2048
	ds_read_b128 v[156:159], v156 offset:3072
	v_lshl_add_u64 v[190:191], s[16:17], 0, v[166:167]
	s_add_i32 m0, s73, 0xc000
	ds_read_b128 v[170:173], v185
	ds_read_b128 v[174:177], v185 offset:1024
	ds_read_b128 v[178:181], v185 offset:2048
	ds_read_b128 v[186:189], v185 offset:3072
	ds_read_b128 v[194:197], v185 offset:4096
	ds_read_b128 v[198:201], v185 offset:5120
	ds_read_b128 v[204:207], v185 offset:6144
	ds_read_b128 v[208:211], v185 offset:7168
	global_load_lds_dwordx4 v[190:191], off
	v_lshl_add_u64 v[190:191], s[16:17], 0, v[168:169]
	s_add_i32 m0, s73, 0xe000
	s_nop 0
	global_load_lds_dwordx4 v[190:191], off
	s_waitcnt vmcnt(8)
	s_waitcnt lgkmcnt(0)
	s_barrier
	s_waitcnt lgkmcnt(0)
	v_mfma_f32_16x16x32_bf16 v[148:151], v[104:107], v[170:173], 0
	v_mfma_f32_16x16x32_bf16 v[140:143], v[124:127], v[170:173], 0
	v_mfma_f32_16x16x32_bf16 v[116:119], v[104:107], v[178:181], 0
	v_mfma_f32_16x16x32_bf16 v[108:111], v[124:127], v[178:181], 0
	v_mfma_f32_16x16x32_bf16 v[92:95], v[104:107], v[194:197], 0
	v_mfma_f32_16x16x32_bf16 v[88:91], v[124:127], v[194:197], 0
	v_mfma_f32_16x16x32_bf16 v[76:79], v[104:107], v[204:207], 0
	v_mfma_f32_16x16x32_bf16 v[72:75], v[124:127], v[204:207], 0
	v_mfma_f32_16x16x32_bf16 v[148:151], v[112:115], v[174:177], v[148:151]
	v_mfma_f32_16x16x32_bf16 v[140:143], v[128:131], v[174:177], v[140:143]
	v_mfma_f32_16x16x32_bf16 v[116:119], v[112:115], v[186:189], v[116:119]
	v_mfma_f32_16x16x32_bf16 v[108:111], v[128:131], v[186:189], v[108:111]
	v_mfma_f32_16x16x32_bf16 v[92:95], v[112:115], v[198:201], v[92:95]
	v_mfma_f32_16x16x32_bf16 v[88:91], v[128:131], v[198:201], v[88:91]
	v_mfma_f32_16x16x32_bf16 v[76:79], v[112:115], v[208:211], v[76:79]
	v_mfma_f32_16x16x32_bf16 v[72:75], v[128:131], v[208:211], v[72:75]
	v_mfma_f32_16x16x32_bf16 v[132:135], v[136:139], v[170:173], 0
	v_mfma_f32_16x16x32_bf16 v[120:123], v[152:155], v[170:173], 0
	v_mfma_f32_16x16x32_bf16 v[100:103], v[136:139], v[178:181], 0
	v_mfma_f32_16x16x32_bf16 v[96:99], v[152:155], v[178:181], 0
	v_mfma_f32_16x16x32_bf16 v[84:87], v[136:139], v[194:197], 0
	v_mfma_f32_16x16x32_bf16 v[80:83], v[152:155], v[194:197], 0
	v_mfma_f32_16x16x32_bf16 v[68:71], v[136:139], v[204:207], 0
	v_mfma_f32_16x16x32_bf16 v[64:67], v[152:155], v[204:207], 0
	v_mfma_f32_16x16x32_bf16 v[132:135], v[144:147], v[174:177], v[132:135]
	v_mfma_f32_16x16x32_bf16 v[120:123], v[156:159], v[174:177], v[120:123]
	v_mfma_f32_16x16x32_bf16 v[100:103], v[144:147], v[186:189], v[100:103]
	v_mfma_f32_16x16x32_bf16 v[96:99], v[156:159], v[186:189], v[96:99]
	v_mfma_f32_16x16x32_bf16 v[84:87], v[144:147], v[198:201], v[84:87]
	v_mfma_f32_16x16x32_bf16 v[80:83], v[156:159], v[198:201], v[80:83]
	v_mfma_f32_16x16x32_bf16 v[68:71], v[144:147], v[208:211], v[68:71]
	v_mfma_f32_16x16x32_bf16 v[64:67], v[156:159], v[208:211], v[64:67]
	s_barrier
	s_add_i32 s16, s45, s47
	v_lshl_add_u64 v[190:191], s[20:21], 0, v[192:193]
	s_mov_b32 m0, s16
	ds_read_b128 v[170:173], v185 offset:16384
	ds_read_b128 v[174:177], v185 offset:17408
	ds_read_b128 v[178:181], v185 offset:18432
	ds_read_b128 v[186:189], v185 offset:19456
	ds_read_b128 v[194:197], v185 offset:20480
	ds_read_b128 v[198:201], v185 offset:21504
	ds_read_b128 v[204:207], v185 offset:22528
	ds_read_b128 v[208:211], v185 offset:23552
	global_load_lds_dwordx4 v[190:191], off
	s_add_i32 m0, s16, 0x2000
	s_add_u32 s16, s20, 0x20000
	v_lshl_add_u64 v[212:213], s[20:21], 0, v[164:165]
	s_addc_u32 s17, s21, 0
	s_add_i32 s45, s51, s47
	global_load_lds_dwordx4 v[212:213], off
	v_lshl_add_u64 v[214:215], s[16:17], 0, v[192:193]
	s_mov_b32 m0, s45
	v_lshl_add_u64 v[216:217], s[22:23], 0, v[162:163]
	global_load_lds_dwordx4 v[214:215], off
	v_lshl_add_u64 v[214:215], s[16:17], 0, v[164:165]
	s_add_i32 m0, s45, 0x2000
	s_nop 0
	global_load_lds_dwordx4 v[214:215], off
	v_lshl_add_u64 v[214:215], s[22:23], 0, v[160:161]
	s_mov_b32 m0, s73
	s_nop 0
	global_load_lds_dwordx4 v[214:215], off
	s_mov_b32 m0, s74
	s_nop 0
	global_load_lds_dwordx4 v[216:217], off
	s_waitcnt vmcnt(8)
	s_waitcnt lgkmcnt(0)
	s_barrier
; #define PG8_STAGE(bufoff, gbase, voff) do { _Pragma("unroll") for (int _i = 0; _i < 2; ++_i) \
;         __builtin_amdgcn_global_load_lds((const unsigned*)((const char*)(gbase) + (voff)[_i]), (LAS unsigned*)(lds + (bufoff) + ldsw + _i * 8192), 16, 0, 0); } while (0)
; #define PG8_LDA(dst, b, h) do { _Pragma("unroll") for (int m = 0; m < 4; ++m) _Pragma("unroll") for (int k = 0; k < 2; ++k) dst[m][k] = *(const LAS bf16x8*)(lds + PG8_SA(b, h) + aoff + m * 2048 + k * 1024); } while (0)
; #define PG8_LDB(dst, b, h) do { _Pragma("unroll") for (int n = 0; n < 2; ++n) _Pragma("unroll") for (int k = 0; k < 2; ++k) dst[n][k] = *(const LAS bf16x8*)(lds + PG8_SB(b, h) + boff + n * 2048 + k * 1024); } while (0)
; #define PG8_MMA(ai, bj, At, Bt) do { __builtin_amdgcn_s_setprio(1); _Pragma("unroll") for (int m = 0; m < 4; ++m) _Pragma("unroll") for (int n = 0; n < 2; ++n) _Pragma("unroll") for (int k = 0; k < 2; ++k) \
;         acc[ai][bj][m][n] = __builtin_amdgcn_mfma_f32_16x16x32_bf16(Bt[n][k], At[m][k], acc[ai][bj][m][n], 0, 0, 0); __builtin_amdgcn_s_setprio(0); } while (0)
; #define PG8_WAIT_V(n) asm volatile("s_waitcnt vmcnt(" #n ")" ::: "memory")
; #define PG8_WAIT_L(n) asm volatile("s_waitcnt lgkmcnt(" #n ")" ::: "memory")
; #define PG8_BAR __builtin_amdgcn_s_barrier()
; #define PG8_SCHED __builtin_amdgcn_sched_barrier(0)
; template <class Epi>
; __device__ __forceinline__ void gemm_phase(LAS unsigned char* lds, const Gemm g, const Sched& S, const Epi& E, const int tid) {
;     ...
;             PG8_WAIT_V(8); PG8_WAIT_L(0); PG8_BAR; PG8_MMA(1, 0, At, B0); PG8_MMA(1, 1, At, B1); PG8_BAR; PG8_SCHED;
;             PG8_LDB(B0, 1, 0); PG8_LDB(B1, 1, 1); PG8_SCHED; PG8_LDA(At, 1, 0); PG8_STAGE(PG8_SA(0, 1), a2 + hA, voffA);
;             PG8_WAIT_V(8); PG8_WAIT_L(0); PG8_BAR; PG8_MMA(0, 0, At, B0); PG8_MMA(0, 1, At, B1); PG8_BAR; PG8_SCHED;
	s_waitcnt lgkmcnt(0)
	v_mfma_f32_16x16x32_bf16 v[60:63], v[104:107], v[170:173], 0
	v_mfma_f32_16x16x32_bf16 v[56:59], v[124:127], v[170:173], 0
	v_mfma_f32_16x16x32_bf16 v[44:47], v[104:107], v[178:181], 0
	v_mfma_f32_16x16x32_bf16 v[40:43], v[124:127], v[178:181], 0
	v_mfma_f32_16x16x32_bf16 v[28:31], v[104:107], v[194:197], 0
	v_mfma_f32_16x16x32_bf16 v[24:27], v[124:127], v[194:197], 0
	v_mfma_f32_16x16x32_bf16 v[12:15], v[104:107], v[204:207], 0
	v_mfma_f32_16x16x32_bf16 v[8:11], v[124:127], v[204:207], 0
	v_mfma_f32_16x16x32_bf16 v[60:63], v[112:115], v[174:177], v[60:63]
	v_mfma_f32_16x16x32_bf16 v[56:59], v[128:131], v[174:177], v[56:59]
	v_mfma_f32_16x16x32_bf16 v[44:47], v[112:115], v[186:189], v[44:47]
	v_mfma_f32_16x16x32_bf16 v[40:43], v[128:131], v[186:189], v[40:43]
	v_mfma_f32_16x16x32_bf16 v[28:31], v[112:115], v[198:201], v[28:31]
	v_mfma_f32_16x16x32_bf16 v[24:27], v[128:131], v[198:201], v[24:27]
	v_mfma_f32_16x16x32_bf16 v[12:15], v[112:115], v[208:211], v[12:15]
	v_mfma_f32_16x16x32_bf16 v[8:11], v[128:131], v[208:211], v[8:11]
	v_mfma_f32_16x16x32_bf16 v[52:55], v[136:139], v[170:173], 0
	v_mfma_f32_16x16x32_bf16 v[48:51], v[152:155], v[170:173], 0
	v_mfma_f32_16x16x32_bf16 v[36:39], v[136:139], v[178:181], 0
	v_mfma_f32_16x16x32_bf16 v[32:35], v[152:155], v[178:181], 0
	v_mfma_f32_16x16x32_bf16 v[20:23], v[136:139], v[194:197], 0
	v_mfma_f32_16x16x32_bf16 v[16:19], v[152:155], v[194:197], 0
	v_mfma_f32_16x16x32_bf16 v[4:7], v[136:139], v[204:207], 0
	v_mfma_f32_16x16x32_bf16 v[0:3], v[152:155], v[204:207], 0
	v_mfma_f32_16x16x32_bf16 v[52:55], v[144:147], v[174:177], v[52:55]
	v_mfma_f32_16x16x32_bf16 v[48:51], v[156:159], v[174:177], v[48:51]
	v_mfma_f32_16x16x32_bf16 v[36:39], v[144:147], v[186:189], v[36:39]
	v_mfma_f32_16x16x32_bf16 v[32:35], v[156:159], v[186:189], v[32:35]
	v_mfma_f32_16x16x32_bf16 v[20:23], v[144:147], v[198:201], v[20:23]
	v_mfma_f32_16x16x32_bf16 v[16:19], v[156:159], v[198:201], v[16:19]
	v_mfma_f32_16x16x32_bf16 v[4:7], v[144:147], v[208:211], v[4:7]
	v_mfma_f32_16x16x32_bf16 v[0:3], v[156:159], v[208:211], v[0:3]
	s_barrier
	s_add_i32 s45, 0, 0x18000
	s_add_i32 s51, 0, 0x1c000
	v_add_u32_e32 v128, s45, v183
	v_add_u32_e32 v156, s51, v183
	ds_read_b128 v[104:107], v128
	ds_read_b128 v[112:115], v128 offset:1024
	ds_read_b128 v[124:127], v128 offset:2048
	ds_read_b128 v[128:131], v128 offset:3072
	ds_read_b128 v[136:139], v156
	ds_read_b128 v[144:147], v156 offset:1024
	ds_read_b128 v[152:155], v156 offset:2048
	ds_read_b128 v[156:159], v156 offset:3072
	s_add_u32 s16, s22, 0x120000
	s_addc_u32 s17, s23, 0
	s_mov_b32 m0, s75
	v_lshl_add_u64 v[218:219], s[16:17], 0, v[160:161]
	ds_read_b128 v[170:173], v185 offset:32768
	ds_read_b128 v[174:177], v185 offset:33792
	ds_read_b128 v[178:181], v185 offset:34816
	ds_read_b128 v[186:189], v185 offset:35840
	ds_read_b128 v[194:197], v185 offset:36864
	ds_read_b128 v[198:201], v185 offset:37888
	ds_read_b128 v[204:207], v185 offset:38912
	ds_read_b128 v[208:211], v185 offset:39936
	global_load_lds_dwordx4 v[218:219], off
	v_lshl_add_u64 v[218:219], s[16:17], 0, v[162:163]
	s_mov_b32 m0, s76
	s_nop 0
	global_load_lds_dwordx4 v[218:219], off
	s_waitcnt vmcnt(8)
	s_waitcnt lgkmcnt(0)
	s_barrier
	s_waitcnt lgkmcnt(0)
	v_mfma_f32_16x16x32_bf16 v[148:151], v[104:107], v[170:173], v[148:151]
	v_mfma_f32_16x16x32_bf16 v[140:143], v[124:127], v[170:173], v[140:143]
	v_mfma_f32_16x16x32_bf16 v[116:119], v[104:107], v[178:181], v[116:119]
	v_mfma_f32_16x16x32_bf16 v[108:111], v[124:127], v[178:181], v[108:111]
	v_mfma_f32_16x16x32_bf16 v[92:95], v[104:107], v[194:197], v[92:95]
	v_mfma_f32_16x16x32_bf16 v[88:91], v[124:127], v[194:197], v[88:91]
	v_mfma_f32_16x16x32_bf16 v[76:79], v[104:107], v[204:207], v[76:79]
	v_mfma_f32_16x16x32_bf16 v[72:75], v[124:127], v[204:207], v[72:75]
	v_mfma_f32_16x16x32_bf16 v[148:151], v[112:115], v[174:177], v[148:151]
	v_mfma_f32_16x16x32_bf16 v[140:143], v[128:131], v[174:177], v[140:143]
	v_mfma_f32_16x16x32_bf16 v[116:119], v[112:115], v[186:189], v[116:119]
	v_mfma_f32_16x16x32_bf16 v[108:111], v[128:131], v[186:189], v[108:111]
	v_mfma_f32_16x16x32_bf16 v[92:95], v[112:115], v[198:201], v[92:95]
	v_mfma_f32_16x16x32_bf16 v[88:91], v[128:131], v[198:201], v[88:91]
	v_mfma_f32_16x16x32_bf16 v[76:79], v[112:115], v[208:211], v[76:79]
	v_mfma_f32_16x16x32_bf16 v[72:75], v[128:131], v[208:211], v[72:75]
	v_mfma_f32_16x16x32_bf16 v[132:135], v[136:139], v[170:173], v[132:135]
	v_mfma_f32_16x16x32_bf16 v[120:123], v[152:155], v[170:173], v[120:123]
	v_mfma_f32_16x16x32_bf16 v[100:103], v[136:139], v[178:181], v[100:103]
	v_mfma_f32_16x16x32_bf16 v[96:99], v[152:155], v[178:181], v[96:99]
	v_mfma_f32_16x16x32_bf16 v[84:87], v[136:139], v[194:197], v[84:87]
	v_mfma_f32_16x16x32_bf16 v[80:83], v[152:155], v[194:197], v[80:83]
	v_mfma_f32_16x16x32_bf16 v[68:71], v[136:139], v[204:207], v[68:71]
	v_mfma_f32_16x16x32_bf16 v[64:67], v[152:155], v[204:207], v[64:67]
	v_mfma_f32_16x16x32_bf16 v[132:135], v[144:147], v[174:177], v[132:135]
	v_mfma_f32_16x16x32_bf16 v[120:123], v[156:159], v[174:177], v[120:123]
	v_mfma_f32_16x16x32_bf16 v[100:103], v[144:147], v[186:189], v[100:103]
	v_mfma_f32_16x16x32_bf16 v[96:99], v[156:159], v[186:189], v[96:99]
	v_mfma_f32_16x16x32_bf16 v[84:87], v[144:147], v[198:201], v[84:87]
	v_mfma_f32_16x16x32_bf16 v[80:83], v[156:159], v[198:201], v[80:83]
	v_mfma_f32_16x16x32_bf16 v[68:71], v[144:147], v[208:211], v[68:71]
	v_mfma_f32_16x16x32_bf16 v[64:67], v[156:159], v[208:211], v[64:67]
	s_barrier
; #define PG8_STAGE(bufoff, gbase, voff) do { _Pragma("unroll") for (int _i = 0; _i < 2; ++_i) \
;         __builtin_amdgcn_global_load_lds((const unsigned*)((const char*)(gbase) + (voff)[_i]), (LAS unsigned*)(lds + (bufoff) + ldsw + _i * 8192), 16, 0, 0); } while (0)
; #define PG8_LDA(dst, b, h) do { _Pragma("unroll") for (int m = 0; m < 4; ++m) _Pragma("unroll") for (int k = 0; k < 2; ++k) dst[m][k] = *(const LAS bf16x8*)(lds + PG8_SA(b, h) + aoff + m * 2048 + k * 1024); } while (0)
; #define PG8_LDB(dst, b, h) do { _Pragma("unroll") for (int n = 0; n < 2; ++n) _Pragma("unroll") for (int k = 0; k < 2; ++k) dst[n][k] = *(const LAS bf16x8*)(lds + PG8_SB(b, h) + boff + n * 2048 + k * 1024); } while (0)
; #define PG8_WAIT_V(n) asm volatile("s_waitcnt vmcnt(" #n ")" ::: "memory")
; #define PG8_WAIT_L(n) asm volatile("s_waitcnt lgkmcnt(" #n ")" ::: "memory")
; template <class Epi>
; __device__ __forceinline__ void gemm_phase(LAS unsigned char* lds, const Gemm g, const Sched& S, const Epi& E, const int tid) {
;     ...
;         for (int t = 0; t < nt; t += 2) {
;             const bool last = (t == nt - 2);
;             const char* a1 = cA + (size_t)(t + 1) * kstep;
;             const char* a2 = last ? nA : cA + (size_t)(t + 2) * kstep; const char* b2 = last ? nB : cB + (size_t)(t + 2) * kstep;
;             const char* a3 = a2 + kstep; const char* b3 = b2 + kstep;
;             PG8_LDB(B0, 0, 0); PG8_LDB(B1, 0, 1); PG8_SCHED; PG8_LDA(At, 0, 0); PG8_STAGE(PG8_SA(1, 1), a1 + hA, voffA);
;             PG8_WAIT_V(8); PG8_WAIT_L(0); PG8_BAR; PG8_MMA(0, 0, At, B0); PG8_MMA(0, 1, At, B1); PG8_BAR; PG8_SCHED;
;             PG8_LDA(At, 0, 1); PG8_STAGE(PG8_SB(0, 0), b2, voffB); PG8_STAGE(PG8_SB(0, 1), b2 + hB, voffB); PG8_STAGE(PG8_SA(0, 0), a2, voffA);
;             PG8_WAIT_V(8); PG8_WAIT_L(0); PG8_BAR; PG8_MMA(1, 0, At, B0); PG8_MMA(1, 1, At, B1); PG8_BAR; PG8_SCHED;
;             PG8_LDB(B0, 1, 0); PG8_LDB(B1, 1, 1); PG8_SCHED; PG8_LDA(At, 1, 0); PG8_STAGE(PG8_SA(0, 1), a2 + hA, voffA);
;             PG8_WAIT_V(8); PG8_WAIT_L(0); PG8_BAR; PG8_MMA(0, 0, At, B0); PG8_MMA(0, 1, At, B1); PG8_BAR; PG8_SCHED;
;             PG8_LDA(At, 1, 1); PG8_STAGE(PG8_SB(1, 0), b3, voffB); PG8_STAGE(PG8_SB(1, 1), b3 + hB, voffB); PG8_STAGE(PG8_SA(1, 0), a3, voffA);
;             PG8_WAIT_V(8); PG8_WAIT_L(0); PG8_BAR; PG8_MMA(1, 0, At, B0); PG8_MMA(1, 1, At, B1); PG8_BAR; PG8_SCHED;
	s_add_i32 s16, s45, s47
	v_lshl_add_u64 v[190:191], v[190:191], 0, s[94:95]
	s_mov_b32 m0, s16
	ds_read_b128 v[170:173], v185 offset:49152
	ds_read_b128 v[174:177], v185 offset:50176
	ds_read_b128 v[178:181], v185 offset:51200
	ds_read_b128 v[186:189], v185 offset:52224
	ds_read_b128 v[194:197], v185 offset:53248
	ds_read_b128 v[198:201], v185 offset:54272
	ds_read_b128 v[204:207], v185 offset:55296
	ds_read_b128 v[208:211], v185 offset:56320
	global_load_lds_dwordx4 v[190:191], off
	s_add_i32 m0, s16, 0x2000
	s_add_u32 s16, s20, 0x20080
	v_lshl_add_u64 v[190:191], v[212:213], 0, s[94:95]
	s_addc_u32 s17, s21, 0
	s_add_i32 s20, s51, s47
	global_load_lds_dwordx4 v[190:191], off
	v_lshl_add_u64 v[190:191], s[16:17], 0, v[192:193]
	s_mov_b32 m0, s20
	s_nop 0
	global_load_lds_dwordx4 v[190:191], off
	v_lshl_add_u64 v[190:191], s[16:17], 0, v[164:165]
	s_add_i32 m0, s20, 0x2000
	s_nop 0
	global_load_lds_dwordx4 v[190:191], off
	v_lshl_add_u64 v[190:191], v[214:215], 0, s[94:95]
	s_mov_b32 m0, s77
	s_nop 0
	global_load_lds_dwordx4 v[190:191], off
	v_lshl_add_u64 v[190:191], v[216:217], 0, s[94:95]
	s_mov_b32 m0, s78
	s_nop 0
	global_load_lds_dwordx4 v[190:191], off
	s_waitcnt vmcnt(8)
	s_waitcnt lgkmcnt(0)
	s_barrier
	s_waitcnt lgkmcnt(0)
	v_mfma_f32_16x16x32_bf16 v[60:63], v[104:107], v[170:173], v[60:63]
	v_mfma_f32_16x16x32_bf16 v[56:59], v[124:127], v[170:173], v[56:59]
	v_mfma_f32_16x16x32_bf16 v[44:47], v[104:107], v[178:181], v[44:47]
	v_mfma_f32_16x16x32_bf16 v[40:43], v[124:127], v[178:181], v[40:43]
	v_mfma_f32_16x16x32_bf16 v[28:31], v[104:107], v[194:197], v[28:31]
	v_mfma_f32_16x16x32_bf16 v[24:27], v[124:127], v[194:197], v[24:27]
	v_mfma_f32_16x16x32_bf16 v[12:15], v[104:107], v[204:207], v[12:15]
	v_mfma_f32_16x16x32_bf16 v[8:11], v[124:127], v[204:207], v[8:11]
	v_mfma_f32_16x16x32_bf16 v[60:63], v[112:115], v[174:177], v[60:63]
	v_mfma_f32_16x16x32_bf16 v[56:59], v[128:131], v[174:177], v[56:59]
	v_mfma_f32_16x16x32_bf16 v[44:47], v[112:115], v[186:189], v[44:47]
	v_mfma_f32_16x16x32_bf16 v[40:43], v[128:131], v[186:189], v[40:43]
	v_mfma_f32_16x16x32_bf16 v[28:31], v[112:115], v[198:201], v[28:31]
	v_mfma_f32_16x16x32_bf16 v[24:27], v[128:131], v[198:201], v[24:27]
	v_mfma_f32_16x16x32_bf16 v[12:15], v[112:115], v[208:211], v[12:15]
	v_mfma_f32_16x16x32_bf16 v[8:11], v[128:131], v[208:211], v[8:11]
	v_mfma_f32_16x16x32_bf16 v[52:55], v[136:139], v[170:173], v[52:55]
	v_mfma_f32_16x16x32_bf16 v[48:51], v[152:155], v[170:173], v[48:51]
	v_mfma_f32_16x16x32_bf16 v[36:39], v[136:139], v[178:181], v[36:39]
	v_mfma_f32_16x16x32_bf16 v[32:35], v[152:155], v[178:181], v[32:35]
	v_mfma_f32_16x16x32_bf16 v[20:23], v[136:139], v[194:197], v[20:23]
	v_mfma_f32_16x16x32_bf16 v[16:19], v[152:155], v[194:197], v[16:19]
	v_mfma_f32_16x16x32_bf16 v[4:7], v[136:139], v[204:207], v[4:7]
	v_mfma_f32_16x16x32_bf16 v[0:3], v[152:155], v[204:207], v[0:3]
	v_mfma_f32_16x16x32_bf16 v[52:55], v[144:147], v[174:177], v[52:55]
	v_mfma_f32_16x16x32_bf16 v[48:51], v[156:159], v[174:177], v[48:51]
	v_mfma_f32_16x16x32_bf16 v[36:39], v[144:147], v[186:189], v[36:39]
	v_mfma_f32_16x16x32_bf16 v[32:35], v[156:159], v[186:189], v[32:35]
	v_mfma_f32_16x16x32_bf16 v[20:23], v[144:147], v[198:201], v[20:23]
	v_mfma_f32_16x16x32_bf16 v[16:19], v[156:159], v[198:201], v[16:19]
	v_mfma_f32_16x16x32_bf16 v[4:7], v[144:147], v[208:211], v[4:7]
	v_mfma_f32_16x16x32_bf16 v[0:3], v[156:159], v[208:211], v[0:3]
	s_barrier
	s_add_i32 s42, s42, 2
	s_add_u32 s13, s13, 0x100
	s_addc_u32 s40, s40, 0
	s_cmp_gt_u32 s42, 5
	s_mov_b64 s[16:17], s[18:19]
	s_cbranch_scc1 .Lgk_exit_1
.LBB0_994:
	s_add_u32 s18, s16, 0x100
	s_addc_u32 s19, s17, 0
	s_add_i32 s45, 0, 0x10000
	s_cmp_eq_u32 s42, 4
	s_cselect_b32 s23, s7, s19
	s_cselect_b32 s22, s6, s18
	s_cselect_b32 s21, s15, s40
	s_cselect_b32 s20, s14, s13
	s_add_i32 s51, 0, 0x14000
	v_add_u32_e32 v128, s45, v183
	v_add_u32_e32 v156, s51, v183
	ds_read_b128 v[104:107], v128
	ds_read_b128 v[112:115], v128 offset:1024
	ds_read_b128 v[124:127], v128 offset:2048
	ds_read_b128 v[128:131], v128 offset:3072
	ds_read_b128 v[136:139], v156
	ds_read_b128 v[144:147], v156 offset:1024
	ds_read_b128 v[152:155], v156 offset:2048
	ds_read_b128 v[156:159], v156 offset:3072
	v_lshl_add_u64 v[190:191], s[16:17], 0, v[166:167]
	s_add_i32 m0, s73, 0xc000
	ds_read_b128 v[170:173], v185
	ds_read_b128 v[174:177], v185 offset:1024
	ds_read_b128 v[178:181], v185 offset:2048
	ds_read_b128 v[186:189], v185 offset:3072
	ds_read_b128 v[194:197], v185 offset:4096
	ds_read_b128 v[198:201], v185 offset:5120
	ds_read_b128 v[204:207], v185 offset:6144
	ds_read_b128 v[208:211], v185 offset:7168
	global_load_lds_dwordx4 v[190:191], off
	v_lshl_add_u64 v[190:191], s[16:17], 0, v[168:169]
	s_add_i32 m0, s73, 0xe000
	s_nop 0
	global_load_lds_dwordx4 v[190:191], off
	s_waitcnt vmcnt(8)
	s_waitcnt lgkmcnt(0)
	s_barrier
; #define PG8_STAGE(bufoff, gbase, voff) do { _Pragma("unroll") for (int _i = 0; _i < 2; ++_i) \
;         __builtin_amdgcn_global_load_lds((const unsigned*)((const char*)(gbase) + (voff)[_i]), (LAS unsigned*)(lds + (bufoff) + ldsw + _i * 8192), 16, 0, 0); } while (0)
; #define PG8_LDA(dst, b, h) do { _Pragma("unroll") for (int m = 0; m < 4; ++m) _Pragma("unroll") for (int k = 0; k < 2; ++k) dst[m][k] = *(const LAS bf16x8*)(lds + PG8_SA(b, h) + aoff + m * 2048 + k * 1024); } while (0)
; #define PG8_MMA(ai, bj, At, Bt) do { __builtin_amdgcn_s_setprio(1); _Pragma("unroll") for (int m = 0; m < 4; ++m) _Pragma("unroll") for (int n = 0; n < 2; ++n) _Pragma("unroll") for (int k = 0; k < 2; ++k) \
;         acc[ai][bj][m][n] = __builtin_amdgcn_mfma_f32_16x16x32_bf16(Bt[n][k], At[m][k], acc[ai][bj][m][n], 0, 0, 0); __builtin_amdgcn_s_setprio(0); } while (0)
; #define PG8_WAIT_V(n) asm volatile("s_waitcnt vmcnt(" #n ")" ::: "memory")
; #define PG8_WAIT_L(n) asm volatile("s_waitcnt lgkmcnt(" #n ")" ::: "memory")
; #define PG8_BAR __builtin_amdgcn_s_barrier()
; #define PG8_SCHED __builtin_amdgcn_sched_barrier(0)
; template <class Epi>
; __device__ __forceinline__ void gemm_phase(LAS unsigned char* lds, const Gemm g, const Sched& S, const Epi& E, const int tid) {
;     ...
;             PG8_WAIT_V(8); PG8_WAIT_L(0); PG8_BAR; PG8_MMA(0, 0, At, B0); PG8_MMA(0, 1, At, B1); PG8_BAR; PG8_SCHED;
;             PG8_LDA(At, 0, 1); PG8_STAGE(PG8_SB(0, 0), b2, voffB); PG8_STAGE(PG8_SB(0, 1), b2 + hB, voffB); PG8_STAGE(PG8_SA(0, 0), a2, voffA);
;             PG8_WAIT_V(8); PG8_WAIT_L(0); PG8_BAR; PG8_MMA(1, 0, At, B0); PG8_MMA(1, 1, At, B1); PG8_BAR; PG8_SCHED;
	s_waitcnt lgkmcnt(0)
	v_mfma_f32_16x16x32_bf16 v[148:151], v[104:107], v[170:173], v[148:151]
	v_mfma_f32_16x16x32_bf16 v[140:143], v[124:127], v[170:173], v[140:143]
	v_mfma_f32_16x16x32_bf16 v[116:119], v[104:107], v[178:181], v[116:119]
	v_mfma_f32_16x16x32_bf16 v[108:111], v[124:127], v[178:181], v[108:111]
	v_mfma_f32_16x16x32_bf16 v[92:95], v[104:107], v[194:197], v[92:95]
	v_mfma_f32_16x16x32_bf16 v[88:91], v[124:127], v[194:197], v[88:91]
	v_mfma_f32_16x16x32_bf16 v[76:79], v[104:107], v[204:207], v[76:79]
	v_mfma_f32_16x16x32_bf16 v[72:75], v[124:127], v[204:207], v[72:75]
	v_mfma_f32_16x16x32_bf16 v[148:151], v[112:115], v[174:177], v[148:151]
	v_mfma_f32_16x16x32_bf16 v[140:143], v[128:131], v[174:177], v[140:143]
	v_mfma_f32_16x16x32_bf16 v[116:119], v[112:115], v[186:189], v[116:119]
	v_mfma_f32_16x16x32_bf16 v[108:111], v[128:131], v[186:189], v[108:111]
	v_mfma_f32_16x16x32_bf16 v[92:95], v[112:115], v[198:201], v[92:95]
	v_mfma_f32_16x16x32_bf16 v[88:91], v[128:131], v[198:201], v[88:91]
	v_mfma_f32_16x16x32_bf16 v[76:79], v[112:115], v[208:211], v[76:79]
	v_mfma_f32_16x16x32_bf16 v[72:75], v[128:131], v[208:211], v[72:75]
	v_mfma_f32_16x16x32_bf16 v[132:135], v[136:139], v[170:173], v[132:135]
	v_mfma_f32_16x16x32_bf16 v[120:123], v[152:155], v[170:173], v[120:123]
	v_mfma_f32_16x16x32_bf16 v[100:103], v[136:139], v[178:181], v[100:103]
	v_mfma_f32_16x16x32_bf16 v[96:99], v[152:155], v[178:181], v[96:99]
	v_mfma_f32_16x16x32_bf16 v[84:87], v[136:139], v[194:197], v[84:87]
	v_mfma_f32_16x16x32_bf16 v[80:83], v[152:155], v[194:197], v[80:83]
	v_mfma_f32_16x16x32_bf16 v[68:71], v[136:139], v[204:207], v[68:71]
	v_mfma_f32_16x16x32_bf16 v[64:67], v[152:155], v[204:207], v[64:67]
	v_mfma_f32_16x16x32_bf16 v[132:135], v[144:147], v[174:177], v[132:135]
	v_mfma_f32_16x16x32_bf16 v[120:123], v[156:159], v[174:177], v[120:123]
	v_mfma_f32_16x16x32_bf16 v[100:103], v[144:147], v[186:189], v[100:103]
	v_mfma_f32_16x16x32_bf16 v[96:99], v[156:159], v[186:189], v[96:99]
	v_mfma_f32_16x16x32_bf16 v[84:87], v[144:147], v[198:201], v[84:87]
	v_mfma_f32_16x16x32_bf16 v[80:83], v[156:159], v[198:201], v[80:83]
	v_mfma_f32_16x16x32_bf16 v[68:71], v[144:147], v[208:211], v[68:71]
	v_mfma_f32_16x16x32_bf16 v[64:67], v[156:159], v[208:211], v[64:67]
	s_barrier
	s_add_i32 s16, s45, s47
	v_lshl_add_u64 v[190:191], s[20:21], 0, v[192:193]
	s_mov_b32 m0, s16
	ds_read_b128 v[170:173], v185 offset:16384
	ds_read_b128 v[174:177], v185 offset:17408
	ds_read_b128 v[178:181], v185 offset:18432
	ds_read_b128 v[186:189], v185 offset:19456
	ds_read_b128 v[194:197], v185 offset:20480
	ds_read_b128 v[198:201], v185 offset:21504
	ds_read_b128 v[204:207], v185 offset:22528
	ds_read_b128 v[208:211], v185 offset:23552
	global_load_lds_dwordx4 v[190:191], off
	s_add_i32 m0, s16, 0x2000
	s_add_u32 s16, s20, 0x20000
	v_lshl_add_u64 v[212:213], s[20:21], 0, v[164:165]
	s_addc_u32 s17, s21, 0
	s_add_i32 s45, s51, s47
	global_load_lds_dwordx4 v[212:213], off
	v_lshl_add_u64 v[214:215], s[16:17], 0, v[192:193]
	s_mov_b32 m0, s45
	v_lshl_add_u64 v[216:217], s[22:23], 0, v[162:163]
	global_load_lds_dwordx4 v[214:215], off
	v_lshl_add_u64 v[214:215], s[16:17], 0, v[164:165]
	s_add_i32 m0, s45, 0x2000
	s_nop 0
	global_load_lds_dwordx4 v[214:215], off
	v_lshl_add_u64 v[214:215], s[22:23], 0, v[160:161]
	s_mov_b32 m0, s73
	s_nop 0
	global_load_lds_dwordx4 v[214:215], off
	s_mov_b32 m0, s74
	s_nop 0
	global_load_lds_dwordx4 v[216:217], off
	s_waitcnt vmcnt(8)
	s_waitcnt lgkmcnt(0)
	s_barrier
	s_waitcnt lgkmcnt(0)
	v_mfma_f32_16x16x32_bf16 v[60:63], v[104:107], v[170:173], v[60:63]
	v_mfma_f32_16x16x32_bf16 v[56:59], v[124:127], v[170:173], v[56:59]
	v_mfma_f32_16x16x32_bf16 v[44:47], v[104:107], v[178:181], v[44:47]
	v_mfma_f32_16x16x32_bf16 v[40:43], v[124:127], v[178:181], v[40:43]
	v_mfma_f32_16x16x32_bf16 v[28:31], v[104:107], v[194:197], v[28:31]
	v_mfma_f32_16x16x32_bf16 v[24:27], v[124:127], v[194:197], v[24:27]
	v_mfma_f32_16x16x32_bf16 v[12:15], v[104:107], v[204:207], v[12:15]
	v_mfma_f32_16x16x32_bf16 v[8:11], v[124:127], v[204:207], v[8:11]
	v_mfma_f32_16x16x32_bf16 v[60:63], v[112:115], v[174:177], v[60:63]
	v_mfma_f32_16x16x32_bf16 v[56:59], v[128:131], v[174:177], v[56:59]
	v_mfma_f32_16x16x32_bf16 v[44:47], v[112:115], v[186:189], v[44:47]
	v_mfma_f32_16x16x32_bf16 v[40:43], v[128:131], v[186:189], v[40:43]
	v_mfma_f32_16x16x32_bf16 v[28:31], v[112:115], v[198:201], v[28:31]
	v_mfma_f32_16x16x32_bf16 v[24:27], v[128:131], v[198:201], v[24:27]
	v_mfma_f32_16x16x32_bf16 v[12:15], v[112:115], v[208:211], v[12:15]
	v_mfma_f32_16x16x32_bf16 v[8:11], v[128:131], v[208:211], v[8:11]
	v_mfma_f32_16x16x32_bf16 v[52:55], v[136:139], v[170:173], v[52:55]
	v_mfma_f32_16x16x32_bf16 v[48:51], v[152:155], v[170:173], v[48:51]
	v_mfma_f32_16x16x32_bf16 v[36:39], v[136:139], v[178:181], v[36:39]
	v_mfma_f32_16x16x32_bf16 v[32:35], v[152:155], v[178:181], v[32:35]
	v_mfma_f32_16x16x32_bf16 v[20:23], v[136:139], v[194:197], v[20:23]
	v_mfma_f32_16x16x32_bf16 v[16:19], v[152:155], v[194:197], v[16:19]
	v_mfma_f32_16x16x32_bf16 v[4:7], v[136:139], v[204:207], v[4:7]
	v_mfma_f32_16x16x32_bf16 v[0:3], v[152:155], v[204:207], v[0:3]
	v_mfma_f32_16x16x32_bf16 v[52:55], v[144:147], v[174:177], v[52:55]
	v_mfma_f32_16x16x32_bf16 v[48:51], v[156:159], v[174:177], v[48:51]
	v_mfma_f32_16x16x32_bf16 v[36:39], v[144:147], v[186:189], v[36:39]
	v_mfma_f32_16x16x32_bf16 v[32:35], v[156:159], v[186:189], v[32:35]
	v_mfma_f32_16x16x32_bf16 v[20:23], v[144:147], v[198:201], v[20:23]
	v_mfma_f32_16x16x32_bf16 v[16:19], v[156:159], v[198:201], v[16:19]
	v_mfma_f32_16x16x32_bf16 v[4:7], v[144:147], v[208:211], v[4:7]
	v_mfma_f32_16x16x32_bf16 v[0:3], v[156:159], v[208:211], v[0:3]
	s_barrier
; #define PG8_STAGE(bufoff, gbase, voff) do { _Pragma("unroll") for (int _i = 0; _i < 2; ++_i) \
;         __builtin_amdgcn_global_load_lds((const unsigned*)((const char*)(gbase) + (voff)[_i]), (LAS unsigned*)(lds + (bufoff) + ldsw + _i * 8192), 16, 0, 0); } while (0)
; #define PG8_LDA(dst, b, h) do { _Pragma("unroll") for (int m = 0; m < 4; ++m) _Pragma("unroll") for (int k = 0; k < 2; ++k) dst[m][k] = *(const LAS bf16x8*)(lds + PG8_SA(b, h) + aoff + m * 2048 + k * 1024); } while (0)
; #define PG8_LDB(dst, b, h) do { _Pragma("unroll") for (int n = 0; n < 2; ++n) _Pragma("unroll") for (int k = 0; k < 2; ++k) dst[n][k] = *(const LAS bf16x8*)(lds + PG8_SB(b, h) + boff + n * 2048 + k * 1024); } while (0)
; #define PG8_MMA(ai, bj, At, Bt) do { __builtin_amdgcn_s_setprio(1); _Pragma("unroll") for (int m = 0; m < 4; ++m) _Pragma("unroll") for (int n = 0; n < 2; ++n) _Pragma("unroll") for (int k = 0; k < 2; ++k) \
;         acc[ai][bj][m][n] = __builtin_amdgcn_mfma_f32_16x16x32_bf16(Bt[n][k], At[m][k], acc[ai][bj][m][n], 0, 0, 0); __builtin_amdgcn_s_setprio(0); } while (0)
; #define PG8_WAIT_V(n) asm volatile("s_waitcnt vmcnt(" #n ")" ::: "memory")
; #define PG8_WAIT_L(n) asm volatile("s_waitcnt lgkmcnt(" #n ")" ::: "memory")
; #define PG8_BAR __builtin_amdgcn_s_barrier()
; #define PG8_SCHED __builtin_amdgcn_sched_barrier(0)
; template <class Epi>
; __device__ __forceinline__ void gemm_phase(LAS unsigned char* lds, const Gemm g, const Sched& S, const Epi& E, const int tid) {
;     ...
;             PG8_LDB(B0, 1, 0); PG8_LDB(B1, 1, 1); PG8_SCHED; PG8_LDA(At, 1, 0); PG8_STAGE(PG8_SA(0, 1), a2 + hA, voffA);
;             PG8_WAIT_V(8); PG8_WAIT_L(0); PG8_BAR; PG8_MMA(0, 0, At, B0); PG8_MMA(0, 1, At, B1); PG8_BAR; PG8_SCHED;
;             PG8_LDA(At, 1, 1); PG8_STAGE(PG8_SB(1, 0), b3, voffB); PG8_STAGE(PG8_SB(1, 1), b3 + hB, voffB); PG8_STAGE(PG8_SA(1, 0), a3, voffA);
;             PG8_WAIT_V(8); PG8_WAIT_L(0); PG8_BAR; PG8_MMA(1, 0, At, B0); PG8_MMA(1, 1, At, B1); PG8_BAR; PG8_SCHED;
;         }
	s_add_i32 s45, 0, 0x18000
	s_add_i32 s51, 0, 0x1c000
	v_add_u32_e32 v128, s45, v183
	v_add_u32_e32 v156, s51, v183
	ds_read_b128 v[104:107], v128
	ds_read_b128 v[112:115], v128 offset:1024
	ds_read_b128 v[124:127], v128 offset:2048
	ds_read_b128 v[128:131], v128 offset:3072
	ds_read_b128 v[136:139], v156
	ds_read_b128 v[144:147], v156 offset:1024
	ds_read_b128 v[152:155], v156 offset:2048
	ds_read_b128 v[156:159], v156 offset:3072
	s_add_u32 s16, s22, 0x120000
	s_addc_u32 s17, s23, 0
	s_mov_b32 m0, s75
	v_lshl_add_u64 v[218:219], s[16:17], 0, v[160:161]
	ds_read_b128 v[170:173], v185 offset:32768
	ds_read_b128 v[174:177], v185 offset:33792
	ds_read_b128 v[178:181], v185 offset:34816
	ds_read_b128 v[186:189], v185 offset:35840
	ds_read_b128 v[194:197], v185 offset:36864
	ds_read_b128 v[198:201], v185 offset:37888
	ds_read_b128 v[204:207], v185 offset:38912
	ds_read_b128 v[208:211], v185 offset:39936
	global_load_lds_dwordx4 v[218:219], off
	v_lshl_add_u64 v[218:219], s[16:17], 0, v[162:163]
	s_mov_b32 m0, s76
	s_nop 0
	global_load_lds_dwordx4 v[218:219], off
	s_waitcnt vmcnt(8)
	s_waitcnt lgkmcnt(0)
	s_barrier
	s_waitcnt lgkmcnt(0)
	v_mfma_f32_16x16x32_bf16 v[148:151], v[104:107], v[170:173], v[148:151]
	v_mfma_f32_16x16x32_bf16 v[140:143], v[124:127], v[170:173], v[140:143]
	v_mfma_f32_16x16x32_bf16 v[116:119], v[104:107], v[178:181], v[116:119]
	v_mfma_f32_16x16x32_bf16 v[108:111], v[124:127], v[178:181], v[108:111]
	v_mfma_f32_16x16x32_bf16 v[92:95], v[104:107], v[194:197], v[92:95]
	v_mfma_f32_16x16x32_bf16 v[88:91], v[124:127], v[194:197], v[88:91]
	v_mfma_f32_16x16x32_bf16 v[76:79], v[104:107], v[204:207], v[76:79]
	v_mfma_f32_16x16x32_bf16 v[72:75], v[124:127], v[204:207], v[72:75]
	v_mfma_f32_16x16x32_bf16 v[148:151], v[112:115], v[174:177], v[148:151]
	v_mfma_f32_16x16x32_bf16 v[140:143], v[128:131], v[174:177], v[140:143]
	v_mfma_f32_16x16x32_bf16 v[116:119], v[112:115], v[186:189], v[116:119]
	v_mfma_f32_16x16x32_bf16 v[108:111], v[128:131], v[186:189], v[108:111]
	v_mfma_f32_16x16x32_bf16 v[92:95], v[112:115], v[198:201], v[92:95]
	v_mfma_f32_16x16x32_bf16 v[88:91], v[128:131], v[198:201], v[88:91]
	v_mfma_f32_16x16x32_bf16 v[76:79], v[112:115], v[208:211], v[76:79]
	v_mfma_f32_16x16x32_bf16 v[72:75], v[128:131], v[208:211], v[72:75]
	v_mfma_f32_16x16x32_bf16 v[132:135], v[136:139], v[170:173], v[132:135]
	v_mfma_f32_16x16x32_bf16 v[120:123], v[152:155], v[170:173], v[120:123]
	v_mfma_f32_16x16x32_bf16 v[100:103], v[136:139], v[178:181], v[100:103]
	v_mfma_f32_16x16x32_bf16 v[96:99], v[152:155], v[178:181], v[96:99]
	v_mfma_f32_16x16x32_bf16 v[84:87], v[136:139], v[194:197], v[84:87]
	v_mfma_f32_16x16x32_bf16 v[80:83], v[152:155], v[194:197], v[80:83]
	v_mfma_f32_16x16x32_bf16 v[68:71], v[136:139], v[204:207], v[68:71]
	v_mfma_f32_16x16x32_bf16 v[64:67], v[152:155], v[204:207], v[64:67]
	v_mfma_f32_16x16x32_bf16 v[132:135], v[144:147], v[174:177], v[132:135]
	v_mfma_f32_16x16x32_bf16 v[120:123], v[156:159], v[174:177], v[120:123]
	v_mfma_f32_16x16x32_bf16 v[100:103], v[144:147], v[186:189], v[100:103]
	v_mfma_f32_16x16x32_bf16 v[96:99], v[156:159], v[186:189], v[96:99]
	v_mfma_f32_16x16x32_bf16 v[84:87], v[144:147], v[198:201], v[84:87]
	v_mfma_f32_16x16x32_bf16 v[80:83], v[156:159], v[198:201], v[80:83]
	v_mfma_f32_16x16x32_bf16 v[68:71], v[144:147], v[208:211], v[68:71]
	v_mfma_f32_16x16x32_bf16 v[64:67], v[156:159], v[208:211], v[64:67]
	s_barrier
	s_add_i32 s16, s45, s47
	v_lshl_add_u64 v[190:191], v[190:191], 0, s[94:95]
	s_mov_b32 m0, s16
	ds_read_b128 v[170:173], v185 offset:49152
	ds_read_b128 v[174:177], v185 offset:50176
	ds_read_b128 v[178:181], v185 offset:51200
	ds_read_b128 v[186:189], v185 offset:52224
	ds_read_b128 v[194:197], v185 offset:53248
	ds_read_b128 v[198:201], v185 offset:54272
	ds_read_b128 v[204:207], v185 offset:55296
	ds_read_b128 v[208:211], v185 offset:56320
	global_load_lds_dwordx4 v[190:191], off
	s_add_i32 m0, s16, 0x2000
	s_add_u32 s16, s20, 0x20080
	v_lshl_add_u64 v[190:191], v[212:213], 0, s[94:95]
	s_addc_u32 s17, s21, 0
	s_add_i32 s20, s51, s47
	global_load_lds_dwordx4 v[190:191], off
	v_lshl_add_u64 v[190:191], s[16:17], 0, v[192:193]
	s_mov_b32 m0, s20
	s_nop 0
	global_load_lds_dwordx4 v[190:191], off
	v_lshl_add_u64 v[190:191], s[16:17], 0, v[164:165]
	s_add_i32 m0, s20, 0x2000
	s_nop 0
	global_load_lds_dwordx4 v[190:191], off
	v_lshl_add_u64 v[190:191], v[214:215], 0, s[94:95]
	s_mov_b32 m0, s77
	s_nop 0
	global_load_lds_dwordx4 v[190:191], off
	v_lshl_add_u64 v[190:191], v[216:217], 0, s[94:95]
	s_mov_b32 m0, s78
	s_nop 0
	global_load_lds_dwordx4 v[190:191], off
	s_waitcnt vmcnt(8)
	s_waitcnt lgkmcnt(0)
	s_barrier
	s_waitcnt lgkmcnt(0)
	v_mfma_f32_16x16x32_bf16 v[60:63], v[104:107], v[170:173], v[60:63]
	v_mfma_f32_16x16x32_bf16 v[56:59], v[124:127], v[170:173], v[56:59]
	v_mfma_f32_16x16x32_bf16 v[44:47], v[104:107], v[178:181], v[44:47]
	v_mfma_f32_16x16x32_bf16 v[40:43], v[124:127], v[178:181], v[40:43]
	v_mfma_f32_16x16x32_bf16 v[28:31], v[104:107], v[194:197], v[28:31]
	v_mfma_f32_16x16x32_bf16 v[24:27], v[124:127], v[194:197], v[24:27]
	v_mfma_f32_16x16x32_bf16 v[12:15], v[104:107], v[204:207], v[12:15]
	v_mfma_f32_16x16x32_bf16 v[8:11], v[124:127], v[204:207], v[8:11]
	v_mfma_f32_16x16x32_bf16 v[60:63], v[112:115], v[174:177], v[60:63]
	v_mfma_f32_16x16x32_bf16 v[56:59], v[128:131], v[174:177], v[56:59]
	v_mfma_f32_16x16x32_bf16 v[44:47], v[112:115], v[186:189], v[44:47]
	v_mfma_f32_16x16x32_bf16 v[40:43], v[128:131], v[186:189], v[40:43]
	v_mfma_f32_16x16x32_bf16 v[28:31], v[112:115], v[198:201], v[28:31]
	v_mfma_f32_16x16x32_bf16 v[24:27], v[128:131], v[198:201], v[24:27]
	v_mfma_f32_16x16x32_bf16 v[12:15], v[112:115], v[208:211], v[12:15]
	v_mfma_f32_16x16x32_bf16 v[8:11], v[128:131], v[208:211], v[8:11]
	v_mfma_f32_16x16x32_bf16 v[52:55], v[136:139], v[170:173], v[52:55]
	v_mfma_f32_16x16x32_bf16 v[48:51], v[152:155], v[170:173], v[48:51]
	v_mfma_f32_16x16x32_bf16 v[36:39], v[136:139], v[178:181], v[36:39]
	v_mfma_f32_16x16x32_bf16 v[32:35], v[152:155], v[178:181], v[32:35]
	v_mfma_f32_16x16x32_bf16 v[20:23], v[136:139], v[194:197], v[20:23]
	v_mfma_f32_16x16x32_bf16 v[16:19], v[152:155], v[194:197], v[16:19]
	v_mfma_f32_16x16x32_bf16 v[4:7], v[136:139], v[204:207], v[4:7]
	v_mfma_f32_16x16x32_bf16 v[0:3], v[152:155], v[204:207], v[0:3]
	v_mfma_f32_16x16x32_bf16 v[52:55], v[144:147], v[174:177], v[52:55]
	v_mfma_f32_16x16x32_bf16 v[48:51], v[156:159], v[174:177], v[48:51]
	v_mfma_f32_16x16x32_bf16 v[36:39], v[144:147], v[186:189], v[36:39]
	v_mfma_f32_16x16x32_bf16 v[32:35], v[156:159], v[186:189], v[32:35]
	v_mfma_f32_16x16x32_bf16 v[20:23], v[144:147], v[198:201], v[20:23]
	v_mfma_f32_16x16x32_bf16 v[16:19], v[156:159], v[198:201], v[16:19]
	v_mfma_f32_16x16x32_bf16 v[4:7], v[144:147], v[208:211], v[4:7]
	v_mfma_f32_16x16x32_bf16 v[0:3], v[156:159], v[208:211], v[0:3]
	s_barrier
	s_add_i32 s42, s42, 2
	s_add_u32 s13, s13, 0x100
	s_addc_u32 s40, s40, 0
	s_cmp_gt_u32 s42, 5
	s_mov_b64 s[16:17], s[18:19]
	s_cbranch_scc0 .LBB0_994

; #define PG8_STAGE(bufoff, gbase, voff) do { _Pragma("unroll") for (int _i = 0; _i < 2; ++_i) \
;         __builtin_amdgcn_global_load_lds((const unsigned*)((const char*)(gbase) + (voff)[_i]), (LAS unsigned*)(lds + (bufoff) + ldsw + _i * 8192), 16, 0, 0); } while (0)
; #define PG8_LDA(dst, b, h) do { _Pragma("unroll") for (int m = 0; m < 4; ++m) _Pragma("unroll") for (int k = 0; k < 2; ++k) dst[m][k] = *(const LAS bf16x8*)(lds + PG8_SA(b, h) + aoff + m * 2048 + k * 1024); } while (0)
; #define PG8_LDB(dst, b, h) do { _Pragma("unroll") for (int n = 0; n < 2; ++n) _Pragma("unroll") for (int k = 0; k < 2; ++k) dst[n][k] = *(const LAS bf16x8*)(lds + PG8_SB(b, h) + boff + n * 2048 + k * 1024); } while (0)
; #define PG8_MMA(ai, bj, At, Bt) do { __builtin_amdgcn_s_setprio(1); _Pragma("unroll") for (int m = 0; m < 4; ++m) _Pragma("unroll") for (int n = 0; n < 2; ++n) _Pragma("unroll") for (int k = 0; k < 2; ++k) \
;         acc[ai][bj][m][n] = __builtin_amdgcn_mfma_f32_16x16x32_bf16(Bt[n][k], At[m][k], acc[ai][bj][m][n], 0, 0, 0); __builtin_amdgcn_s_setprio(0); } while (0)
; #define PG8_WAIT_V(n) asm volatile("s_waitcnt vmcnt(" #n ")" ::: "memory")
; #define PG8_WAIT_L(n) asm volatile("s_waitcnt lgkmcnt(" #n ")" ::: "memory")
; #define PG8_BAR __builtin_amdgcn_s_barrier()
; template <class Epi>
; __device__ __forceinline__ void gemm_phase(LAS unsigned char* lds, const Gemm g, const Sched& S, const Epi& E, const int tid) {
;     ...
;         const char* nA = cA; const char* nB = cB; if (has_next) S.ptrs(nxt, nA, nB);
;         for (int t = 0; t < nt; t += 2) {
;             const bool last = (t == nt - 2);
;             const char* a1 = cA + (size_t)(t + 1) * kstep;
;             const char* a2 = last ? nA : cA + (size_t)(t + 2) * kstep; const char* b2 = last ? nB : cB + (size_t)(t + 2) * kstep;
;             const char* a3 = a2 + kstep; const char* b3 = b2 + kstep;
;             PG8_LDB(B0, 0, 0); PG8_LDB(B1, 0, 1); PG8_SCHED; PG8_LDA(At, 0, 0); PG8_STAGE(PG8_SA(1, 1), a1 + hA, voffA);
;             PG8_WAIT_V(8); PG8_WAIT_L(0); PG8_BAR; PG8_MMA(0, 0, At, B0); PG8_MMA(0, 1, At, B1); PG8_BAR; PG8_SCHED;
;             PG8_LDA(At, 0, 1); PG8_STAGE(PG8_SB(0, 0), b2, voffB); PG8_STAGE(PG8_SB(0, 1), b2 + hB, voffB); PG8_STAGE(PG8_SA(0, 0), a2, voffA);
;             PG8_WAIT_V(8); PG8_WAIT_L(0); PG8_BAR; PG8_MMA(1, 0, At, B0); PG8_MMA(1, 1, At, B1); PG8_BAR; PG8_SCHED;
.LBB0_1028:
	s_add_u32 s13, s22, 0x100
	s_addc_u32 s37, s23, 0
	s_mov_b32 s40, -2
	s_add_u32 s6, s20, 0x100
	s_addc_u32 s7, s21, 0
	s_add_i32 s42, 0, 0x10000
	s_cmp_eq_u32 s40, 4
	s_cselect_b32 s73, s15, s7
	s_cselect_b32 s72, s14, s6
	s_cselect_b32 s23, s17, s37
	s_cselect_b32 s22, s16, s13
	s_add_i32 s45, 0, 0x14000
	v_add_u32_e32 v128, s42, v241
	v_add_u32_e32 v156, s45, v241
	ds_read_b128 v[104:107], v128
	ds_read_b128 v[112:115], v128 offset:1024
	ds_read_b128 v[120:123], v128 offset:2048
	ds_read_b128 v[128:131], v128 offset:3072
	ds_read_b128 v[136:139], v156
	ds_read_b128 v[140:143], v156 offset:1024
	ds_read_b128 v[148:151], v156 offset:2048
	ds_read_b128 v[156:159], v156 offset:3072
	v_lshl_add_u64 v[194:195], s[20:21], 0, v[210:211]
	s_add_i32 m0, s19, 0xc000
	ds_read_b128 v[160:163], v243
	ds_read_b128 v[164:167], v243 offset:1024
	ds_read_b128 v[168:171], v243 offset:2048
	ds_read_b128 v[172:175], v243 offset:3072
	ds_read_b128 v[176:179], v243 offset:4096
	ds_read_b128 v[180:183], v243 offset:5120
	ds_read_b128 v[184:187], v243 offset:6144
	ds_read_b128 v[188:191], v243 offset:7168
	global_load_lds_dwordx4 v[194:195], off
	v_lshl_add_u64 v[194:195], s[20:21], 0, v[212:213]
	s_add_i32 m0, s19, 0xe000
	s_nop 0
	global_load_lds_dwordx4 v[194:195], off
	s_waitcnt vmcnt(8)
	s_waitcnt lgkmcnt(0)
	s_barrier
	s_waitcnt lgkmcnt(0)
	v_mfma_f32_16x16x32_bf16 v[152:155], v[104:107], v[160:163], 0
	v_mfma_f32_16x16x32_bf16 v[144:147], v[120:123], v[160:163], 0
	v_mfma_f32_16x16x32_bf16 v[116:119], v[104:107], v[168:171], 0
	v_mfma_f32_16x16x32_bf16 v[108:111], v[120:123], v[168:171], 0
	v_mfma_f32_16x16x32_bf16 v[92:95], v[104:107], v[176:179], 0
	v_mfma_f32_16x16x32_bf16 v[88:91], v[120:123], v[176:179], 0
	v_mfma_f32_16x16x32_bf16 v[76:79], v[104:107], v[184:187], 0
	v_mfma_f32_16x16x32_bf16 v[72:75], v[120:123], v[184:187], 0
	v_mfma_f32_16x16x32_bf16 v[152:155], v[112:115], v[164:167], v[152:155]
	v_mfma_f32_16x16x32_bf16 v[144:147], v[128:131], v[164:167], v[144:147]
	v_mfma_f32_16x16x32_bf16 v[116:119], v[112:115], v[172:175], v[116:119]
	v_mfma_f32_16x16x32_bf16 v[108:111], v[128:131], v[172:175], v[108:111]
	v_mfma_f32_16x16x32_bf16 v[92:95], v[112:115], v[180:183], v[92:95]
	v_mfma_f32_16x16x32_bf16 v[88:91], v[128:131], v[180:183], v[88:91]
	v_mfma_f32_16x16x32_bf16 v[76:79], v[112:115], v[188:191], v[76:79]
	v_mfma_f32_16x16x32_bf16 v[72:75], v[128:131], v[188:191], v[72:75]
	v_mfma_f32_16x16x32_bf16 v[132:135], v[136:139], v[160:163], 0
	v_mfma_f32_16x16x32_bf16 v[124:127], v[148:151], v[160:163], 0
	v_mfma_f32_16x16x32_bf16 v[100:103], v[136:139], v[168:171], 0
	v_mfma_f32_16x16x32_bf16 v[96:99], v[148:151], v[168:171], 0
	v_mfma_f32_16x16x32_bf16 v[84:87], v[136:139], v[176:179], 0
	v_mfma_f32_16x16x32_bf16 v[80:83], v[148:151], v[176:179], 0
	v_mfma_f32_16x16x32_bf16 v[68:71], v[136:139], v[184:187], 0
	v_mfma_f32_16x16x32_bf16 v[64:67], v[148:151], v[184:187], 0
	v_mfma_f32_16x16x32_bf16 v[132:135], v[140:143], v[164:167], v[132:135]
	v_mfma_f32_16x16x32_bf16 v[124:127], v[156:159], v[164:167], v[124:127]
	v_mfma_f32_16x16x32_bf16 v[100:103], v[140:143], v[172:175], v[100:103]
	v_mfma_f32_16x16x32_bf16 v[96:99], v[156:159], v[172:175], v[96:99]
	v_mfma_f32_16x16x32_bf16 v[84:87], v[140:143], v[180:183], v[84:87]
	v_mfma_f32_16x16x32_bf16 v[80:83], v[156:159], v[180:183], v[80:83]
	v_mfma_f32_16x16x32_bf16 v[68:71], v[140:143], v[188:191], v[68:71]
	v_mfma_f32_16x16x32_bf16 v[64:67], v[156:159], v[188:191], v[64:67]
	s_barrier
	s_add_i32 s20, s42, s35
	v_lshl_add_u64 v[194:195], s[22:23], 0, v[192:193]
	s_mov_b32 m0, s20
	ds_read_b128 v[160:163], v243 offset:16384
	ds_read_b128 v[164:167], v243 offset:17408
	ds_read_b128 v[168:171], v243 offset:18432
	ds_read_b128 v[172:175], v243 offset:19456
	ds_read_b128 v[176:179], v243 offset:20480
	ds_read_b128 v[180:183], v243 offset:21504
	ds_read_b128 v[184:187], v243 offset:22528
	ds_read_b128 v[188:191], v243 offset:23552
	global_load_lds_dwordx4 v[194:195], off
	s_add_i32 m0, s20, 0x2000
	s_add_u32 s20, s22, 0x20000
	v_lshl_add_u64 v[196:197], s[22:23], 0, v[208:209]
	s_addc_u32 s21, s23, 0
	s_add_i32 s42, s45, s35
	global_load_lds_dwordx4 v[196:197], off
	v_lshl_add_u64 v[198:199], s[20:21], 0, v[192:193]
	s_mov_b32 m0, s42
	v_lshl_add_u64 v[200:201], s[72:73], 0, v[206:207]
	global_load_lds_dwordx4 v[198:199], off
	v_lshl_add_u64 v[198:199], s[20:21], 0, v[208:209]
	s_add_i32 m0, s42, 0x2000
	s_nop 0
	global_load_lds_dwordx4 v[198:199], off
	v_lshl_add_u64 v[198:199], s[72:73], 0, v[204:205]
	s_mov_b32 m0, s19
	s_nop 0
	global_load_lds_dwordx4 v[198:199], off
	s_mov_b32 m0, s74
	s_nop 0
	global_load_lds_dwordx4 v[200:201], off
	s_waitcnt vmcnt(8)
	s_waitcnt lgkmcnt(0)
	s_barrier
; #define PG8_STAGE(bufoff, gbase, voff) do { _Pragma("unroll") for (int _i = 0; _i < 2; ++_i) \
;         __builtin_amdgcn_global_load_lds((const unsigned*)((const char*)(gbase) + (voff)[_i]), (LAS unsigned*)(lds + (bufoff) + ldsw + _i * 8192), 16, 0, 0); } while (0)
; #define PG8_LDA(dst, b, h) do { _Pragma("unroll") for (int m = 0; m < 4; ++m) _Pragma("unroll") for (int k = 0; k < 2; ++k) dst[m][k] = *(const LAS bf16x8*)(lds + PG8_SA(b, h) + aoff + m * 2048 + k * 1024); } while (0)
; #define PG8_LDB(dst, b, h) do { _Pragma("unroll") for (int n = 0; n < 2; ++n) _Pragma("unroll") for (int k = 0; k < 2; ++k) dst[n][k] = *(const LAS bf16x8*)(lds + PG8_SB(b, h) + boff + n * 2048 + k * 1024); } while (0)
; #define PG8_MMA(ai, bj, At, Bt) do { __builtin_amdgcn_s_setprio(1); _Pragma("unroll") for (int m = 0; m < 4; ++m) _Pragma("unroll") for (int n = 0; n < 2; ++n) _Pragma("unroll") for (int k = 0; k < 2; ++k) \
;         acc[ai][bj][m][n] = __builtin_amdgcn_mfma_f32_16x16x32_bf16(Bt[n][k], At[m][k], acc[ai][bj][m][n], 0, 0, 0); __builtin_amdgcn_s_setprio(0); } while (0)
; #define PG8_WAIT_V(n) asm volatile("s_waitcnt vmcnt(" #n ")" ::: "memory")
; #define PG8_WAIT_L(n) asm volatile("s_waitcnt lgkmcnt(" #n ")" ::: "memory")
; #define PG8_BAR __builtin_amdgcn_s_barrier()
; #define PG8_SCHED __builtin_amdgcn_sched_barrier(0)
; template <class Epi>
; __device__ __forceinline__ void gemm_phase(LAS unsigned char* lds, const Gemm g, const Sched& S, const Epi& E, const int tid) {
;     ...
;             PG8_WAIT_V(8); PG8_WAIT_L(0); PG8_BAR; PG8_MMA(1, 0, At, B0); PG8_MMA(1, 1, At, B1); PG8_BAR; PG8_SCHED;
;             PG8_LDB(B0, 1, 0); PG8_LDB(B1, 1, 1); PG8_SCHED; PG8_LDA(At, 1, 0); PG8_STAGE(PG8_SA(0, 1), a2 + hA, voffA);
;             PG8_WAIT_V(8); PG8_WAIT_L(0); PG8_BAR; PG8_MMA(0, 0, At, B0); PG8_MMA(0, 1, At, B1); PG8_BAR; PG8_SCHED;
	s_waitcnt lgkmcnt(0)
	v_mfma_f32_16x16x32_bf16 v[60:63], v[104:107], v[160:163], 0
	v_mfma_f32_16x16x32_bf16 v[56:59], v[120:123], v[160:163], 0
	v_mfma_f32_16x16x32_bf16 v[44:47], v[104:107], v[168:171], 0
	v_mfma_f32_16x16x32_bf16 v[40:43], v[120:123], v[168:171], 0
	v_mfma_f32_16x16x32_bf16 v[28:31], v[104:107], v[176:179], 0
	v_mfma_f32_16x16x32_bf16 v[24:27], v[120:123], v[176:179], 0
	v_mfma_f32_16x16x32_bf16 v[12:15], v[104:107], v[184:187], 0
	v_mfma_f32_16x16x32_bf16 v[8:11], v[120:123], v[184:187], 0
	v_mfma_f32_16x16x32_bf16 v[60:63], v[112:115], v[164:167], v[60:63]
	v_mfma_f32_16x16x32_bf16 v[56:59], v[128:131], v[164:167], v[56:59]
	v_mfma_f32_16x16x32_bf16 v[44:47], v[112:115], v[172:175], v[44:47]
	v_mfma_f32_16x16x32_bf16 v[40:43], v[128:131], v[172:175], v[40:43]
	v_mfma_f32_16x16x32_bf16 v[28:31], v[112:115], v[180:183], v[28:31]
	v_mfma_f32_16x16x32_bf16 v[24:27], v[128:131], v[180:183], v[24:27]
	v_mfma_f32_16x16x32_bf16 v[12:15], v[112:115], v[188:191], v[12:15]
	v_mfma_f32_16x16x32_bf16 v[8:11], v[128:131], v[188:191], v[8:11]
	v_mfma_f32_16x16x32_bf16 v[52:55], v[136:139], v[160:163], 0
	v_mfma_f32_16x16x32_bf16 v[48:51], v[148:151], v[160:163], 0
	v_mfma_f32_16x16x32_bf16 v[36:39], v[136:139], v[168:171], 0
	v_mfma_f32_16x16x32_bf16 v[32:35], v[148:151], v[168:171], 0
	v_mfma_f32_16x16x32_bf16 v[20:23], v[136:139], v[176:179], 0
	v_mfma_f32_16x16x32_bf16 v[16:19], v[148:151], v[176:179], 0
	v_mfma_f32_16x16x32_bf16 v[4:7], v[136:139], v[184:187], 0
	v_mfma_f32_16x16x32_bf16 v[0:3], v[148:151], v[184:187], 0
	v_mfma_f32_16x16x32_bf16 v[52:55], v[140:143], v[164:167], v[52:55]
	v_mfma_f32_16x16x32_bf16 v[48:51], v[156:159], v[164:167], v[48:51]
	v_mfma_f32_16x16x32_bf16 v[36:39], v[140:143], v[172:175], v[36:39]
	v_mfma_f32_16x16x32_bf16 v[32:35], v[156:159], v[172:175], v[32:35]
	v_mfma_f32_16x16x32_bf16 v[20:23], v[140:143], v[180:183], v[20:23]
	v_mfma_f32_16x16x32_bf16 v[16:19], v[156:159], v[180:183], v[16:19]
	v_mfma_f32_16x16x32_bf16 v[4:7], v[140:143], v[188:191], v[4:7]
	v_mfma_f32_16x16x32_bf16 v[0:3], v[156:159], v[188:191], v[0:3]
	s_barrier
	s_add_i32 s42, 0, 0x18000
	s_add_i32 s45, 0, 0x1c000
	v_add_u32_e32 v128, s42, v241
	v_add_u32_e32 v156, s45, v241
	ds_read_b128 v[104:107], v128
	ds_read_b128 v[112:115], v128 offset:1024
	ds_read_b128 v[120:123], v128 offset:2048
	ds_read_b128 v[128:131], v128 offset:3072
	ds_read_b128 v[136:139], v156
	ds_read_b128 v[140:143], v156 offset:1024
	ds_read_b128 v[148:151], v156 offset:2048
	ds_read_b128 v[156:159], v156 offset:3072
	s_add_u32 s20, s72, 0x120000
	s_addc_u32 s21, s73, 0
	s_mov_b32 m0, s75
	v_lshl_add_u64 v[214:215], s[20:21], 0, v[204:205]
	ds_read_b128 v[160:163], v243 offset:32768
	ds_read_b128 v[164:167], v243 offset:33792
	ds_read_b128 v[168:171], v243 offset:34816
	ds_read_b128 v[172:175], v243 offset:35840
	ds_read_b128 v[176:179], v243 offset:36864
	ds_read_b128 v[180:183], v243 offset:37888
	ds_read_b128 v[184:187], v243 offset:38912
	ds_read_b128 v[188:191], v243 offset:39936
	global_load_lds_dwordx4 v[214:215], off
	v_lshl_add_u64 v[214:215], s[20:21], 0, v[206:207]
	s_mov_b32 m0, s76
	s_nop 0
	global_load_lds_dwordx4 v[214:215], off
	s_waitcnt vmcnt(8)
	s_waitcnt lgkmcnt(0)
	s_barrier
	s_waitcnt lgkmcnt(0)
	v_mfma_f32_16x16x32_bf16 v[152:155], v[104:107], v[160:163], v[152:155]
	v_mfma_f32_16x16x32_bf16 v[144:147], v[120:123], v[160:163], v[144:147]
	v_mfma_f32_16x16x32_bf16 v[116:119], v[104:107], v[168:171], v[116:119]
	v_mfma_f32_16x16x32_bf16 v[108:111], v[120:123], v[168:171], v[108:111]
	v_mfma_f32_16x16x32_bf16 v[92:95], v[104:107], v[176:179], v[92:95]
	v_mfma_f32_16x16x32_bf16 v[88:91], v[120:123], v[176:179], v[88:91]
	v_mfma_f32_16x16x32_bf16 v[76:79], v[104:107], v[184:187], v[76:79]
	v_mfma_f32_16x16x32_bf16 v[72:75], v[120:123], v[184:187], v[72:75]
	v_mfma_f32_16x16x32_bf16 v[152:155], v[112:115], v[164:167], v[152:155]
	v_mfma_f32_16x16x32_bf16 v[144:147], v[128:131], v[164:167], v[144:147]
	v_mfma_f32_16x16x32_bf16 v[116:119], v[112:115], v[172:175], v[116:119]
	v_mfma_f32_16x16x32_bf16 v[108:111], v[128:131], v[172:175], v[108:111]
	v_mfma_f32_16x16x32_bf16 v[92:95], v[112:115], v[180:183], v[92:95]
	v_mfma_f32_16x16x32_bf16 v[88:91], v[128:131], v[180:183], v[88:91]
	v_mfma_f32_16x16x32_bf16 v[76:79], v[112:115], v[188:191], v[76:79]
	v_mfma_f32_16x16x32_bf16 v[72:75], v[128:131], v[188:191], v[72:75]
	v_mfma_f32_16x16x32_bf16 v[132:135], v[136:139], v[160:163], v[132:135]
	v_mfma_f32_16x16x32_bf16 v[124:127], v[148:151], v[160:163], v[124:127]
	v_mfma_f32_16x16x32_bf16 v[100:103], v[136:139], v[168:171], v[100:103]
	v_mfma_f32_16x16x32_bf16 v[96:99], v[148:151], v[168:171], v[96:99]
	v_mfma_f32_16x16x32_bf16 v[84:87], v[136:139], v[176:179], v[84:87]
	v_mfma_f32_16x16x32_bf16 v[80:83], v[148:151], v[176:179], v[80:83]
	v_mfma_f32_16x16x32_bf16 v[68:71], v[136:139], v[184:187], v[68:71]
	v_mfma_f32_16x16x32_bf16 v[64:67], v[148:151], v[184:187], v[64:67]
	v_mfma_f32_16x16x32_bf16 v[132:135], v[140:143], v[164:167], v[132:135]
	v_mfma_f32_16x16x32_bf16 v[124:127], v[156:159], v[164:167], v[124:127]
	v_mfma_f32_16x16x32_bf16 v[100:103], v[140:143], v[172:175], v[100:103]
	v_mfma_f32_16x16x32_bf16 v[96:99], v[156:159], v[172:175], v[96:99]
	v_mfma_f32_16x16x32_bf16 v[84:87], v[140:143], v[180:183], v[84:87]
	v_mfma_f32_16x16x32_bf16 v[80:83], v[156:159], v[180:183], v[80:83]
	v_mfma_f32_16x16x32_bf16 v[68:71], v[140:143], v[188:191], v[68:71]
	v_mfma_f32_16x16x32_bf16 v[64:67], v[156:159], v[188:191], v[64:67]
	s_barrier
; #define PG8_STAGE(bufoff, gbase, voff) do { _Pragma("unroll") for (int _i = 0; _i < 2; ++_i) \
;         __builtin_amdgcn_global_load_lds((const unsigned*)((const char*)(gbase) + (voff)[_i]), (LAS unsigned*)(lds + (bufoff) + ldsw + _i * 8192), 16, 0, 0); } while (0)
; #define PG8_LDA(dst, b, h) do { _Pragma("unroll") for (int m = 0; m < 4; ++m) _Pragma("unroll") for (int k = 0; k < 2; ++k) dst[m][k] = *(const LAS bf16x8*)(lds + PG8_SA(b, h) + aoff + m * 2048 + k * 1024); } while (0)
; #define PG8_LDB(dst, b, h) do { _Pragma("unroll") for (int n = 0; n < 2; ++n) _Pragma("unroll") for (int k = 0; k < 2; ++k) dst[n][k] = *(const LAS bf16x8*)(lds + PG8_SB(b, h) + boff + n * 2048 + k * 1024); } while (0)
; #define PG8_WAIT_V(n) asm volatile("s_waitcnt vmcnt(" #n ")" ::: "memory")
; #define PG8_WAIT_L(n) asm volatile("s_waitcnt lgkmcnt(" #n ")" ::: "memory")
; template <class Epi>
; __device__ __forceinline__ void gemm_phase(LAS unsigned char* lds, const Gemm g, const Sched& S, const Epi& E, const int tid) {
;     ...
;         for (int t = 0; t < nt; t += 2) {
;             const bool last = (t == nt - 2);
;             const char* a1 = cA + (size_t)(t + 1) * kstep;
;             const char* a2 = last ? nA : cA + (size_t)(t + 2) * kstep; const char* b2 = last ? nB : cB + (size_t)(t + 2) * kstep;
;             const char* a3 = a2 + kstep; const char* b3 = b2 + kstep;
;             PG8_LDB(B0, 0, 0); PG8_LDB(B1, 0, 1); PG8_SCHED; PG8_LDA(At, 0, 0); PG8_STAGE(PG8_SA(1, 1), a1 + hA, voffA);
;             PG8_WAIT_V(8); PG8_WAIT_L(0); PG8_BAR; PG8_MMA(0, 0, At, B0); PG8_MMA(0, 1, At, B1); PG8_BAR; PG8_SCHED;
;             PG8_LDA(At, 0, 1); PG8_STAGE(PG8_SB(0, 0), b2, voffB); PG8_STAGE(PG8_SB(0, 1), b2 + hB, voffB); PG8_STAGE(PG8_SA(0, 0), a2, voffA);
;             PG8_WAIT_V(8); PG8_WAIT_L(0); PG8_BAR; PG8_MMA(1, 0, At, B0); PG8_MMA(1, 1, At, B1); PG8_BAR; PG8_SCHED;
;             PG8_LDB(B0, 1, 0); PG8_LDB(B1, 1, 1); PG8_SCHED; PG8_LDA(At, 1, 0); PG8_STAGE(PG8_SA(0, 1), a2 + hA, voffA);
;             PG8_WAIT_V(8); PG8_WAIT_L(0); PG8_BAR; PG8_MMA(0, 0, At, B0); PG8_MMA(0, 1, At, B1); PG8_BAR; PG8_SCHED;
;             PG8_LDA(At, 1, 1); PG8_STAGE(PG8_SB(1, 0), b3, voffB); PG8_STAGE(PG8_SB(1, 1), b3 + hB, voffB); PG8_STAGE(PG8_SA(1, 0), a3, voffA);
;             PG8_WAIT_V(8); PG8_WAIT_L(0); PG8_BAR; PG8_MMA(1, 0, At, B0); PG8_MMA(1, 1, At, B1); PG8_BAR; PG8_SCHED;
	s_add_i32 s20, s42, s35
	v_lshl_add_u64 v[194:195], v[194:195], 0, s[94:95]
	s_mov_b32 m0, s20
	ds_read_b128 v[160:163], v243 offset:49152
	ds_read_b128 v[164:167], v243 offset:50176
	ds_read_b128 v[168:171], v243 offset:51200
	ds_read_b128 v[172:175], v243 offset:52224
	ds_read_b128 v[176:179], v243 offset:53248
	ds_read_b128 v[180:183], v243 offset:54272
	ds_read_b128 v[184:187], v243 offset:55296
	ds_read_b128 v[188:191], v243 offset:56320
	global_load_lds_dwordx4 v[194:195], off
	s_add_i32 m0, s20, 0x2000
	s_add_u32 s20, s22, 0x20080
	v_lshl_add_u64 v[194:195], v[196:197], 0, s[94:95]
	s_addc_u32 s21, s23, 0
	s_add_i32 s22, s45, s35
	global_load_lds_dwordx4 v[194:195], off
	v_lshl_add_u64 v[194:195], s[20:21], 0, v[192:193]
	s_mov_b32 m0, s22
	s_nop 0
	global_load_lds_dwordx4 v[194:195], off
	v_lshl_add_u64 v[194:195], s[20:21], 0, v[208:209]
	s_add_i32 m0, s22, 0x2000
	s_nop 0
	global_load_lds_dwordx4 v[194:195], off
	v_lshl_add_u64 v[194:195], v[198:199], 0, s[94:95]
	s_mov_b32 m0, s77
	s_nop 0
	global_load_lds_dwordx4 v[194:195], off
	v_lshl_add_u64 v[194:195], v[200:201], 0, s[94:95]
	s_mov_b32 m0, s78
	s_nop 0
	global_load_lds_dwordx4 v[194:195], off
	s_waitcnt vmcnt(8)
	s_waitcnt lgkmcnt(0)
	s_barrier
	s_waitcnt lgkmcnt(0)
	v_mfma_f32_16x16x32_bf16 v[60:63], v[104:107], v[160:163], v[60:63]
	v_mfma_f32_16x16x32_bf16 v[56:59], v[120:123], v[160:163], v[56:59]
	v_mfma_f32_16x16x32_bf16 v[44:47], v[104:107], v[168:171], v[44:47]
	v_mfma_f32_16x16x32_bf16 v[40:43], v[120:123], v[168:171], v[40:43]
	v_mfma_f32_16x16x32_bf16 v[28:31], v[104:107], v[176:179], v[28:31]
	v_mfma_f32_16x16x32_bf16 v[24:27], v[120:123], v[176:179], v[24:27]
	v_mfma_f32_16x16x32_bf16 v[12:15], v[104:107], v[184:187], v[12:15]
	v_mfma_f32_16x16x32_bf16 v[8:11], v[120:123], v[184:187], v[8:11]
	v_mfma_f32_16x16x32_bf16 v[60:63], v[112:115], v[164:167], v[60:63]
	v_mfma_f32_16x16x32_bf16 v[56:59], v[128:131], v[164:167], v[56:59]
	v_mfma_f32_16x16x32_bf16 v[44:47], v[112:115], v[172:175], v[44:47]
	v_mfma_f32_16x16x32_bf16 v[40:43], v[128:131], v[172:175], v[40:43]
	v_mfma_f32_16x16x32_bf16 v[28:31], v[112:115], v[180:183], v[28:31]
	v_mfma_f32_16x16x32_bf16 v[24:27], v[128:131], v[180:183], v[24:27]
	v_mfma_f32_16x16x32_bf16 v[12:15], v[112:115], v[188:191], v[12:15]
	v_mfma_f32_16x16x32_bf16 v[8:11], v[128:131], v[188:191], v[8:11]
	v_mfma_f32_16x16x32_bf16 v[52:55], v[136:139], v[160:163], v[52:55]
	v_mfma_f32_16x16x32_bf16 v[48:51], v[148:151], v[160:163], v[48:51]
	v_mfma_f32_16x16x32_bf16 v[36:39], v[136:139], v[168:171], v[36:39]
	v_mfma_f32_16x16x32_bf16 v[32:35], v[148:151], v[168:171], v[32:35]
	v_mfma_f32_16x16x32_bf16 v[20:23], v[136:139], v[176:179], v[20:23]
	v_mfma_f32_16x16x32_bf16 v[16:19], v[148:151], v[176:179], v[16:19]
	v_mfma_f32_16x16x32_bf16 v[4:7], v[136:139], v[184:187], v[4:7]
	v_mfma_f32_16x16x32_bf16 v[0:3], v[148:151], v[184:187], v[0:3]
	v_mfma_f32_16x16x32_bf16 v[52:55], v[140:143], v[164:167], v[52:55]
	v_mfma_f32_16x16x32_bf16 v[48:51], v[156:159], v[164:167], v[48:51]
	v_mfma_f32_16x16x32_bf16 v[36:39], v[140:143], v[172:175], v[36:39]
	v_mfma_f32_16x16x32_bf16 v[32:35], v[156:159], v[172:175], v[32:35]
	v_mfma_f32_16x16x32_bf16 v[20:23], v[140:143], v[180:183], v[20:23]
	v_mfma_f32_16x16x32_bf16 v[16:19], v[156:159], v[180:183], v[16:19]
	v_mfma_f32_16x16x32_bf16 v[4:7], v[140:143], v[188:191], v[4:7]
	v_mfma_f32_16x16x32_bf16 v[0:3], v[156:159], v[188:191], v[0:3]
	s_barrier
	s_add_i32 s40, s40, 2
	s_add_u32 s13, s13, 0x100
	s_addc_u32 s37, s37, 0
	s_cmp_gt_u32 s40, 5
	s_mov_b64 s[20:21], s[6:7]
	s_cbranch_scc1 .Lgk_exit_2
.LBB0_1029:
	s_add_u32 s6, s20, 0x100
	s_addc_u32 s7, s21, 0
	s_add_i32 s42, 0, 0x10000
	s_cmp_eq_u32 s40, 4
	s_cselect_b32 s73, s15, s7
	s_cselect_b32 s72, s14, s6
	s_cselect_b32 s23, s17, s37
	s_cselect_b32 s22, s16, s13
	s_add_i32 s45, 0, 0x14000
	v_add_u32_e32 v128, s42, v241
	v_add_u32_e32 v156, s45, v241
	ds_read_b128 v[104:107], v128
	ds_read_b128 v[112:115], v128 offset:1024
	ds_read_b128 v[120:123], v128 offset:2048
	ds_read_b128 v[128:131], v128 offset:3072
	ds_read_b128 v[136:139], v156
	ds_read_b128 v[140:143], v156 offset:1024
	ds_read_b128 v[148:151], v156 offset:2048
	ds_read_b128 v[156:159], v156 offset:3072
	v_lshl_add_u64 v[194:195], s[20:21], 0, v[210:211]
	s_add_i32 m0, s19, 0xc000
	ds_read_b128 v[160:163], v243
	ds_read_b128 v[164:167], v243 offset:1024
	ds_read_b128 v[168:171], v243 offset:2048
	ds_read_b128 v[172:175], v243 offset:3072
	ds_read_b128 v[176:179], v243 offset:4096
	ds_read_b128 v[180:183], v243 offset:5120
	ds_read_b128 v[184:187], v243 offset:6144
	ds_read_b128 v[188:191], v243 offset:7168
	global_load_lds_dwordx4 v[194:195], off
	v_lshl_add_u64 v[194:195], s[20:21], 0, v[212:213]
	s_add_i32 m0, s19, 0xe000
	s_nop 0
	global_load_lds_dwordx4 v[194:195], off
	s_waitcnt vmcnt(8)
	s_waitcnt lgkmcnt(0)
	s_barrier
; #define PG8_STAGE(bufoff, gbase, voff) do { _Pragma("unroll") for (int _i = 0; _i < 2; ++_i) \
;         __builtin_amdgcn_global_load_lds((const unsigned*)((const char*)(gbase) + (voff)[_i]), (LAS unsigned*)(lds + (bufoff) + ldsw + _i * 8192), 16, 0, 0); } while (0)
; #define PG8_LDA(dst, b, h) do { _Pragma("unroll") for (int m = 0; m < 4; ++m) _Pragma("unroll") for (int k = 0; k < 2; ++k) dst[m][k] = *(const LAS bf16x8*)(lds + PG8_SA(b, h) + aoff + m * 2048 + k * 1024); } while (0)
; #define PG8_MMA(ai, bj, At, Bt) do { __builtin_amdgcn_s_setprio(1); _Pragma("unroll") for (int m = 0; m < 4; ++m) _Pragma("unroll") for (int n = 0; n < 2; ++n) _Pragma("unroll") for (int k = 0; k < 2; ++k) \
;         acc[ai][bj][m][n] = __builtin_amdgcn_mfma_f32_16x16x32_bf16(Bt[n][k], At[m][k], acc[ai][bj][m][n], 0, 0, 0); __builtin_amdgcn_s_setprio(0); } while (0)
; #define PG8_WAIT_V(n) asm volatile("s_waitcnt vmcnt(" #n ")" ::: "memory")
; #define PG8_WAIT_L(n) asm volatile("s_waitcnt lgkmcnt(" #n ")" ::: "memory")
; #define PG8_BAR __builtin_amdgcn_s_barrier()
; #define PG8_SCHED __builtin_amdgcn_sched_barrier(0)
; template <class Epi>
; __device__ __forceinline__ void gemm_phase(LAS unsigned char* lds, const Gemm g, const Sched& S, const Epi& E, const int tid) {
;     ...
;             PG8_WAIT_V(8); PG8_WAIT_L(0); PG8_BAR; PG8_MMA(0, 0, At, B0); PG8_MMA(0, 1, At, B1); PG8_BAR; PG8_SCHED;
;             PG8_LDA(At, 0, 1); PG8_STAGE(PG8_SB(0, 0), b2, voffB); PG8_STAGE(PG8_SB(0, 1), b2 + hB, voffB); PG8_STAGE(PG8_SA(0, 0), a2, voffA);
;             PG8_WAIT_V(8); PG8_WAIT_L(0); PG8_BAR; PG8_MMA(1, 0, At, B0); PG8_MMA(1, 1, At, B1); PG8_BAR; PG8_SCHED;
	s_waitcnt lgkmcnt(0)
	v_mfma_f32_16x16x32_bf16 v[152:155], v[104:107], v[160:163], v[152:155]
	v_mfma_f32_16x16x32_bf16 v[144:147], v[120:123], v[160:163], v[144:147]
	v_mfma_f32_16x16x32_bf16 v[116:119], v[104:107], v[168:171], v[116:119]
	v_mfma_f32_16x16x32_bf16 v[108:111], v[120:123], v[168:171], v[108:111]
	v_mfma_f32_16x16x32_bf16 v[92:95], v[104:107], v[176:179], v[92:95]
	v_mfma_f32_16x16x32_bf16 v[88:91], v[120:123], v[176:179], v[88:91]
	v_mfma_f32_16x16x32_bf16 v[76:79], v[104:107], v[184:187], v[76:79]
	v_mfma_f32_16x16x32_bf16 v[72:75], v[120:123], v[184:187], v[72:75]
	v_mfma_f32_16x16x32_bf16 v[152:155], v[112:115], v[164:167], v[152:155]
	v_mfma_f32_16x16x32_bf16 v[144:147], v[128:131], v[164:167], v[144:147]
	v_mfma_f32_16x16x32_bf16 v[116:119], v[112:115], v[172:175], v[116:119]
	v_mfma_f32_16x16x32_bf16 v[108:111], v[128:131], v[172:175], v[108:111]
	v_mfma_f32_16x16x32_bf16 v[92:95], v[112:115], v[180:183], v[92:95]
	v_mfma_f32_16x16x32_bf16 v[88:91], v[128:131], v[180:183], v[88:91]
	v_mfma_f32_16x16x32_bf16 v[76:79], v[112:115], v[188:191], v[76:79]
	v_mfma_f32_16x16x32_bf16 v[72:75], v[128:131], v[188:191], v[72:75]
	v_mfma_f32_16x16x32_bf16 v[132:135], v[136:139], v[160:163], v[132:135]
	v_mfma_f32_16x16x32_bf16 v[124:127], v[148:151], v[160:163], v[124:127]
	v_mfma_f32_16x16x32_bf16 v[100:103], v[136:139], v[168:171], v[100:103]
	v_mfma_f32_16x16x32_bf16 v[96:99], v[148:151], v[168:171], v[96:99]
	v_mfma_f32_16x16x32_bf16 v[84:87], v[136:139], v[176:179], v[84:87]
	v_mfma_f32_16x16x32_bf16 v[80:83], v[148:151], v[176:179], v[80:83]
	v_mfma_f32_16x16x32_bf16 v[68:71], v[136:139], v[184:187], v[68:71]
	v_mfma_f32_16x16x32_bf16 v[64:67], v[148:151], v[184:187], v[64:67]
	v_mfma_f32_16x16x32_bf16 v[132:135], v[140:143], v[164:167], v[132:135]
	v_mfma_f32_16x16x32_bf16 v[124:127], v[156:159], v[164:167], v[124:127]
	v_mfma_f32_16x16x32_bf16 v[100:103], v[140:143], v[172:175], v[100:103]
	v_mfma_f32_16x16x32_bf16 v[96:99], v[156:159], v[172:175], v[96:99]
	v_mfma_f32_16x16x32_bf16 v[84:87], v[140:143], v[180:183], v[84:87]
	v_mfma_f32_16x16x32_bf16 v[80:83], v[156:159], v[180:183], v[80:83]
	v_mfma_f32_16x16x32_bf16 v[68:71], v[140:143], v[188:191], v[68:71]
	v_mfma_f32_16x16x32_bf16 v[64:67], v[156:159], v[188:191], v[64:67]
	s_barrier
	s_add_i32 s20, s42, s35
	v_lshl_add_u64 v[194:195], s[22:23], 0, v[192:193]
	s_mov_b32 m0, s20
	ds_read_b128 v[160:163], v243 offset:16384
	ds_read_b128 v[164:167], v243 offset:17408
	ds_read_b128 v[168:171], v243 offset:18432
	ds_read_b128 v[172:175], v243 offset:19456
	ds_read_b128 v[176:179], v243 offset:20480
	ds_read_b128 v[180:183], v243 offset:21504
	ds_read_b128 v[184:187], v243 offset:22528
	ds_read_b128 v[188:191], v243 offset:23552
	global_load_lds_dwordx4 v[194:195], off
	s_add_i32 m0, s20, 0x2000
	s_add_u32 s20, s22, 0x20000
	v_lshl_add_u64 v[196:197], s[22:23], 0, v[208:209]
	s_addc_u32 s21, s23, 0
	s_add_i32 s42, s45, s35
	global_load_lds_dwordx4 v[196:197], off
	v_lshl_add_u64 v[198:199], s[20:21], 0, v[192:193]
	s_mov_b32 m0, s42
	v_lshl_add_u64 v[200:201], s[72:73], 0, v[206:207]
	global_load_lds_dwordx4 v[198:199], off
	v_lshl_add_u64 v[198:199], s[20:21], 0, v[208:209]
	s_add_i32 m0, s42, 0x2000
	s_nop 0
	global_load_lds_dwordx4 v[198:199], off
	v_lshl_add_u64 v[198:199], s[72:73], 0, v[204:205]
	s_mov_b32 m0, s19
	s_nop 0
	global_load_lds_dwordx4 v[198:199], off
	s_mov_b32 m0, s74
	s_nop 0
	global_load_lds_dwordx4 v[200:201], off
	s_waitcnt vmcnt(8)
	s_waitcnt lgkmcnt(0)
	s_barrier
	s_waitcnt lgkmcnt(0)
	v_mfma_f32_16x16x32_bf16 v[60:63], v[104:107], v[160:163], v[60:63]
	v_mfma_f32_16x16x32_bf16 v[56:59], v[120:123], v[160:163], v[56:59]
	v_mfma_f32_16x16x32_bf16 v[44:47], v[104:107], v[168:171], v[44:47]
	v_mfma_f32_16x16x32_bf16 v[40:43], v[120:123], v[168:171], v[40:43]
	v_mfma_f32_16x16x32_bf16 v[28:31], v[104:107], v[176:179], v[28:31]
	v_mfma_f32_16x16x32_bf16 v[24:27], v[120:123], v[176:179], v[24:27]
	v_mfma_f32_16x16x32_bf16 v[12:15], v[104:107], v[184:187], v[12:15]
	v_mfma_f32_16x16x32_bf16 v[8:11], v[120:123], v[184:187], v[8:11]
	v_mfma_f32_16x16x32_bf16 v[60:63], v[112:115], v[164:167], v[60:63]
	v_mfma_f32_16x16x32_bf16 v[56:59], v[128:131], v[164:167], v[56:59]
	v_mfma_f32_16x16x32_bf16 v[44:47], v[112:115], v[172:175], v[44:47]
	v_mfma_f32_16x16x32_bf16 v[40:43], v[128:131], v[172:175], v[40:43]
	v_mfma_f32_16x16x32_bf16 v[28:31], v[112:115], v[180:183], v[28:31]
	v_mfma_f32_16x16x32_bf16 v[24:27], v[128:131], v[180:183], v[24:27]
	v_mfma_f32_16x16x32_bf16 v[12:15], v[112:115], v[188:191], v[12:15]
	v_mfma_f32_16x16x32_bf16 v[8:11], v[128:131], v[188:191], v[8:11]
	v_mfma_f32_16x16x32_bf16 v[52:55], v[136:139], v[160:163], v[52:55]
	v_mfma_f32_16x16x32_bf16 v[48:51], v[148:151], v[160:163], v[48:51]
	v_mfma_f32_16x16x32_bf16 v[36:39], v[136:139], v[168:171], v[36:39]
	v_mfma_f32_16x16x32_bf16 v[32:35], v[148:151], v[168:171], v[32:35]
	v_mfma_f32_16x16x32_bf16 v[20:23], v[136:139], v[176:179], v[20:23]
	v_mfma_f32_16x16x32_bf16 v[16:19], v[148:151], v[176:179], v[16:19]
	v_mfma_f32_16x16x32_bf16 v[4:7], v[136:139], v[184:187], v[4:7]
	v_mfma_f32_16x16x32_bf16 v[0:3], v[148:151], v[184:187], v[0:3]
	v_mfma_f32_16x16x32_bf16 v[52:55], v[140:143], v[164:167], v[52:55]
	v_mfma_f32_16x16x32_bf16 v[48:51], v[156:159], v[164:167], v[48:51]
	v_mfma_f32_16x16x32_bf16 v[36:39], v[140:143], v[172:175], v[36:39]
	v_mfma_f32_16x16x32_bf16 v[32:35], v[156:159], v[172:175], v[32:35]
	v_mfma_f32_16x16x32_bf16 v[20:23], v[140:143], v[180:183], v[20:23]
	v_mfma_f32_16x16x32_bf16 v[16:19], v[156:159], v[180:183], v[16:19]
	v_mfma_f32_16x16x32_bf16 v[4:7], v[140:143], v[188:191], v[4:7]
	v_mfma_f32_16x16x32_bf16 v[0:3], v[156:159], v[188:191], v[0:3]
	s_barrier
; #define PG8_STAGE(bufoff, gbase, voff) do { _Pragma("unroll") for (int _i = 0; _i < 2; ++_i) \
;         __builtin_amdgcn_global_load_lds((const unsigned*)((const char*)(gbase) + (voff)[_i]), (LAS unsigned*)(lds + (bufoff) + ldsw + _i * 8192), 16, 0, 0); } while (0)
; #define PG8_LDA(dst, b, h) do { _Pragma("unroll") for (int m = 0; m < 4; ++m) _Pragma("unroll") for (int k = 0; k < 2; ++k) dst[m][k] = *(const LAS bf16x8*)(lds + PG8_SA(b, h) + aoff + m * 2048 + k * 1024); } while (0)
; #define PG8_LDB(dst, b, h) do { _Pragma("unroll") for (int n = 0; n < 2; ++n) _Pragma("unroll") for (int k = 0; k < 2; ++k) dst[n][k] = *(const LAS bf16x8*)(lds + PG8_SB(b, h) + boff + n * 2048 + k * 1024); } while (0)
; #define PG8_MMA(ai, bj, At, Bt) do { __builtin_amdgcn_s_setprio(1); _Pragma("unroll") for (int m = 0; m < 4; ++m) _Pragma("unroll") for (int n = 0; n < 2; ++n) _Pragma("unroll") for (int k = 0; k < 2; ++k) \
;         acc[ai][bj][m][n] = __builtin_amdgcn_mfma_f32_16x16x32_bf16(Bt[n][k], At[m][k], acc[ai][bj][m][n], 0, 0, 0); __builtin_amdgcn_s_setprio(0); } while (0)
; #define PG8_WAIT_V(n) asm volatile("s_waitcnt vmcnt(" #n ")" ::: "memory")
; #define PG8_WAIT_L(n) asm volatile("s_waitcnt lgkmcnt(" #n ")" ::: "memory")
; #define PG8_BAR __builtin_amdgcn_s_barrier()
; #define PG8_SCHED __builtin_amdgcn_sched_barrier(0)
; template <class Epi>
; __device__ __forceinline__ void gemm_phase(LAS unsigned char* lds, const Gemm g, const Sched& S, const Epi& E, const int tid) {
;     ...
;             PG8_LDB(B0, 1, 0); PG8_LDB(B1, 1, 1); PG8_SCHED; PG8_LDA(At, 1, 0); PG8_STAGE(PG8_SA(0, 1), a2 + hA, voffA);
;             PG8_WAIT_V(8); PG8_WAIT_L(0); PG8_BAR; PG8_MMA(0, 0, At, B0); PG8_MMA(0, 1, At, B1); PG8_BAR; PG8_SCHED;
;             PG8_LDA(At, 1, 1); PG8_STAGE(PG8_SB(1, 0), b3, voffB); PG8_STAGE(PG8_SB(1, 1), b3 + hB, voffB); PG8_STAGE(PG8_SA(1, 0), a3, voffA);
;             PG8_WAIT_V(8); PG8_WAIT_L(0); PG8_BAR; PG8_MMA(1, 0, At, B0); PG8_MMA(1, 1, At, B1); PG8_BAR; PG8_SCHED;
;         }
	s_add_i32 s42, 0, 0x18000
	s_add_i32 s45, 0, 0x1c000
	v_add_u32_e32 v128, s42, v241
	v_add_u32_e32 v156, s45, v241
	ds_read_b128 v[104:107], v128
	ds_read_b128 v[112:115], v128 offset:1024
	ds_read_b128 v[120:123], v128 offset:2048
	ds_read_b128 v[128:131], v128 offset:3072
	ds_read_b128 v[136:139], v156
	ds_read_b128 v[140:143], v156 offset:1024
	ds_read_b128 v[148:151], v156 offset:2048
	ds_read_b128 v[156:159], v156 offset:3072
	s_add_u32 s20, s72, 0x120000
	s_addc_u32 s21, s73, 0
	s_mov_b32 m0, s75
	v_lshl_add_u64 v[214:215], s[20:21], 0, v[204:205]
	ds_read_b128 v[160:163], v243 offset:32768
	ds_read_b128 v[164:167], v243 offset:33792
	ds_read_b128 v[168:171], v243 offset:34816
	ds_read_b128 v[172:175], v243 offset:35840
	ds_read_b128 v[176:179], v243 offset:36864
	ds_read_b128 v[180:183], v243 offset:37888
	ds_read_b128 v[184:187], v243 offset:38912
	ds_read_b128 v[188:191], v243 offset:39936
	global_load_lds_dwordx4 v[214:215], off
	v_lshl_add_u64 v[214:215], s[20:21], 0, v[206:207]
	s_mov_b32 m0, s76
	s_nop 0
	global_load_lds_dwordx4 v[214:215], off
	s_waitcnt vmcnt(8)
	s_waitcnt lgkmcnt(0)
	s_barrier
	s_waitcnt lgkmcnt(0)
	v_mfma_f32_16x16x32_bf16 v[152:155], v[104:107], v[160:163], v[152:155]
	v_mfma_f32_16x16x32_bf16 v[144:147], v[120:123], v[160:163], v[144:147]
	v_mfma_f32_16x16x32_bf16 v[116:119], v[104:107], v[168:171], v[116:119]
	v_mfma_f32_16x16x32_bf16 v[108:111], v[120:123], v[168:171], v[108:111]
	v_mfma_f32_16x16x32_bf16 v[92:95], v[104:107], v[176:179], v[92:95]
	v_mfma_f32_16x16x32_bf16 v[88:91], v[120:123], v[176:179], v[88:91]
	v_mfma_f32_16x16x32_bf16 v[76:79], v[104:107], v[184:187], v[76:79]
	v_mfma_f32_16x16x32_bf16 v[72:75], v[120:123], v[184:187], v[72:75]
	v_mfma_f32_16x16x32_bf16 v[152:155], v[112:115], v[164:167], v[152:155]
	v_mfma_f32_16x16x32_bf16 v[144:147], v[128:131], v[164:167], v[144:147]
	v_mfma_f32_16x16x32_bf16 v[116:119], v[112:115], v[172:175], v[116:119]
	v_mfma_f32_16x16x32_bf16 v[108:111], v[128:131], v[172:175], v[108:111]
	v_mfma_f32_16x16x32_bf16 v[92:95], v[112:115], v[180:183], v[92:95]
	v_mfma_f32_16x16x32_bf16 v[88:91], v[128:131], v[180:183], v[88:91]
	v_mfma_f32_16x16x32_bf16 v[76:79], v[112:115], v[188:191], v[76:79]
	v_mfma_f32_16x16x32_bf16 v[72:75], v[128:131], v[188:191], v[72:75]
	v_mfma_f32_16x16x32_bf16 v[132:135], v[136:139], v[160:163], v[132:135]
	v_mfma_f32_16x16x32_bf16 v[124:127], v[148:151], v[160:163], v[124:127]
	v_mfma_f32_16x16x32_bf16 v[100:103], v[136:139], v[168:171], v[100:103]
	v_mfma_f32_16x16x32_bf16 v[96:99], v[148:151], v[168:171], v[96:99]
	v_mfma_f32_16x16x32_bf16 v[84:87], v[136:139], v[176:179], v[84:87]
	v_mfma_f32_16x16x32_bf16 v[80:83], v[148:151], v[176:179], v[80:83]
	v_mfma_f32_16x16x32_bf16 v[68:71], v[136:139], v[184:187], v[68:71]
	v_mfma_f32_16x16x32_bf16 v[64:67], v[148:151], v[184:187], v[64:67]
	v_mfma_f32_16x16x32_bf16 v[132:135], v[140:143], v[164:167], v[132:135]
	v_mfma_f32_16x16x32_bf16 v[124:127], v[156:159], v[164:167], v[124:127]
	v_mfma_f32_16x16x32_bf16 v[100:103], v[140:143], v[172:175], v[100:103]
	v_mfma_f32_16x16x32_bf16 v[96:99], v[156:159], v[172:175], v[96:99]
	v_mfma_f32_16x16x32_bf16 v[84:87], v[140:143], v[180:183], v[84:87]
	v_mfma_f32_16x16x32_bf16 v[80:83], v[156:159], v[180:183], v[80:83]
	v_mfma_f32_16x16x32_bf16 v[68:71], v[140:143], v[188:191], v[68:71]
	v_mfma_f32_16x16x32_bf16 v[64:67], v[156:159], v[188:191], v[64:67]
	s_barrier
	s_add_i32 s20, s42, s35
	v_lshl_add_u64 v[194:195], v[194:195], 0, s[94:95]
	s_mov_b32 m0, s20
	ds_read_b128 v[160:163], v243 offset:49152
	ds_read_b128 v[164:167], v243 offset:50176
	ds_read_b128 v[168:171], v243 offset:51200
	ds_read_b128 v[172:175], v243 offset:52224
	ds_read_b128 v[176:179], v243 offset:53248
	ds_read_b128 v[180:183], v243 offset:54272
	ds_read_b128 v[184:187], v243 offset:55296
	ds_read_b128 v[188:191], v243 offset:56320
	global_load_lds_dwordx4 v[194:195], off
	s_add_i32 m0, s20, 0x2000
	s_add_u32 s20, s22, 0x20080
	v_lshl_add_u64 v[194:195], v[196:197], 0, s[94:95]
	s_addc_u32 s21, s23, 0
	s_add_i32 s22, s45, s35
	global_load_lds_dwordx4 v[194:195], off
	v_lshl_add_u64 v[194:195], s[20:21], 0, v[192:193]
	s_mov_b32 m0, s22
	s_nop 0
	global_load_lds_dwordx4 v[194:195], off
	v_lshl_add_u64 v[194:195], s[20:21], 0, v[208:209]
	s_add_i32 m0, s22, 0x2000
	s_nop 0
	global_load_lds_dwordx4 v[194:195], off
	v_lshl_add_u64 v[194:195], v[198:199], 0, s[94:95]
	s_mov_b32 m0, s77
	s_nop 0
	global_load_lds_dwordx4 v[194:195], off
	v_lshl_add_u64 v[194:195], v[200:201], 0, s[94:95]
	s_mov_b32 m0, s78
	s_nop 0
	global_load_lds_dwordx4 v[194:195], off
	s_waitcnt vmcnt(8)
	s_waitcnt lgkmcnt(0)
	s_barrier
	s_waitcnt lgkmcnt(0)
	v_mfma_f32_16x16x32_bf16 v[60:63], v[104:107], v[160:163], v[60:63]
	v_mfma_f32_16x16x32_bf16 v[56:59], v[120:123], v[160:163], v[56:59]
	v_mfma_f32_16x16x32_bf16 v[44:47], v[104:107], v[168:171], v[44:47]
	v_mfma_f32_16x16x32_bf16 v[40:43], v[120:123], v[168:171], v[40:43]
	v_mfma_f32_16x16x32_bf16 v[28:31], v[104:107], v[176:179], v[28:31]
	v_mfma_f32_16x16x32_bf16 v[24:27], v[120:123], v[176:179], v[24:27]
	v_mfma_f32_16x16x32_bf16 v[12:15], v[104:107], v[184:187], v[12:15]
	v_mfma_f32_16x16x32_bf16 v[8:11], v[120:123], v[184:187], v[8:11]
	v_mfma_f32_16x16x32_bf16 v[60:63], v[112:115], v[164:167], v[60:63]
	v_mfma_f32_16x16x32_bf16 v[56:59], v[128:131], v[164:167], v[56:59]
	v_mfma_f32_16x16x32_bf16 v[44:47], v[112:115], v[172:175], v[44:47]
	v_mfma_f32_16x16x32_bf16 v[40:43], v[128:131], v[172:175], v[40:43]
	v_mfma_f32_16x16x32_bf16 v[28:31], v[112:115], v[180:183], v[28:31]
	v_mfma_f32_16x16x32_bf16 v[24:27], v[128:131], v[180:183], v[24:27]
	v_mfma_f32_16x16x32_bf16 v[12:15], v[112:115], v[188:191], v[12:15]
	v_mfma_f32_16x16x32_bf16 v[8:11], v[128:131], v[188:191], v[8:11]
	v_mfma_f32_16x16x32_bf16 v[52:55], v[136:139], v[160:163], v[52:55]
	v_mfma_f32_16x16x32_bf16 v[48:51], v[148:151], v[160:163], v[48:51]
	v_mfma_f32_16x16x32_bf16 v[36:39], v[136:139], v[168:171], v[36:39]
	v_mfma_f32_16x16x32_bf16 v[32:35], v[148:151], v[168:171], v[32:35]
	v_mfma_f32_16x16x32_bf16 v[20:23], v[136:139], v[176:179], v[20:23]
	v_mfma_f32_16x16x32_bf16 v[16:19], v[148:151], v[176:179], v[16:19]
	v_mfma_f32_16x16x32_bf16 v[4:7], v[136:139], v[184:187], v[4:7]
	v_mfma_f32_16x16x32_bf16 v[0:3], v[148:151], v[184:187], v[0:3]
	v_mfma_f32_16x16x32_bf16 v[52:55], v[140:143], v[164:167], v[52:55]
	v_mfma_f32_16x16x32_bf16 v[48:51], v[156:159], v[164:167], v[48:51]
	v_mfma_f32_16x16x32_bf16 v[36:39], v[140:143], v[172:175], v[36:39]
	v_mfma_f32_16x16x32_bf16 v[32:35], v[156:159], v[172:175], v[32:35]
	v_mfma_f32_16x16x32_bf16 v[20:23], v[140:143], v[180:183], v[20:23]
	v_mfma_f32_16x16x32_bf16 v[16:19], v[156:159], v[180:183], v[16:19]
	v_mfma_f32_16x16x32_bf16 v[4:7], v[140:143], v[188:191], v[4:7]
	v_mfma_f32_16x16x32_bf16 v[0:3], v[156:159], v[188:191], v[0:3]
	s_barrier
	s_add_i32 s40, s40, 2
	s_add_u32 s13, s13, 0x100
	s_addc_u32 s37, s37, 0
	s_cmp_gt_u32 s40, 5
	s_mov_b64 s[20:21], s[6:7]
	s_cbranch_scc0 .LBB0_1029

; #define PG8_STAGE(bufoff, gbase, voff) do { _Pragma("unroll") for (int _i = 0; _i < 2; ++_i) \
;         __builtin_amdgcn_global_load_lds((const unsigned*)((const char*)(gbase) + (voff)[_i]), (LAS unsigned*)(lds + (bufoff) + ldsw + _i * 8192), 16, 0, 0); } while (0)
; #define PG8_LDA(dst, b, h) do { _Pragma("unroll") for (int m = 0; m < 4; ++m) _Pragma("unroll") for (int k = 0; k < 2; ++k) dst[m][k] = *(const LAS bf16x8*)(lds + PG8_SA(b, h) + aoff + m * 2048 + k * 1024); } while (0)
; #define PG8_LDB(dst, b, h) do { _Pragma("unroll") for (int n = 0; n < 2; ++n) _Pragma("unroll") for (int k = 0; k < 2; ++k) dst[n][k] = *(const LAS bf16x8*)(lds + PG8_SB(b, h) + boff + n * 2048 + k * 1024); } while (0)
; #define PG8_MMA(ai, bj, At, Bt) do { __builtin_amdgcn_s_setprio(1); _Pragma("unroll") for (int m = 0; m < 4; ++m) _Pragma("unroll") for (int n = 0; n < 2; ++n) _Pragma("unroll") for (int k = 0; k < 2; ++k) \
;         acc[ai][bj][m][n] = __builtin_amdgcn_mfma_f32_16x16x32_bf16(Bt[n][k], At[m][k], acc[ai][bj][m][n], 0, 0, 0); __builtin_amdgcn_s_setprio(0); } while (0)
; #define PG8_WAIT_V(n) asm volatile("s_waitcnt vmcnt(" #n ")" ::: "memory")
; #define PG8_WAIT_L(n) asm volatile("s_waitcnt lgkmcnt(" #n ")" ::: "memory")
; #define PG8_BAR __builtin_amdgcn_s_barrier()
; template <class Epi>
; __device__ __forceinline__ void gemm_phase(LAS unsigned char* lds, const Gemm g, const Sched& S, const Epi& E, const int tid) {
;     ...
;         const char* nA = cA; const char* nB = cB; if (has_next) S.ptrs(nxt, nA, nB);
;         for (int t = 0; t < nt; t += 2) {
;             const bool last = (t == nt - 2);
;             const char* a1 = cA + (size_t)(t + 1) * kstep;
;             const char* a2 = last ? nA : cA + (size_t)(t + 2) * kstep; const char* b2 = last ? nB : cB + (size_t)(t + 2) * kstep;
;             const char* a3 = a2 + kstep; const char* b3 = b2 + kstep;
;             PG8_LDB(B0, 0, 0); PG8_LDB(B1, 0, 1); PG8_SCHED; PG8_LDA(At, 0, 0); PG8_STAGE(PG8_SA(1, 1), a1 + hA, voffA);
;             PG8_WAIT_V(8); PG8_WAIT_L(0); PG8_BAR; PG8_MMA(0, 0, At, B0); PG8_MMA(0, 1, At, B1); PG8_BAR; PG8_SCHED;
;             PG8_LDA(At, 0, 1); PG8_STAGE(PG8_SB(0, 0), b2, voffB); PG8_STAGE(PG8_SB(0, 1), b2 + hB, voffB); PG8_STAGE(PG8_SA(0, 0), a2, voffA);
;             PG8_WAIT_V(8); PG8_WAIT_L(0); PG8_BAR; PG8_MMA(1, 0, At, B0); PG8_MMA(1, 1, At, B1); PG8_BAR; PG8_SCHED;
.LBB0_1142:
	s_add_u32 s17, s22, 0x100
	s_addc_u32 vcc_lo, s23, 0
	s_mov_b32 vcc_hi, -2
	s_add_u32 s22, s20, 0x100
	s_addc_u32 s23, s21, 0
	s_add_i32 s43, 0, 0x10000
	s_cmp_eq_u32 vcc_hi, 12
	s_cselect_b32 s75, s7, s23
	s_cselect_b32 s74, s6, s22
	s_cselect_b32 s73, s19, vcc_lo
	s_cselect_b32 s72, s18, s17
	s_add_i32 s44, 0, 0x14000
	v_add_u32_e32 v100, s43, v159
	v_add_u32_e32 v170, s44, v159
	ds_read_b128 v[64:67], v100
	ds_read_b128 v[68:71], v100 offset:1024
	ds_read_b128 v[72:75], v100 offset:2048
	ds_read_b128 v[100:103], v100 offset:3072
	ds_read_b128 v[154:157], v170
	ds_read_b128 v[162:165], v170 offset:1024
	ds_read_b128 v[166:169], v170 offset:2048
	ds_read_b128 v[170:173], v170 offset:3072
	v_lshl_add_u64 v[190:191], s[20:21], 0, v[150:151]
	s_add_i32 m0, s80, 0xc000
	ds_read_b128 v[174:177], v161
	ds_read_b128 v[178:181], v161 offset:1024
	ds_read_b128 v[182:185], v161 offset:2048
	ds_read_b128 v[186:189], v161 offset:3072
	ds_read_b128 v[194:197], v161 offset:4096
	ds_read_b128 v[198:201], v161 offset:5120
	ds_read_b128 v[204:207], v161 offset:6144
	ds_read_b128 v[208:211], v161 offset:7168
	global_load_lds_dwordx4 v[190:191], off
	v_lshl_add_u64 v[190:191], s[20:21], 0, v[152:153]
	s_add_i32 m0, s80, 0xe000
	s_nop 0
	global_load_lds_dwordx4 v[190:191], off
	s_waitcnt vmcnt(8)
	s_waitcnt lgkmcnt(0)
	s_barrier
	s_waitcnt lgkmcnt(0)
	v_mfma_f32_16x16x32_bf16 v[140:143], v[64:67], v[174:177], 0
	v_mfma_f32_16x16x32_bf16 v[136:139], v[72:75], v[174:177], 0
	v_mfma_f32_16x16x32_bf16 v[132:135], v[64:67], v[182:185], 0
	v_mfma_f32_16x16x32_bf16 v[120:123], v[72:75], v[182:185], 0
	v_mfma_f32_16x16x32_bf16 v[108:111], v[64:67], v[194:197], 0
	v_mfma_f32_16x16x32_bf16 v[104:107], v[72:75], v[194:197], 0
	v_mfma_f32_16x16x32_bf16 v[96:99], v[64:67], v[204:207], 0
	v_mfma_f32_16x16x32_bf16 v[84:87], v[72:75], v[204:207], 0
	v_mfma_f32_16x16x32_bf16 v[140:143], v[68:71], v[178:181], v[140:143]
	v_mfma_f32_16x16x32_bf16 v[136:139], v[100:103], v[178:181], v[136:139]
	v_mfma_f32_16x16x32_bf16 v[132:135], v[68:71], v[186:189], v[132:135]
	v_mfma_f32_16x16x32_bf16 v[120:123], v[100:103], v[186:189], v[120:123]
	v_mfma_f32_16x16x32_bf16 v[108:111], v[68:71], v[198:201], v[108:111]
	v_mfma_f32_16x16x32_bf16 v[104:107], v[100:103], v[198:201], v[104:107]
	v_mfma_f32_16x16x32_bf16 v[96:99], v[68:71], v[208:211], v[96:99]
	v_mfma_f32_16x16x32_bf16 v[84:87], v[100:103], v[208:211], v[84:87]
	v_mfma_f32_16x16x32_bf16 v[128:131], v[154:157], v[174:177], 0
	v_mfma_f32_16x16x32_bf16 v[124:127], v[166:169], v[174:177], 0
	v_mfma_f32_16x16x32_bf16 v[116:119], v[154:157], v[182:185], 0
	v_mfma_f32_16x16x32_bf16 v[112:115], v[166:169], v[182:185], 0
	v_mfma_f32_16x16x32_bf16 v[92:95], v[154:157], v[194:197], 0
	v_mfma_f32_16x16x32_bf16 v[88:91], v[166:169], v[194:197], 0
	v_mfma_f32_16x16x32_bf16 v[80:83], v[154:157], v[204:207], 0
	v_mfma_f32_16x16x32_bf16 v[76:79], v[166:169], v[204:207], 0
	v_mfma_f32_16x16x32_bf16 v[128:131], v[162:165], v[178:181], v[128:131]
	v_mfma_f32_16x16x32_bf16 v[124:127], v[170:173], v[178:181], v[124:127]
	v_mfma_f32_16x16x32_bf16 v[116:119], v[162:165], v[186:189], v[116:119]
	v_mfma_f32_16x16x32_bf16 v[112:115], v[170:173], v[186:189], v[112:115]
	v_mfma_f32_16x16x32_bf16 v[92:95], v[162:165], v[198:201], v[92:95]
	v_mfma_f32_16x16x32_bf16 v[88:91], v[170:173], v[198:201], v[88:91]
	v_mfma_f32_16x16x32_bf16 v[80:83], v[162:165], v[208:211], v[80:83]
	v_mfma_f32_16x16x32_bf16 v[76:79], v[170:173], v[208:211], v[76:79]
	s_barrier
	s_add_i32 s20, s43, s76
	v_lshl_add_u64 v[190:191], s[72:73], 0, v[192:193]
	s_mov_b32 m0, s20
	ds_read_b128 v[174:177], v161 offset:16384
	ds_read_b128 v[178:181], v161 offset:17408
	ds_read_b128 v[182:185], v161 offset:18432
	ds_read_b128 v[186:189], v161 offset:19456
	ds_read_b128 v[194:197], v161 offset:20480
	ds_read_b128 v[198:201], v161 offset:21504
	ds_read_b128 v[204:207], v161 offset:22528
	ds_read_b128 v[208:211], v161 offset:23552
	global_load_lds_dwordx4 v[190:191], off
	s_add_i32 m0, s20, 0x2000
	s_add_u32 s20, s72, 0x40000
	v_lshl_add_u64 v[212:213], s[72:73], 0, v[144:145]
	s_addc_u32 s21, s73, 0
	s_add_i32 s43, s44, s76
	global_load_lds_dwordx4 v[212:213], off
	v_lshl_add_u64 v[214:215], s[20:21], 0, v[192:193]
	s_mov_b32 m0, s43
	v_lshl_add_u64 v[216:217], s[74:75], 0, v[146:147]
	global_load_lds_dwordx4 v[214:215], off
	v_lshl_add_u64 v[214:215], s[20:21], 0, v[144:145]
	s_add_i32 m0, s43, 0x2000
	s_nop 0
	global_load_lds_dwordx4 v[214:215], off
	v_lshl_add_u64 v[214:215], s[74:75], 0, v[148:149]
	s_mov_b32 m0, s80
	s_nop 0
	global_load_lds_dwordx4 v[214:215], off
	s_mov_b32 m0, s81
	s_nop 0
	global_load_lds_dwordx4 v[216:217], off
	s_waitcnt vmcnt(8)
	s_waitcnt lgkmcnt(0)
	s_barrier
; #define PG8_STAGE(bufoff, gbase, voff) do { _Pragma("unroll") for (int _i = 0; _i < 2; ++_i) \
;         __builtin_amdgcn_global_load_lds((const unsigned*)((const char*)(gbase) + (voff)[_i]), (LAS unsigned*)(lds + (bufoff) + ldsw + _i * 8192), 16, 0, 0); } while (0)
; #define PG8_LDA(dst, b, h) do { _Pragma("unroll") for (int m = 0; m < 4; ++m) _Pragma("unroll") for (int k = 0; k < 2; ++k) dst[m][k] = *(const LAS bf16x8*)(lds + PG8_SA(b, h) + aoff + m * 2048 + k * 1024); } while (0)
; #define PG8_LDB(dst, b, h) do { _Pragma("unroll") for (int n = 0; n < 2; ++n) _Pragma("unroll") for (int k = 0; k < 2; ++k) dst[n][k] = *(const LAS bf16x8*)(lds + PG8_SB(b, h) + boff + n * 2048 + k * 1024); } while (0)
; #define PG8_MMA(ai, bj, At, Bt) do { __builtin_amdgcn_s_setprio(1); _Pragma("unroll") for (int m = 0; m < 4; ++m) _Pragma("unroll") for (int n = 0; n < 2; ++n) _Pragma("unroll") for (int k = 0; k < 2; ++k) \
;         acc[ai][bj][m][n] = __builtin_amdgcn_mfma_f32_16x16x32_bf16(Bt[n][k], At[m][k], acc[ai][bj][m][n], 0, 0, 0); __builtin_amdgcn_s_setprio(0); } while (0)
; #define PG8_WAIT_V(n) asm volatile("s_waitcnt vmcnt(" #n ")" ::: "memory")
; #define PG8_WAIT_L(n) asm volatile("s_waitcnt lgkmcnt(" #n ")" ::: "memory")
; #define PG8_BAR __builtin_amdgcn_s_barrier()
; #define PG8_SCHED __builtin_amdgcn_sched_barrier(0)
; template <class Epi>
; __device__ __forceinline__ void gemm_phase(LAS unsigned char* lds, const Gemm g, const Sched& S, const Epi& E, const int tid) {
;     ...
;             PG8_LDA(At, 0, 1); PG8_STAGE(PG8_SB(0, 0), b2, voffB); PG8_STAGE(PG8_SB(0, 1), b2 + hB, voffB); PG8_STAGE(PG8_SA(0, 0), a2, voffA);
;             PG8_WAIT_V(8); PG8_WAIT_L(0); PG8_BAR; PG8_MMA(1, 0, At, B0); PG8_MMA(1, 1, At, B1); PG8_BAR; PG8_SCHED;
;             PG8_LDB(B0, 1, 0); PG8_LDB(B1, 1, 1); PG8_SCHED; PG8_LDA(At, 1, 0); PG8_STAGE(PG8_SA(0, 1), a2 + hA, voffA);
;             PG8_WAIT_V(8); PG8_WAIT_L(0); PG8_BAR; PG8_MMA(0, 0, At, B0); PG8_MMA(0, 1, At, B1); PG8_BAR; PG8_SCHED;
	s_waitcnt lgkmcnt(0)
	v_mfma_f32_16x16x32_bf16 v[60:63], v[64:67], v[174:177], 0
	v_mfma_f32_16x16x32_bf16 v[56:59], v[72:75], v[174:177], 0
	v_mfma_f32_16x16x32_bf16 v[52:55], v[64:67], v[182:185], 0
	v_mfma_f32_16x16x32_bf16 v[40:43], v[72:75], v[182:185], 0
	v_mfma_f32_16x16x32_bf16 v[28:31], v[64:67], v[194:197], 0
	v_mfma_f32_16x16x32_bf16 v[24:27], v[72:75], v[194:197], 0
	v_mfma_f32_16x16x32_bf16 v[20:23], v[64:67], v[204:207], 0
	v_mfma_f32_16x16x32_bf16 v[8:11], v[72:75], v[204:207], 0
	v_mfma_f32_16x16x32_bf16 v[60:63], v[68:71], v[178:181], v[60:63]
	v_mfma_f32_16x16x32_bf16 v[56:59], v[100:103], v[178:181], v[56:59]
	v_mfma_f32_16x16x32_bf16 v[52:55], v[68:71], v[186:189], v[52:55]
	v_mfma_f32_16x16x32_bf16 v[40:43], v[100:103], v[186:189], v[40:43]
	v_mfma_f32_16x16x32_bf16 v[28:31], v[68:71], v[198:201], v[28:31]
	v_mfma_f32_16x16x32_bf16 v[24:27], v[100:103], v[198:201], v[24:27]
	v_mfma_f32_16x16x32_bf16 v[20:23], v[68:71], v[208:211], v[20:23]
	v_mfma_f32_16x16x32_bf16 v[8:11], v[100:103], v[208:211], v[8:11]
	v_mfma_f32_16x16x32_bf16 v[48:51], v[154:157], v[174:177], 0
	v_mfma_f32_16x16x32_bf16 v[44:47], v[166:169], v[174:177], 0
	v_mfma_f32_16x16x32_bf16 v[36:39], v[154:157], v[182:185], 0
	v_mfma_f32_16x16x32_bf16 v[32:35], v[166:169], v[182:185], 0
	v_mfma_f32_16x16x32_bf16 v[16:19], v[154:157], v[194:197], 0
	v_mfma_f32_16x16x32_bf16 v[12:15], v[166:169], v[194:197], 0
	v_mfma_f32_16x16x32_bf16 v[4:7], v[154:157], v[204:207], 0
	v_mfma_f32_16x16x32_bf16 v[0:3], v[166:169], v[204:207], 0
	v_mfma_f32_16x16x32_bf16 v[48:51], v[162:165], v[178:181], v[48:51]
	v_mfma_f32_16x16x32_bf16 v[44:47], v[170:173], v[178:181], v[44:47]
	v_mfma_f32_16x16x32_bf16 v[36:39], v[162:165], v[186:189], v[36:39]
	v_mfma_f32_16x16x32_bf16 v[32:35], v[170:173], v[186:189], v[32:35]
	v_mfma_f32_16x16x32_bf16 v[16:19], v[162:165], v[198:201], v[16:19]
	v_mfma_f32_16x16x32_bf16 v[12:15], v[170:173], v[198:201], v[12:15]
	v_mfma_f32_16x16x32_bf16 v[4:7], v[162:165], v[208:211], v[4:7]
	v_mfma_f32_16x16x32_bf16 v[0:3], v[170:173], v[208:211], v[0:3]
	s_barrier
	s_add_i32 s43, 0, 0x18000
	s_add_i32 s44, 0, 0x1c000
	v_add_u32_e32 v100, s43, v159
	v_add_u32_e32 v170, s44, v159
	ds_read_b128 v[64:67], v100
	ds_read_b128 v[68:71], v100 offset:1024
	ds_read_b128 v[72:75], v100 offset:2048
	ds_read_b128 v[100:103], v100 offset:3072
	ds_read_b128 v[154:157], v170
	ds_read_b128 v[162:165], v170 offset:1024
	ds_read_b128 v[166:169], v170 offset:2048
	ds_read_b128 v[170:173], v170 offset:3072
	s_add_u32 s20, s74, 0x120000
	s_addc_u32 s21, s75, 0
	s_mov_b32 m0, s3
	v_lshl_add_u64 v[218:219], s[20:21], 0, v[148:149]
	ds_read_b128 v[174:177], v161 offset:32768
	ds_read_b128 v[178:181], v161 offset:33792
	ds_read_b128 v[182:185], v161 offset:34816
	ds_read_b128 v[186:189], v161 offset:35840
	ds_read_b128 v[194:197], v161 offset:36864
	ds_read_b128 v[198:201], v161 offset:37888
	ds_read_b128 v[204:207], v161 offset:38912
	ds_read_b128 v[208:211], v161 offset:39936
	global_load_lds_dwordx4 v[218:219], off
	v_lshl_add_u64 v[218:219], s[20:21], 0, v[146:147]
	s_mov_b32 m0, s34
	s_nop 0
	global_load_lds_dwordx4 v[218:219], off
	s_waitcnt vmcnt(8)
	s_waitcnt lgkmcnt(0)
	s_barrier
	s_waitcnt lgkmcnt(0)
	v_mfma_f32_16x16x32_bf16 v[140:143], v[64:67], v[174:177], v[140:143]
	v_mfma_f32_16x16x32_bf16 v[136:139], v[72:75], v[174:177], v[136:139]
	v_mfma_f32_16x16x32_bf16 v[132:135], v[64:67], v[182:185], v[132:135]
	v_mfma_f32_16x16x32_bf16 v[120:123], v[72:75], v[182:185], v[120:123]
	v_mfma_f32_16x16x32_bf16 v[108:111], v[64:67], v[194:197], v[108:111]
	v_mfma_f32_16x16x32_bf16 v[104:107], v[72:75], v[194:197], v[104:107]
	v_mfma_f32_16x16x32_bf16 v[96:99], v[64:67], v[204:207], v[96:99]
	v_mfma_f32_16x16x32_bf16 v[84:87], v[72:75], v[204:207], v[84:87]
	v_mfma_f32_16x16x32_bf16 v[140:143], v[68:71], v[178:181], v[140:143]
	v_mfma_f32_16x16x32_bf16 v[136:139], v[100:103], v[178:181], v[136:139]
	v_mfma_f32_16x16x32_bf16 v[132:135], v[68:71], v[186:189], v[132:135]
	v_mfma_f32_16x16x32_bf16 v[120:123], v[100:103], v[186:189], v[120:123]
	v_mfma_f32_16x16x32_bf16 v[108:111], v[68:71], v[198:201], v[108:111]
	v_mfma_f32_16x16x32_bf16 v[104:107], v[100:103], v[198:201], v[104:107]
	v_mfma_f32_16x16x32_bf16 v[96:99], v[68:71], v[208:211], v[96:99]
	v_mfma_f32_16x16x32_bf16 v[84:87], v[100:103], v[208:211], v[84:87]
	v_mfma_f32_16x16x32_bf16 v[128:131], v[154:157], v[174:177], v[128:131]
	v_mfma_f32_16x16x32_bf16 v[124:127], v[166:169], v[174:177], v[124:127]
	v_mfma_f32_16x16x32_bf16 v[116:119], v[154:157], v[182:185], v[116:119]
	v_mfma_f32_16x16x32_bf16 v[112:115], v[166:169], v[182:185], v[112:115]
	v_mfma_f32_16x16x32_bf16 v[92:95], v[154:157], v[194:197], v[92:95]
	v_mfma_f32_16x16x32_bf16 v[88:91], v[166:169], v[194:197], v[88:91]
	v_mfma_f32_16x16x32_bf16 v[80:83], v[154:157], v[204:207], v[80:83]
	v_mfma_f32_16x16x32_bf16 v[76:79], v[166:169], v[204:207], v[76:79]
	v_mfma_f32_16x16x32_bf16 v[128:131], v[162:165], v[178:181], v[128:131]
	v_mfma_f32_16x16x32_bf16 v[124:127], v[170:173], v[178:181], v[124:127]
	v_mfma_f32_16x16x32_bf16 v[116:119], v[162:165], v[186:189], v[116:119]
	v_mfma_f32_16x16x32_bf16 v[112:115], v[170:173], v[186:189], v[112:115]
	v_mfma_f32_16x16x32_bf16 v[92:95], v[162:165], v[198:201], v[92:95]
	v_mfma_f32_16x16x32_bf16 v[88:91], v[170:173], v[198:201], v[88:91]
	v_mfma_f32_16x16x32_bf16 v[80:83], v[162:165], v[208:211], v[80:83]
	v_mfma_f32_16x16x32_bf16 v[76:79], v[170:173], v[208:211], v[76:79]
	s_barrier
; #define PG8_STAGE(bufoff, gbase, voff) do { _Pragma("unroll") for (int _i = 0; _i < 2; ++_i) \
;         __builtin_amdgcn_global_load_lds((const unsigned*)((const char*)(gbase) + (voff)[_i]), (LAS unsigned*)(lds + (bufoff) + ldsw + _i * 8192), 16, 0, 0); } while (0)
; #define PG8_LDA(dst, b, h) do { _Pragma("unroll") for (int m = 0; m < 4; ++m) _Pragma("unroll") for (int k = 0; k < 2; ++k) dst[m][k] = *(const LAS bf16x8*)(lds + PG8_SA(b, h) + aoff + m * 2048 + k * 1024); } while (0)
; #define PG8_LDB(dst, b, h) do { _Pragma("unroll") for (int n = 0; n < 2; ++n) _Pragma("unroll") for (int k = 0; k < 2; ++k) dst[n][k] = *(const LAS bf16x8*)(lds + PG8_SB(b, h) + boff + n * 2048 + k * 1024); } while (0)
; #define PG8_WAIT_V(n) asm volatile("s_waitcnt vmcnt(" #n ")" ::: "memory")
; #define PG8_WAIT_L(n) asm volatile("s_waitcnt lgkmcnt(" #n ")" ::: "memory")
; template <class Epi>
; __device__ __forceinline__ void gemm_phase(LAS unsigned char* lds, const Gemm g, const Sched& S, const Epi& E, const int tid) {
;     ...
;         for (int t = 0; t < nt; t += 2) {
;             const bool last = (t == nt - 2);
;             const char* a1 = cA + (size_t)(t + 1) * kstep;
;             const char* a2 = last ? nA : cA + (size_t)(t + 2) * kstep; const char* b2 = last ? nB : cB + (size_t)(t + 2) * kstep;
;             const char* a3 = a2 + kstep; const char* b3 = b2 + kstep;
;             PG8_LDB(B0, 0, 0); PG8_LDB(B1, 0, 1); PG8_SCHED; PG8_LDA(At, 0, 0); PG8_STAGE(PG8_SA(1, 1), a1 + hA, voffA);
;             PG8_WAIT_V(8); PG8_WAIT_L(0); PG8_BAR; PG8_MMA(0, 0, At, B0); PG8_MMA(0, 1, At, B1); PG8_BAR; PG8_SCHED;
;             PG8_LDA(At, 0, 1); PG8_STAGE(PG8_SB(0, 0), b2, voffB); PG8_STAGE(PG8_SB(0, 1), b2 + hB, voffB); PG8_STAGE(PG8_SA(0, 0), a2, voffA);
;             PG8_WAIT_V(8); PG8_WAIT_L(0); PG8_BAR; PG8_MMA(1, 0, At, B0); PG8_MMA(1, 1, At, B1); PG8_BAR; PG8_SCHED;
;             PG8_LDB(B0, 1, 0); PG8_LDB(B1, 1, 1); PG8_SCHED; PG8_LDA(At, 1, 0); PG8_STAGE(PG8_SA(0, 1), a2 + hA, voffA);
;             PG8_WAIT_V(8); PG8_WAIT_L(0); PG8_BAR; PG8_MMA(0, 0, At, B0); PG8_MMA(0, 1, At, B1); PG8_BAR; PG8_SCHED;
;             PG8_LDA(At, 1, 1); PG8_STAGE(PG8_SB(1, 0), b3, voffB); PG8_STAGE(PG8_SB(1, 1), b3 + hB, voffB); PG8_STAGE(PG8_SA(1, 0), a3, voffA);
;             PG8_WAIT_V(8); PG8_WAIT_L(0); PG8_BAR; PG8_MMA(1, 0, At, B0); PG8_MMA(1, 1, At, B1); PG8_BAR; PG8_SCHED;
	s_add_i32 s20, s43, s76
	v_lshl_add_u64 v[190:191], v[190:191], 0, s[94:95]
	s_mov_b32 m0, s20
	ds_read_b128 v[174:177], v161 offset:49152
	ds_read_b128 v[178:181], v161 offset:50176
	ds_read_b128 v[182:185], v161 offset:51200
	ds_read_b128 v[186:189], v161 offset:52224
	ds_read_b128 v[194:197], v161 offset:53248
	ds_read_b128 v[198:201], v161 offset:54272
	ds_read_b128 v[204:207], v161 offset:55296
	ds_read_b128 v[208:211], v161 offset:56320
	global_load_lds_dwordx4 v[190:191], off
	s_add_i32 m0, s20, 0x2000
	s_add_u32 s20, s72, 0x40080
	v_lshl_add_u64 v[190:191], v[212:213], 0, s[94:95]
	s_addc_u32 s21, s73, 0
	s_add_i32 s43, s44, s76
	global_load_lds_dwordx4 v[190:191], off
	v_lshl_add_u64 v[190:191], s[20:21], 0, v[192:193]
	s_mov_b32 m0, s43
	s_nop 0
	global_load_lds_dwordx4 v[190:191], off
	v_lshl_add_u64 v[190:191], s[20:21], 0, v[144:145]
	s_add_i32 m0, s43, 0x2000
	s_nop 0
	global_load_lds_dwordx4 v[190:191], off
	v_lshl_add_u64 v[190:191], v[214:215], 0, s[94:95]
	s_mov_b32 m0, s47
	s_nop 0
	global_load_lds_dwordx4 v[190:191], off
	v_lshl_add_u64 v[190:191], v[216:217], 0, s[94:95]
	s_mov_b32 m0, s40
	s_nop 0
	global_load_lds_dwordx4 v[190:191], off
	s_waitcnt vmcnt(8)
	s_waitcnt lgkmcnt(0)
	s_barrier
	s_waitcnt lgkmcnt(0)
	v_mfma_f32_16x16x32_bf16 v[60:63], v[64:67], v[174:177], v[60:63]
	v_mfma_f32_16x16x32_bf16 v[56:59], v[72:75], v[174:177], v[56:59]
	v_mfma_f32_16x16x32_bf16 v[52:55], v[64:67], v[182:185], v[52:55]
	v_mfma_f32_16x16x32_bf16 v[40:43], v[72:75], v[182:185], v[40:43]
	v_mfma_f32_16x16x32_bf16 v[28:31], v[64:67], v[194:197], v[28:31]
	v_mfma_f32_16x16x32_bf16 v[24:27], v[72:75], v[194:197], v[24:27]
	v_mfma_f32_16x16x32_bf16 v[20:23], v[64:67], v[204:207], v[20:23]
	v_mfma_f32_16x16x32_bf16 v[8:11], v[72:75], v[204:207], v[8:11]
	v_mfma_f32_16x16x32_bf16 v[60:63], v[68:71], v[178:181], v[60:63]
	v_mfma_f32_16x16x32_bf16 v[56:59], v[100:103], v[178:181], v[56:59]
	v_mfma_f32_16x16x32_bf16 v[52:55], v[68:71], v[186:189], v[52:55]
	v_mfma_f32_16x16x32_bf16 v[40:43], v[100:103], v[186:189], v[40:43]
	v_mfma_f32_16x16x32_bf16 v[28:31], v[68:71], v[198:201], v[28:31]
	v_mfma_f32_16x16x32_bf16 v[24:27], v[100:103], v[198:201], v[24:27]
	v_mfma_f32_16x16x32_bf16 v[20:23], v[68:71], v[208:211], v[20:23]
	v_mfma_f32_16x16x32_bf16 v[8:11], v[100:103], v[208:211], v[8:11]
	v_mfma_f32_16x16x32_bf16 v[48:51], v[154:157], v[174:177], v[48:51]
	v_mfma_f32_16x16x32_bf16 v[44:47], v[166:169], v[174:177], v[44:47]
	v_mfma_f32_16x16x32_bf16 v[36:39], v[154:157], v[182:185], v[36:39]
	v_mfma_f32_16x16x32_bf16 v[32:35], v[166:169], v[182:185], v[32:35]
	v_mfma_f32_16x16x32_bf16 v[16:19], v[154:157], v[194:197], v[16:19]
	v_mfma_f32_16x16x32_bf16 v[12:15], v[166:169], v[194:197], v[12:15]
	v_mfma_f32_16x16x32_bf16 v[4:7], v[154:157], v[204:207], v[4:7]
	v_mfma_f32_16x16x32_bf16 v[0:3], v[166:169], v[204:207], v[0:3]
	v_mfma_f32_16x16x32_bf16 v[48:51], v[162:165], v[178:181], v[48:51]
	v_mfma_f32_16x16x32_bf16 v[44:47], v[170:173], v[178:181], v[44:47]
	v_mfma_f32_16x16x32_bf16 v[36:39], v[162:165], v[186:189], v[36:39]
	v_mfma_f32_16x16x32_bf16 v[32:35], v[170:173], v[186:189], v[32:35]
	v_mfma_f32_16x16x32_bf16 v[16:19], v[162:165], v[198:201], v[16:19]
	v_mfma_f32_16x16x32_bf16 v[12:15], v[170:173], v[198:201], v[12:15]
	v_mfma_f32_16x16x32_bf16 v[4:7], v[162:165], v[208:211], v[4:7]
	v_mfma_f32_16x16x32_bf16 v[0:3], v[170:173], v[208:211], v[0:3]
	s_barrier
	s_add_i32 vcc_hi, vcc_hi, 2
	s_add_u32 s17, s17, 0x100
	s_addc_u32 vcc_lo, vcc_lo, 0
	s_cmp_gt_u32 vcc_hi, 13
	s_mov_b64 s[20:21], s[22:23]
	s_cbranch_scc1 .Lgk_exit_3
.LBB0_1143:
	s_add_u32 s22, s20, 0x100
	s_addc_u32 s23, s21, 0
	s_add_i32 s43, 0, 0x10000
	s_cmp_eq_u32 vcc_hi, 12
	s_cselect_b32 s75, s7, s23
	s_cselect_b32 s74, s6, s22
	s_cselect_b32 s73, s19, vcc_lo
	s_cselect_b32 s72, s18, s17
	s_add_i32 s44, 0, 0x14000
	v_add_u32_e32 v100, s43, v159
	v_add_u32_e32 v170, s44, v159
	ds_read_b128 v[64:67], v100
	ds_read_b128 v[68:71], v100 offset:1024
	ds_read_b128 v[72:75], v100 offset:2048
	ds_read_b128 v[100:103], v100 offset:3072
	ds_read_b128 v[154:157], v170
	ds_read_b128 v[162:165], v170 offset:1024
	ds_read_b128 v[166:169], v170 offset:2048
	ds_read_b128 v[170:173], v170 offset:3072
	v_lshl_add_u64 v[190:191], s[20:21], 0, v[150:151]
	s_add_i32 m0, s80, 0xc000
	ds_read_b128 v[174:177], v161
	ds_read_b128 v[178:181], v161 offset:1024
	ds_read_b128 v[182:185], v161 offset:2048
	ds_read_b128 v[186:189], v161 offset:3072
	ds_read_b128 v[194:197], v161 offset:4096
	ds_read_b128 v[198:201], v161 offset:5120
	ds_read_b128 v[204:207], v161 offset:6144
	ds_read_b128 v[208:211], v161 offset:7168
	global_load_lds_dwordx4 v[190:191], off
	v_lshl_add_u64 v[190:191], s[20:21], 0, v[152:153]
	s_add_i32 m0, s80, 0xe000
	s_nop 0
	global_load_lds_dwordx4 v[190:191], off
	s_waitcnt vmcnt(8)
	s_waitcnt lgkmcnt(0)
	s_barrier
; #define PG8_STAGE(bufoff, gbase, voff) do { _Pragma("unroll") for (int _i = 0; _i < 2; ++_i) \
;         __builtin_amdgcn_global_load_lds((const unsigned*)((const char*)(gbase) + (voff)[_i]), (LAS unsigned*)(lds + (bufoff) + ldsw + _i * 8192), 16, 0, 0); } while (0)
; #define PG8_LDA(dst, b, h) do { _Pragma("unroll") for (int m = 0; m < 4; ++m) _Pragma("unroll") for (int k = 0; k < 2; ++k) dst[m][k] = *(const LAS bf16x8*)(lds + PG8_SA(b, h) + aoff + m * 2048 + k * 1024); } while (0)
; #define PG8_LDB(dst, b, h) do { _Pragma("unroll") for (int n = 0; n < 2; ++n) _Pragma("unroll") for (int k = 0; k < 2; ++k) dst[n][k] = *(const LAS bf16x8*)(lds + PG8_SB(b, h) + boff + n * 2048 + k * 1024); } while (0)
; #define PG8_MMA(ai, bj, At, Bt) do { __builtin_amdgcn_s_setprio(1); _Pragma("unroll") for (int m = 0; m < 4; ++m) _Pragma("unroll") for (int n = 0; n < 2; ++n) _Pragma("unroll") for (int k = 0; k < 2; ++k) \
;         acc[ai][bj][m][n] = __builtin_amdgcn_mfma_f32_16x16x32_bf16(Bt[n][k], At[m][k], acc[ai][bj][m][n], 0, 0, 0); __builtin_amdgcn_s_setprio(0); } while (0)
; #define PG8_WAIT_V(n) asm volatile("s_waitcnt vmcnt(" #n ")" ::: "memory")
; #define PG8_WAIT_L(n) asm volatile("s_waitcnt lgkmcnt(" #n ")" ::: "memory")
; #define PG8_BAR __builtin_amdgcn_s_barrier()
; #define PG8_SCHED __builtin_amdgcn_sched_barrier(0)
; template <class Epi>
; __device__ __forceinline__ void gemm_phase(LAS unsigned char* lds, const Gemm g, const Sched& S, const Epi& E, const int tid) {
;     ...
;             PG8_LDB(B0, 0, 0); PG8_LDB(B1, 0, 1); PG8_SCHED; PG8_LDA(At, 0, 0); PG8_STAGE(PG8_SA(1, 1), a1 + hA, voffA);
;             PG8_WAIT_V(8); PG8_WAIT_L(0); PG8_BAR; PG8_MMA(0, 0, At, B0); PG8_MMA(0, 1, At, B1); PG8_BAR; PG8_SCHED;
;             PG8_LDA(At, 0, 1); PG8_STAGE(PG8_SB(0, 0), b2, voffB); PG8_STAGE(PG8_SB(0, 1), b2 + hB, voffB); PG8_STAGE(PG8_SA(0, 0), a2, voffA);
;             PG8_WAIT_V(8); PG8_WAIT_L(0); PG8_BAR; PG8_MMA(1, 0, At, B0); PG8_MMA(1, 1, At, B1); PG8_BAR; PG8_SCHED;
	s_waitcnt lgkmcnt(0)
	v_mfma_f32_16x16x32_bf16 v[140:143], v[64:67], v[174:177], v[140:143]
	v_mfma_f32_16x16x32_bf16 v[136:139], v[72:75], v[174:177], v[136:139]
	v_mfma_f32_16x16x32_bf16 v[132:135], v[64:67], v[182:185], v[132:135]
	v_mfma_f32_16x16x32_bf16 v[120:123], v[72:75], v[182:185], v[120:123]
	v_mfma_f32_16x16x32_bf16 v[108:111], v[64:67], v[194:197], v[108:111]
	v_mfma_f32_16x16x32_bf16 v[104:107], v[72:75], v[194:197], v[104:107]
	v_mfma_f32_16x16x32_bf16 v[96:99], v[64:67], v[204:207], v[96:99]
	v_mfma_f32_16x16x32_bf16 v[84:87], v[72:75], v[204:207], v[84:87]
	v_mfma_f32_16x16x32_bf16 v[140:143], v[68:71], v[178:181], v[140:143]
	v_mfma_f32_16x16x32_bf16 v[136:139], v[100:103], v[178:181], v[136:139]
	v_mfma_f32_16x16x32_bf16 v[132:135], v[68:71], v[186:189], v[132:135]
	v_mfma_f32_16x16x32_bf16 v[120:123], v[100:103], v[186:189], v[120:123]
	v_mfma_f32_16x16x32_bf16 v[108:111], v[68:71], v[198:201], v[108:111]
	v_mfma_f32_16x16x32_bf16 v[104:107], v[100:103], v[198:201], v[104:107]
	v_mfma_f32_16x16x32_bf16 v[96:99], v[68:71], v[208:211], v[96:99]
	v_mfma_f32_16x16x32_bf16 v[84:87], v[100:103], v[208:211], v[84:87]
	v_mfma_f32_16x16x32_bf16 v[128:131], v[154:157], v[174:177], v[128:131]
	v_mfma_f32_16x16x32_bf16 v[124:127], v[166:169], v[174:177], v[124:127]
	v_mfma_f32_16x16x32_bf16 v[116:119], v[154:157], v[182:185], v[116:119]
	v_mfma_f32_16x16x32_bf16 v[112:115], v[166:169], v[182:185], v[112:115]
	v_mfma_f32_16x16x32_bf16 v[92:95], v[154:157], v[194:197], v[92:95]
	v_mfma_f32_16x16x32_bf16 v[88:91], v[166:169], v[194:197], v[88:91]
	v_mfma_f32_16x16x32_bf16 v[80:83], v[154:157], v[204:207], v[80:83]
	v_mfma_f32_16x16x32_bf16 v[76:79], v[166:169], v[204:207], v[76:79]
	v_mfma_f32_16x16x32_bf16 v[128:131], v[162:165], v[178:181], v[128:131]
	v_mfma_f32_16x16x32_bf16 v[124:127], v[170:173], v[178:181], v[124:127]
	v_mfma_f32_16x16x32_bf16 v[116:119], v[162:165], v[186:189], v[116:119]
	v_mfma_f32_16x16x32_bf16 v[112:115], v[170:173], v[186:189], v[112:115]
	v_mfma_f32_16x16x32_bf16 v[92:95], v[162:165], v[198:201], v[92:95]
	v_mfma_f32_16x16x32_bf16 v[88:91], v[170:173], v[198:201], v[88:91]
	v_mfma_f32_16x16x32_bf16 v[80:83], v[162:165], v[208:211], v[80:83]
	v_mfma_f32_16x16x32_bf16 v[76:79], v[170:173], v[208:211], v[76:79]
	s_barrier
	s_add_i32 s20, s43, s76
	v_lshl_add_u64 v[190:191], s[72:73], 0, v[192:193]
	s_mov_b32 m0, s20
	ds_read_b128 v[174:177], v161 offset:16384
	ds_read_b128 v[178:181], v161 offset:17408
	ds_read_b128 v[182:185], v161 offset:18432
	ds_read_b128 v[186:189], v161 offset:19456
	ds_read_b128 v[194:197], v161 offset:20480
	ds_read_b128 v[198:201], v161 offset:21504
	ds_read_b128 v[204:207], v161 offset:22528
	ds_read_b128 v[208:211], v161 offset:23552
	global_load_lds_dwordx4 v[190:191], off
	s_add_i32 m0, s20, 0x2000
	s_add_u32 s20, s72, 0x40000
	v_lshl_add_u64 v[212:213], s[72:73], 0, v[144:145]
	s_addc_u32 s21, s73, 0
	s_add_i32 s43, s44, s76
	global_load_lds_dwordx4 v[212:213], off
	v_lshl_add_u64 v[214:215], s[20:21], 0, v[192:193]
	s_mov_b32 m0, s43
	v_lshl_add_u64 v[216:217], s[74:75], 0, v[146:147]
	global_load_lds_dwordx4 v[214:215], off
	v_lshl_add_u64 v[214:215], s[20:21], 0, v[144:145]
	s_add_i32 m0, s43, 0x2000
	s_nop 0
	global_load_lds_dwordx4 v[214:215], off
	v_lshl_add_u64 v[214:215], s[74:75], 0, v[148:149]
	s_mov_b32 m0, s80
	s_nop 0
	global_load_lds_dwordx4 v[214:215], off
	s_mov_b32 m0, s81
	s_nop 0
	global_load_lds_dwordx4 v[216:217], off
	s_waitcnt vmcnt(8)
	s_waitcnt lgkmcnt(0)
	s_barrier
	s_waitcnt lgkmcnt(0)
	v_mfma_f32_16x16x32_bf16 v[60:63], v[64:67], v[174:177], v[60:63]
	v_mfma_f32_16x16x32_bf16 v[56:59], v[72:75], v[174:177], v[56:59]
	v_mfma_f32_16x16x32_bf16 v[52:55], v[64:67], v[182:185], v[52:55]
	v_mfma_f32_16x16x32_bf16 v[40:43], v[72:75], v[182:185], v[40:43]
	v_mfma_f32_16x16x32_bf16 v[28:31], v[64:67], v[194:197], v[28:31]
	v_mfma_f32_16x16x32_bf16 v[24:27], v[72:75], v[194:197], v[24:27]
	v_mfma_f32_16x16x32_bf16 v[20:23], v[64:67], v[204:207], v[20:23]
	v_mfma_f32_16x16x32_bf16 v[8:11], v[72:75], v[204:207], v[8:11]
	v_mfma_f32_16x16x32_bf16 v[60:63], v[68:71], v[178:181], v[60:63]
	v_mfma_f32_16x16x32_bf16 v[56:59], v[100:103], v[178:181], v[56:59]
	v_mfma_f32_16x16x32_bf16 v[52:55], v[68:71], v[186:189], v[52:55]
	v_mfma_f32_16x16x32_bf16 v[40:43], v[100:103], v[186:189], v[40:43]
	v_mfma_f32_16x16x32_bf16 v[28:31], v[68:71], v[198:201], v[28:31]
	v_mfma_f32_16x16x32_bf16 v[24:27], v[100:103], v[198:201], v[24:27]
	v_mfma_f32_16x16x32_bf16 v[20:23], v[68:71], v[208:211], v[20:23]
	v_mfma_f32_16x16x32_bf16 v[8:11], v[100:103], v[208:211], v[8:11]
	v_mfma_f32_16x16x32_bf16 v[48:51], v[154:157], v[174:177], v[48:51]
	v_mfma_f32_16x16x32_bf16 v[44:47], v[166:169], v[174:177], v[44:47]
	v_mfma_f32_16x16x32_bf16 v[36:39], v[154:157], v[182:185], v[36:39]
	v_mfma_f32_16x16x32_bf16 v[32:35], v[166:169], v[182:185], v[32:35]
	v_mfma_f32_16x16x32_bf16 v[16:19], v[154:157], v[194:197], v[16:19]
	v_mfma_f32_16x16x32_bf16 v[12:15], v[166:169], v[194:197], v[12:15]
	v_mfma_f32_16x16x32_bf16 v[4:7], v[154:157], v[204:207], v[4:7]
	v_mfma_f32_16x16x32_bf16 v[0:3], v[166:169], v[204:207], v[0:3]
	v_mfma_f32_16x16x32_bf16 v[48:51], v[162:165], v[178:181], v[48:51]
	v_mfma_f32_16x16x32_bf16 v[44:47], v[170:173], v[178:181], v[44:47]
	v_mfma_f32_16x16x32_bf16 v[36:39], v[162:165], v[186:189], v[36:39]
	v_mfma_f32_16x16x32_bf16 v[32:35], v[170:173], v[186:189], v[32:35]
	v_mfma_f32_16x16x32_bf16 v[16:19], v[162:165], v[198:201], v[16:19]
	v_mfma_f32_16x16x32_bf16 v[12:15], v[170:173], v[198:201], v[12:15]
	v_mfma_f32_16x16x32_bf16 v[4:7], v[162:165], v[208:211], v[4:7]
	v_mfma_f32_16x16x32_bf16 v[0:3], v[170:173], v[208:211], v[0:3]
	s_barrier
; #define PG8_STAGE(bufoff, gbase, voff) do { _Pragma("unroll") for (int _i = 0; _i < 2; ++_i) \
;         __builtin_amdgcn_global_load_lds((const unsigned*)((const char*)(gbase) + (voff)[_i]), (LAS unsigned*)(lds + (bufoff) + ldsw + _i * 8192), 16, 0, 0); } while (0)
; #define PG8_LDA(dst, b, h) do { _Pragma("unroll") for (int m = 0; m < 4; ++m) _Pragma("unroll") for (int k = 0; k < 2; ++k) dst[m][k] = *(const LAS bf16x8*)(lds + PG8_SA(b, h) + aoff + m * 2048 + k * 1024); } while (0)
; #define PG8_LDB(dst, b, h) do { _Pragma("unroll") for (int n = 0; n < 2; ++n) _Pragma("unroll") for (int k = 0; k < 2; ++k) dst[n][k] = *(const LAS bf16x8*)(lds + PG8_SB(b, h) + boff + n * 2048 + k * 1024); } while (0)
; #define PG8_MMA(ai, bj, At, Bt) do { __builtin_amdgcn_s_setprio(1); _Pragma("unroll") for (int m = 0; m < 4; ++m) _Pragma("unroll") for (int n = 0; n < 2; ++n) _Pragma("unroll") for (int k = 0; k < 2; ++k) \
;         acc[ai][bj][m][n] = __builtin_amdgcn_mfma_f32_16x16x32_bf16(Bt[n][k], At[m][k], acc[ai][bj][m][n], 0, 0, 0); __builtin_amdgcn_s_setprio(0); } while (0)
; #define PG8_WAIT_V(n) asm volatile("s_waitcnt vmcnt(" #n ")" ::: "memory")
; #define PG8_WAIT_L(n) asm volatile("s_waitcnt lgkmcnt(" #n ")" ::: "memory")
; #define PG8_BAR __builtin_amdgcn_s_barrier()
; #define PG8_SCHED __builtin_amdgcn_sched_barrier(0)
; template <class Epi>
; __device__ __forceinline__ void gemm_phase(LAS unsigned char* lds, const Gemm g, const Sched& S, const Epi& E, const int tid) {
;     ...
;             PG8_LDB(B0, 1, 0); PG8_LDB(B1, 1, 1); PG8_SCHED; PG8_LDA(At, 1, 0); PG8_STAGE(PG8_SA(0, 1), a2 + hA, voffA);
;             PG8_WAIT_V(8); PG8_WAIT_L(0); PG8_BAR; PG8_MMA(0, 0, At, B0); PG8_MMA(0, 1, At, B1); PG8_BAR; PG8_SCHED;
;             PG8_LDA(At, 1, 1); PG8_STAGE(PG8_SB(1, 0), b3, voffB); PG8_STAGE(PG8_SB(1, 1), b3 + hB, voffB); PG8_STAGE(PG8_SA(1, 0), a3, voffA);
;             PG8_WAIT_V(8); PG8_WAIT_L(0); PG8_BAR; PG8_MMA(1, 0, At, B0); PG8_MMA(1, 1, At, B1); PG8_BAR; PG8_SCHED;
	s_add_i32 s43, 0, 0x18000
	s_add_i32 s44, 0, 0x1c000
	v_add_u32_e32 v100, s43, v159
	v_add_u32_e32 v170, s44, v159
	ds_read_b128 v[64:67], v100
	ds_read_b128 v[68:71], v100 offset:1024
	ds_read_b128 v[72:75], v100 offset:2048
	ds_read_b128 v[100:103], v100 offset:3072
	ds_read_b128 v[154:157], v170
	ds_read_b128 v[162:165], v170 offset:1024
	ds_read_b128 v[166:169], v170 offset:2048
	ds_read_b128 v[170:173], v170 offset:3072
	s_add_u32 s20, s74, 0x120000
	s_addc_u32 s21, s75, 0
	s_mov_b32 m0, s3
	v_lshl_add_u64 v[218:219], s[20:21], 0, v[148:149]
	ds_read_b128 v[174:177], v161 offset:32768
	ds_read_b128 v[178:181], v161 offset:33792
	ds_read_b128 v[182:185], v161 offset:34816
	ds_read_b128 v[186:189], v161 offset:35840
	ds_read_b128 v[194:197], v161 offset:36864
	ds_read_b128 v[198:201], v161 offset:37888
	ds_read_b128 v[204:207], v161 offset:38912
	ds_read_b128 v[208:211], v161 offset:39936
	global_load_lds_dwordx4 v[218:219], off
	v_lshl_add_u64 v[218:219], s[20:21], 0, v[146:147]
	s_mov_b32 m0, s34
	s_nop 0
	global_load_lds_dwordx4 v[218:219], off
	s_waitcnt vmcnt(8)
	s_waitcnt lgkmcnt(0)
	s_barrier
	s_waitcnt lgkmcnt(0)
	v_mfma_f32_16x16x32_bf16 v[140:143], v[64:67], v[174:177], v[140:143]
	v_mfma_f32_16x16x32_bf16 v[136:139], v[72:75], v[174:177], v[136:139]
	v_mfma_f32_16x16x32_bf16 v[132:135], v[64:67], v[182:185], v[132:135]
	v_mfma_f32_16x16x32_bf16 v[120:123], v[72:75], v[182:185], v[120:123]
	v_mfma_f32_16x16x32_bf16 v[108:111], v[64:67], v[194:197], v[108:111]
	v_mfma_f32_16x16x32_bf16 v[104:107], v[72:75], v[194:197], v[104:107]
	v_mfma_f32_16x16x32_bf16 v[96:99], v[64:67], v[204:207], v[96:99]
	v_mfma_f32_16x16x32_bf16 v[84:87], v[72:75], v[204:207], v[84:87]
	v_mfma_f32_16x16x32_bf16 v[140:143], v[68:71], v[178:181], v[140:143]
	v_mfma_f32_16x16x32_bf16 v[136:139], v[100:103], v[178:181], v[136:139]
	v_mfma_f32_16x16x32_bf16 v[132:135], v[68:71], v[186:189], v[132:135]
	v_mfma_f32_16x16x32_bf16 v[120:123], v[100:103], v[186:189], v[120:123]
	v_mfma_f32_16x16x32_bf16 v[108:111], v[68:71], v[198:201], v[108:111]
	v_mfma_f32_16x16x32_bf16 v[104:107], v[100:103], v[198:201], v[104:107]
	v_mfma_f32_16x16x32_bf16 v[96:99], v[68:71], v[208:211], v[96:99]
	v_mfma_f32_16x16x32_bf16 v[84:87], v[100:103], v[208:211], v[84:87]
	v_mfma_f32_16x16x32_bf16 v[128:131], v[154:157], v[174:177], v[128:131]
	v_mfma_f32_16x16x32_bf16 v[124:127], v[166:169], v[174:177], v[124:127]
	v_mfma_f32_16x16x32_bf16 v[116:119], v[154:157], v[182:185], v[116:119]
	v_mfma_f32_16x16x32_bf16 v[112:115], v[166:169], v[182:185], v[112:115]
	v_mfma_f32_16x16x32_bf16 v[92:95], v[154:157], v[194:197], v[92:95]
	v_mfma_f32_16x16x32_bf16 v[88:91], v[166:169], v[194:197], v[88:91]
	v_mfma_f32_16x16x32_bf16 v[80:83], v[154:157], v[204:207], v[80:83]
	v_mfma_f32_16x16x32_bf16 v[76:79], v[166:169], v[204:207], v[76:79]
	v_mfma_f32_16x16x32_bf16 v[128:131], v[162:165], v[178:181], v[128:131]
	v_mfma_f32_16x16x32_bf16 v[124:127], v[170:173], v[178:181], v[124:127]
	v_mfma_f32_16x16x32_bf16 v[116:119], v[162:165], v[186:189], v[116:119]
	v_mfma_f32_16x16x32_bf16 v[112:115], v[170:173], v[186:189], v[112:115]
	v_mfma_f32_16x16x32_bf16 v[92:95], v[162:165], v[198:201], v[92:95]
	v_mfma_f32_16x16x32_bf16 v[88:91], v[170:173], v[198:201], v[88:91]
	v_mfma_f32_16x16x32_bf16 v[80:83], v[162:165], v[208:211], v[80:83]
	v_mfma_f32_16x16x32_bf16 v[76:79], v[170:173], v[208:211], v[76:79]
	s_barrier
	s_add_i32 s20, s43, s76
	v_lshl_add_u64 v[190:191], v[190:191], 0, s[94:95]
	s_mov_b32 m0, s20
	ds_read_b128 v[174:177], v161 offset:49152
	ds_read_b128 v[178:181], v161 offset:50176
	ds_read_b128 v[182:185], v161 offset:51200
	ds_read_b128 v[186:189], v161 offset:52224
	ds_read_b128 v[194:197], v161 offset:53248
	ds_read_b128 v[198:201], v161 offset:54272
	ds_read_b128 v[204:207], v161 offset:55296
	ds_read_b128 v[208:211], v161 offset:56320
	global_load_lds_dwordx4 v[190:191], off
	s_add_i32 m0, s20, 0x2000
	s_add_u32 s20, s72, 0x40080
	v_lshl_add_u64 v[190:191], v[212:213], 0, s[94:95]
	s_addc_u32 s21, s73, 0
	s_add_i32 s43, s44, s76
	global_load_lds_dwordx4 v[190:191], off
	v_lshl_add_u64 v[190:191], s[20:21], 0, v[192:193]
	s_mov_b32 m0, s43
	s_nop 0
	global_load_lds_dwordx4 v[190:191], off
	v_lshl_add_u64 v[190:191], s[20:21], 0, v[144:145]
	s_add_i32 m0, s43, 0x2000
	s_nop 0
	global_load_lds_dwordx4 v[190:191], off
	v_lshl_add_u64 v[190:191], v[214:215], 0, s[94:95]
	s_mov_b32 m0, s47
	s_nop 0
	global_load_lds_dwordx4 v[190:191], off
	v_lshl_add_u64 v[190:191], v[216:217], 0, s[94:95]
	s_mov_b32 m0, s40
	s_nop 0
	global_load_lds_dwordx4 v[190:191], off
	s_waitcnt vmcnt(8)
	s_waitcnt lgkmcnt(0)
	s_barrier
	s_waitcnt lgkmcnt(0)
	v_mfma_f32_16x16x32_bf16 v[60:63], v[64:67], v[174:177], v[60:63]
	v_mfma_f32_16x16x32_bf16 v[56:59], v[72:75], v[174:177], v[56:59]
	v_mfma_f32_16x16x32_bf16 v[52:55], v[64:67], v[182:185], v[52:55]
	v_mfma_f32_16x16x32_bf16 v[40:43], v[72:75], v[182:185], v[40:43]
	v_mfma_f32_16x16x32_bf16 v[28:31], v[64:67], v[194:197], v[28:31]
	v_mfma_f32_16x16x32_bf16 v[24:27], v[72:75], v[194:197], v[24:27]
	v_mfma_f32_16x16x32_bf16 v[20:23], v[64:67], v[204:207], v[20:23]
	v_mfma_f32_16x16x32_bf16 v[8:11], v[72:75], v[204:207], v[8:11]
	v_mfma_f32_16x16x32_bf16 v[60:63], v[68:71], v[178:181], v[60:63]
	v_mfma_f32_16x16x32_bf16 v[56:59], v[100:103], v[178:181], v[56:59]
	v_mfma_f32_16x16x32_bf16 v[52:55], v[68:71], v[186:189], v[52:55]
	v_mfma_f32_16x16x32_bf16 v[40:43], v[100:103], v[186:189], v[40:43]
	v_mfma_f32_16x16x32_bf16 v[28:31], v[68:71], v[198:201], v[28:31]
	v_mfma_f32_16x16x32_bf16 v[24:27], v[100:103], v[198:201], v[24:27]
	v_mfma_f32_16x16x32_bf16 v[20:23], v[68:71], v[208:211], v[20:23]
	v_mfma_f32_16x16x32_bf16 v[8:11], v[100:103], v[208:211], v[8:11]
	v_mfma_f32_16x16x32_bf16 v[48:51], v[154:157], v[174:177], v[48:51]
	v_mfma_f32_16x16x32_bf16 v[44:47], v[166:169], v[174:177], v[44:47]
	v_mfma_f32_16x16x32_bf16 v[36:39], v[154:157], v[182:185], v[36:39]
	v_mfma_f32_16x16x32_bf16 v[32:35], v[166:169], v[182:185], v[32:35]
	v_mfma_f32_16x16x32_bf16 v[16:19], v[154:157], v[194:197], v[16:19]
	v_mfma_f32_16x16x32_bf16 v[12:15], v[166:169], v[194:197], v[12:15]
	v_mfma_f32_16x16x32_bf16 v[4:7], v[154:157], v[204:207], v[4:7]
	v_mfma_f32_16x16x32_bf16 v[0:3], v[166:169], v[204:207], v[0:3]
	v_mfma_f32_16x16x32_bf16 v[48:51], v[162:165], v[178:181], v[48:51]
	v_mfma_f32_16x16x32_bf16 v[44:47], v[170:173], v[178:181], v[44:47]
	v_mfma_f32_16x16x32_bf16 v[36:39], v[162:165], v[186:189], v[36:39]
	v_mfma_f32_16x16x32_bf16 v[32:35], v[170:173], v[186:189], v[32:35]
	v_mfma_f32_16x16x32_bf16 v[16:19], v[162:165], v[198:201], v[16:19]
	v_mfma_f32_16x16x32_bf16 v[12:15], v[170:173], v[198:201], v[12:15]
	v_mfma_f32_16x16x32_bf16 v[4:7], v[162:165], v[208:211], v[4:7]
	v_mfma_f32_16x16x32_bf16 v[0:3], v[170:173], v[208:211], v[0:3]
	s_barrier
	s_add_i32 vcc_hi, vcc_hi, 2
	s_add_u32 s17, s17, 0x100
	s_addc_u32 vcc_lo, vcc_lo, 0
	s_cmp_gt_u32 vcc_hi, 13
	s_mov_b64 s[20:21], s[22:23]
	s_cbranch_scc0 .LBB0_1143

; #define PG8_STAGE(bufoff, gbase, voff) do { _Pragma("unroll") for (int _i = 0; _i < 2; ++_i) \
;         __builtin_amdgcn_global_load_lds((const unsigned*)((const char*)(gbase) + (voff)[_i]), (LAS unsigned*)(lds + (bufoff) + ldsw + _i * 8192), 16, 0, 0); } while (0)
; #define PG8_LDA(dst, b, h) do { _Pragma("unroll") for (int m = 0; m < 4; ++m) _Pragma("unroll") for (int k = 0; k < 2; ++k) dst[m][k] = *(const LAS bf16x8*)(lds + PG8_SA(b, h) + aoff + m * 2048 + k * 1024); } while (0)
; #define PG8_LDB(dst, b, h) do { _Pragma("unroll") for (int n = 0; n < 2; ++n) _Pragma("unroll") for (int k = 0; k < 2; ++k) dst[n][k] = *(const LAS bf16x8*)(lds + PG8_SB(b, h) + boff + n * 2048 + k * 1024); } while (0)
; #define PG8_MMA(ai, bj, At, Bt) do { __builtin_amdgcn_s_setprio(1); _Pragma("unroll") for (int m = 0; m < 4; ++m) _Pragma("unroll") for (int n = 0; n < 2; ++n) _Pragma("unroll") for (int k = 0; k < 2; ++k) \
;         acc[ai][bj][m][n] = __builtin_amdgcn_mfma_f32_16x16x32_bf16(Bt[n][k], At[m][k], acc[ai][bj][m][n], 0, 0, 0); __builtin_amdgcn_s_setprio(0); } while (0)
; #define PG8_WAIT_V(n) asm volatile("s_waitcnt vmcnt(" #n ")" ::: "memory")
; #define PG8_WAIT_L(n) asm volatile("s_waitcnt lgkmcnt(" #n ")" ::: "memory")
; #define PG8_BAR __builtin_amdgcn_s_barrier()
; #define PG8_SCHED __builtin_amdgcn_sched_barrier(0)
; template <class Epi>
; __device__ __forceinline__ void gemm_phase(LAS unsigned char* lds, const Gemm g, const Sched& S, const Epi& E, const int tid) {
;     ...
;         const char* nA = cA; const char* nB = cB; if (has_next) S.ptrs(nxt, nA, nB);
;         for (int t = 0; t < nt; t += 2) {
;             const bool last = (t == nt - 2);
;             const char* a1 = cA + (size_t)(t + 1) * kstep;
;             const char* a2 = last ? nA : cA + (size_t)(t + 2) * kstep; const char* b2 = last ? nB : cB + (size_t)(t + 2) * kstep;
;             const char* a3 = a2 + kstep; const char* b3 = b2 + kstep;
;             PG8_LDB(B0, 0, 0); PG8_LDB(B1, 0, 1); PG8_SCHED; PG8_LDA(At, 0, 0); PG8_STAGE(PG8_SA(1, 1), a1 + hA, voffA);
;             PG8_WAIT_V(8); PG8_WAIT_L(0); PG8_BAR; PG8_MMA(0, 0, At, B0); PG8_MMA(0, 1, At, B1); PG8_BAR; PG8_SCHED;
;             PG8_LDA(At, 0, 1); PG8_STAGE(PG8_SB(0, 0), b2, voffB); PG8_STAGE(PG8_SB(0, 1), b2 + hB, voffB); PG8_STAGE(PG8_SA(0, 0), a2, voffA);
.LBB0_1335:
	s_add_u32 s20, s20, 0x40080
	s_addc_u32 s21, s21, 0
	s_add_u32 s13, s22, 0x100
	s_addc_u32 s15, s23, 0
	s_mov_b32 s42, -2
	s_add_u32 s22, s20, 0xfffc0080
	s_addc_u32 s23, s21, -1
	s_add_i32 s43, 0, 0x10000
	s_cmp_eq_u32 s42, 12
	s_cselect_b32 s73, s7, s23
	s_cselect_b32 s72, s6, s22
	v_add_u32_e32 v138, s43, v141
	s_cselect_b32 s23, s17, s15
	s_cselect_b32 s22, s16, s13
	s_add_i32 s44, 0, 0x14000
	ds_read_b128 v[144:147], v138
	ds_read_b128 v[148:151], v138 offset:1024
	ds_read_b128 v[152:155], v138 offset:2048
	ds_read_b128 v[156:159], v138 offset:3072
	v_add_u32_e32 v138, s44, v141
	ds_read_b128 v[160:163], v138
	ds_read_b128 v[164:167], v138 offset:1024
	ds_read_b128 v[168:171], v138 offset:2048
	ds_read_b128 v[172:175], v138 offset:3072
	v_lshl_add_u64 v[138:139], s[20:21], 0, v[134:135]
	s_add_i32 m0, s19, 0xc000
	ds_read_b128 v[176:179], v143
	ds_read_b128 v[180:183], v143 offset:1024
	ds_read_b128 v[184:187], v143 offset:2048
	ds_read_b128 v[188:191], v143 offset:3072
	ds_read_b128 v[194:197], v143 offset:4096
	ds_read_b128 v[198:201], v143 offset:5120
	ds_read_b128 v[204:207], v143 offset:6144
	ds_read_b128 v[208:211], v143 offset:7168
	global_load_lds_dwordx4 v[138:139], off
	v_lshl_add_u64 v[138:139], s[20:21], 0, v[136:137]
	s_add_i32 m0, s19, 0xe000
	s_nop 0
	global_load_lds_dwordx4 v[138:139], off
	s_waitcnt vmcnt(8)
	s_waitcnt lgkmcnt(0)
	s_barrier
	s_waitcnt lgkmcnt(0)
	v_mfma_f32_16x16x32_bf16 v[124:127], v[144:147], v[176:179], 0
	v_mfma_f32_16x16x32_bf16 v[120:123], v[152:155], v[176:179], 0
	v_mfma_f32_16x16x32_bf16 v[108:111], v[144:147], v[184:187], 0
	v_mfma_f32_16x16x32_bf16 v[104:107], v[152:155], v[184:187], 0
	v_mfma_f32_16x16x32_bf16 v[92:95], v[144:147], v[194:197], 0
	v_mfma_f32_16x16x32_bf16 v[88:91], v[152:155], v[194:197], 0
	v_mfma_f32_16x16x32_bf16 v[76:79], v[144:147], v[204:207], 0
	v_mfma_f32_16x16x32_bf16 v[72:75], v[152:155], v[204:207], 0
	v_mfma_f32_16x16x32_bf16 v[124:127], v[148:151], v[180:183], v[124:127]
	v_mfma_f32_16x16x32_bf16 v[120:123], v[156:159], v[180:183], v[120:123]
	v_mfma_f32_16x16x32_bf16 v[108:111], v[148:151], v[188:191], v[108:111]
	v_mfma_f32_16x16x32_bf16 v[104:107], v[156:159], v[188:191], v[104:107]
	v_mfma_f32_16x16x32_bf16 v[92:95], v[148:151], v[198:201], v[92:95]
	v_mfma_f32_16x16x32_bf16 v[88:91], v[156:159], v[198:201], v[88:91]
	v_mfma_f32_16x16x32_bf16 v[76:79], v[148:151], v[208:211], v[76:79]
	v_mfma_f32_16x16x32_bf16 v[72:75], v[156:159], v[208:211], v[72:75]
	v_mfma_f32_16x16x32_bf16 v[116:119], v[160:163], v[176:179], 0
	v_mfma_f32_16x16x32_bf16 v[112:115], v[168:171], v[176:179], 0
	v_mfma_f32_16x16x32_bf16 v[100:103], v[160:163], v[184:187], 0
	v_mfma_f32_16x16x32_bf16 v[96:99], v[168:171], v[184:187], 0
	v_mfma_f32_16x16x32_bf16 v[84:87], v[160:163], v[194:197], 0
	v_mfma_f32_16x16x32_bf16 v[80:83], v[168:171], v[194:197], 0
	v_mfma_f32_16x16x32_bf16 v[68:71], v[160:163], v[204:207], 0
	v_mfma_f32_16x16x32_bf16 v[64:67], v[168:171], v[204:207], 0
	v_mfma_f32_16x16x32_bf16 v[116:119], v[164:167], v[180:183], v[116:119]
	v_mfma_f32_16x16x32_bf16 v[112:115], v[172:175], v[180:183], v[112:115]
	v_mfma_f32_16x16x32_bf16 v[100:103], v[164:167], v[188:191], v[100:103]
	v_mfma_f32_16x16x32_bf16 v[96:99], v[172:175], v[188:191], v[96:99]
	v_mfma_f32_16x16x32_bf16 v[84:87], v[164:167], v[198:201], v[84:87]
	v_mfma_f32_16x16x32_bf16 v[80:83], v[172:175], v[198:201], v[80:83]
	v_mfma_f32_16x16x32_bf16 v[68:71], v[164:167], v[208:211], v[68:71]
	v_mfma_f32_16x16x32_bf16 v[64:67], v[172:175], v[208:211], v[64:67]
	s_barrier
	s_add_i32 s43, s43, s35
	v_lshl_add_u64 v[138:139], s[22:23], 0, v[192:193]
	s_mov_b32 m0, s43
	ds_read_b128 v[176:179], v143 offset:16384
	ds_read_b128 v[180:183], v143 offset:17408
	ds_read_b128 v[184:187], v143 offset:18432
	ds_read_b128 v[188:191], v143 offset:19456
	ds_read_b128 v[194:197], v143 offset:20480
	ds_read_b128 v[198:201], v143 offset:21504
	ds_read_b128 v[204:207], v143 offset:22528
	ds_read_b128 v[208:211], v143 offset:23552
	global_load_lds_dwordx4 v[138:139], off
	s_add_i32 m0, s43, 0x2000
	s_add_u32 s76, s22, 0x40000
	v_lshl_add_u64 v[212:213], s[22:23], 0, v[128:129]
	s_addc_u32 s77, s23, 0
	s_add_i32 s43, s44, s35
	global_load_lds_dwordx4 v[212:213], off
	v_lshl_add_u64 v[214:215], s[76:77], 0, v[192:193]
	s_mov_b32 m0, s43
	v_lshl_add_u64 v[216:217], s[72:73], 0, v[130:131]
	global_load_lds_dwordx4 v[214:215], off
	v_lshl_add_u64 v[214:215], s[76:77], 0, v[128:129]
	s_add_i32 m0, s43, 0x2000
	s_nop 0
	global_load_lds_dwordx4 v[214:215], off
	v_lshl_add_u64 v[214:215], s[72:73], 0, v[132:133]
	s_mov_b32 m0, s19
	s_nop 0
	global_load_lds_dwordx4 v[214:215], off
	s_mov_b32 m0, s39
	s_nop 0
	global_load_lds_dwordx4 v[216:217], off
	s_waitcnt vmcnt(8)
	s_waitcnt lgkmcnt(0)
	s_barrier
; #define PG8_STAGE(bufoff, gbase, voff) do { _Pragma("unroll") for (int _i = 0; _i < 2; ++_i) \
;         __builtin_amdgcn_global_load_lds((const unsigned*)((const char*)(gbase) + (voff)[_i]), (LAS unsigned*)(lds + (bufoff) + ldsw + _i * 8192), 16, 0, 0); } while (0)
; #define PG8_LDA(dst, b, h) do { _Pragma("unroll") for (int m = 0; m < 4; ++m) _Pragma("unroll") for (int k = 0; k < 2; ++k) dst[m][k] = *(const LAS bf16x8*)(lds + PG8_SA(b, h) + aoff + m * 2048 + k * 1024); } while (0)
; #define PG8_LDB(dst, b, h) do { _Pragma("unroll") for (int n = 0; n < 2; ++n) _Pragma("unroll") for (int k = 0; k < 2; ++k) dst[n][k] = *(const LAS bf16x8*)(lds + PG8_SB(b, h) + boff + n * 2048 + k * 1024); } while (0)
; #define PG8_MMA(ai, bj, At, Bt) do { __builtin_amdgcn_s_setprio(1); _Pragma("unroll") for (int m = 0; m < 4; ++m) _Pragma("unroll") for (int n = 0; n < 2; ++n) _Pragma("unroll") for (int k = 0; k < 2; ++k) \
;         acc[ai][bj][m][n] = __builtin_amdgcn_mfma_f32_16x16x32_bf16(Bt[n][k], At[m][k], acc[ai][bj][m][n], 0, 0, 0); __builtin_amdgcn_s_setprio(0); } while (0)
; #define PG8_WAIT_V(n) asm volatile("s_waitcnt vmcnt(" #n ")" ::: "memory")
; #define PG8_WAIT_L(n) asm volatile("s_waitcnt lgkmcnt(" #n ")" ::: "memory")
; #define PG8_BAR __builtin_amdgcn_s_barrier()
; #define PG8_SCHED __builtin_amdgcn_sched_barrier(0)
; template <class Epi>
; __device__ __forceinline__ void gemm_phase(LAS unsigned char* lds, const Gemm g, const Sched& S, const Epi& E, const int tid) {
;     ...
;             PG8_WAIT_V(8); PG8_WAIT_L(0); PG8_BAR; PG8_MMA(1, 0, At, B0); PG8_MMA(1, 1, At, B1); PG8_BAR; PG8_SCHED;
;             PG8_LDB(B0, 1, 0); PG8_LDB(B1, 1, 1); PG8_SCHED; PG8_LDA(At, 1, 0); PG8_STAGE(PG8_SA(0, 1), a2 + hA, voffA);
;             PG8_WAIT_V(8); PG8_WAIT_L(0); PG8_BAR; PG8_MMA(0, 0, At, B0); PG8_MMA(0, 1, At, B1); PG8_BAR; PG8_SCHED;
	s_waitcnt lgkmcnt(0)
	v_mfma_f32_16x16x32_bf16 v[60:63], v[144:147], v[176:179], 0
	v_mfma_f32_16x16x32_bf16 v[56:59], v[152:155], v[176:179], 0
	v_mfma_f32_16x16x32_bf16 v[44:47], v[144:147], v[184:187], 0
	v_mfma_f32_16x16x32_bf16 v[40:43], v[152:155], v[184:187], 0
	v_mfma_f32_16x16x32_bf16 v[28:31], v[144:147], v[194:197], 0
	v_mfma_f32_16x16x32_bf16 v[24:27], v[152:155], v[194:197], 0
	v_mfma_f32_16x16x32_bf16 v[12:15], v[144:147], v[204:207], 0
	v_mfma_f32_16x16x32_bf16 v[8:11], v[152:155], v[204:207], 0
	v_mfma_f32_16x16x32_bf16 v[60:63], v[148:151], v[180:183], v[60:63]
	v_mfma_f32_16x16x32_bf16 v[56:59], v[156:159], v[180:183], v[56:59]
	v_mfma_f32_16x16x32_bf16 v[44:47], v[148:151], v[188:191], v[44:47]
	v_mfma_f32_16x16x32_bf16 v[40:43], v[156:159], v[188:191], v[40:43]
	v_mfma_f32_16x16x32_bf16 v[28:31], v[148:151], v[198:201], v[28:31]
	v_mfma_f32_16x16x32_bf16 v[24:27], v[156:159], v[198:201], v[24:27]
	v_mfma_f32_16x16x32_bf16 v[12:15], v[148:151], v[208:211], v[12:15]
	v_mfma_f32_16x16x32_bf16 v[8:11], v[156:159], v[208:211], v[8:11]
	v_mfma_f32_16x16x32_bf16 v[52:55], v[160:163], v[176:179], 0
	v_mfma_f32_16x16x32_bf16 v[48:51], v[168:171], v[176:179], 0
	v_mfma_f32_16x16x32_bf16 v[36:39], v[160:163], v[184:187], 0
	v_mfma_f32_16x16x32_bf16 v[32:35], v[168:171], v[184:187], 0
	v_mfma_f32_16x16x32_bf16 v[20:23], v[160:163], v[194:197], 0
	v_mfma_f32_16x16x32_bf16 v[16:19], v[168:171], v[194:197], 0
	v_mfma_f32_16x16x32_bf16 v[4:7], v[160:163], v[204:207], 0
	v_mfma_f32_16x16x32_bf16 v[0:3], v[168:171], v[204:207], 0
	v_mfma_f32_16x16x32_bf16 v[52:55], v[164:167], v[180:183], v[52:55]
	v_mfma_f32_16x16x32_bf16 v[48:51], v[172:175], v[180:183], v[48:51]
	v_mfma_f32_16x16x32_bf16 v[36:39], v[164:167], v[188:191], v[36:39]
	v_mfma_f32_16x16x32_bf16 v[32:35], v[172:175], v[188:191], v[32:35]
	v_mfma_f32_16x16x32_bf16 v[20:23], v[164:167], v[198:201], v[20:23]
	v_mfma_f32_16x16x32_bf16 v[16:19], v[172:175], v[198:201], v[16:19]
	v_mfma_f32_16x16x32_bf16 v[4:7], v[164:167], v[208:211], v[4:7]
	v_mfma_f32_16x16x32_bf16 v[0:3], v[172:175], v[208:211], v[0:3]
	s_barrier
	s_add_i32 s43, 0, 0x18000
	s_add_i32 s44, 0, 0x1c000
	v_add_u32_e32 v156, s43, v141
	v_add_u32_e32 v172, s44, v141
	ds_read_b128 v[144:147], v156
	ds_read_b128 v[148:151], v156 offset:1024
	ds_read_b128 v[152:155], v156 offset:2048
	ds_read_b128 v[156:159], v156 offset:3072
	ds_read_b128 v[160:163], v172
	ds_read_b128 v[164:167], v172 offset:1024
	ds_read_b128 v[168:171], v172 offset:2048
	ds_read_b128 v[172:175], v172 offset:3072
	s_add_u32 s72, s72, 0x40000
	s_addc_u32 s73, s73, 0
	s_mov_b32 m0, s40
	v_lshl_add_u64 v[218:219], s[72:73], 0, v[132:133]
	ds_read_b128 v[176:179], v143 offset:32768
	ds_read_b128 v[180:183], v143 offset:33792
	ds_read_b128 v[184:187], v143 offset:34816
	ds_read_b128 v[188:191], v143 offset:35840
	ds_read_b128 v[194:197], v143 offset:36864
	ds_read_b128 v[198:201], v143 offset:37888
	ds_read_b128 v[204:207], v143 offset:38912
	ds_read_b128 v[208:211], v143 offset:39936
	global_load_lds_dwordx4 v[218:219], off
	v_lshl_add_u64 v[218:219], s[72:73], 0, v[130:131]
	s_mov_b32 m0, s45
	s_nop 0
	global_load_lds_dwordx4 v[218:219], off
	s_waitcnt vmcnt(8)
	s_waitcnt lgkmcnt(0)
	s_barrier
	s_waitcnt lgkmcnt(0)
	v_mfma_f32_16x16x32_bf16 v[124:127], v[144:147], v[176:179], v[124:127]
	v_mfma_f32_16x16x32_bf16 v[120:123], v[152:155], v[176:179], v[120:123]
	v_mfma_f32_16x16x32_bf16 v[108:111], v[144:147], v[184:187], v[108:111]
	v_mfma_f32_16x16x32_bf16 v[104:107], v[152:155], v[184:187], v[104:107]
	v_mfma_f32_16x16x32_bf16 v[92:95], v[144:147], v[194:197], v[92:95]
	v_mfma_f32_16x16x32_bf16 v[88:91], v[152:155], v[194:197], v[88:91]
	v_mfma_f32_16x16x32_bf16 v[76:79], v[144:147], v[204:207], v[76:79]
	v_mfma_f32_16x16x32_bf16 v[72:75], v[152:155], v[204:207], v[72:75]
	v_mfma_f32_16x16x32_bf16 v[124:127], v[148:151], v[180:183], v[124:127]
	v_mfma_f32_16x16x32_bf16 v[120:123], v[156:159], v[180:183], v[120:123]
	v_mfma_f32_16x16x32_bf16 v[108:111], v[148:151], v[188:191], v[108:111]
	v_mfma_f32_16x16x32_bf16 v[104:107], v[156:159], v[188:191], v[104:107]
	v_mfma_f32_16x16x32_bf16 v[92:95], v[148:151], v[198:201], v[92:95]
	v_mfma_f32_16x16x32_bf16 v[88:91], v[156:159], v[198:201], v[88:91]
	v_mfma_f32_16x16x32_bf16 v[76:79], v[148:151], v[208:211], v[76:79]
	v_mfma_f32_16x16x32_bf16 v[72:75], v[156:159], v[208:211], v[72:75]
	v_mfma_f32_16x16x32_bf16 v[116:119], v[160:163], v[176:179], v[116:119]
	v_mfma_f32_16x16x32_bf16 v[112:115], v[168:171], v[176:179], v[112:115]
	v_mfma_f32_16x16x32_bf16 v[100:103], v[160:163], v[184:187], v[100:103]
	v_mfma_f32_16x16x32_bf16 v[96:99], v[168:171], v[184:187], v[96:99]
	v_mfma_f32_16x16x32_bf16 v[84:87], v[160:163], v[194:197], v[84:87]
	v_mfma_f32_16x16x32_bf16 v[80:83], v[168:171], v[194:197], v[80:83]
	v_mfma_f32_16x16x32_bf16 v[68:71], v[160:163], v[204:207], v[68:71]
	v_mfma_f32_16x16x32_bf16 v[64:67], v[168:171], v[204:207], v[64:67]
	v_mfma_f32_16x16x32_bf16 v[116:119], v[164:167], v[180:183], v[116:119]
	v_mfma_f32_16x16x32_bf16 v[112:115], v[172:175], v[180:183], v[112:115]
	v_mfma_f32_16x16x32_bf16 v[100:103], v[164:167], v[188:191], v[100:103]
	v_mfma_f32_16x16x32_bf16 v[96:99], v[172:175], v[188:191], v[96:99]
	v_mfma_f32_16x16x32_bf16 v[84:87], v[164:167], v[198:201], v[84:87]
	v_mfma_f32_16x16x32_bf16 v[80:83], v[172:175], v[198:201], v[80:83]
	v_mfma_f32_16x16x32_bf16 v[68:71], v[164:167], v[208:211], v[68:71]
	v_mfma_f32_16x16x32_bf16 v[64:67], v[172:175], v[208:211], v[64:67]
	s_barrier
; #define PG8_STAGE(bufoff, gbase, voff) do { _Pragma("unroll") for (int _i = 0; _i < 2; ++_i) \
;         __builtin_amdgcn_global_load_lds((const unsigned*)((const char*)(gbase) + (voff)[_i]), (LAS unsigned*)(lds + (bufoff) + ldsw + _i * 8192), 16, 0, 0); } while (0)
; #define PG8_LDA(dst, b, h) do { _Pragma("unroll") for (int m = 0; m < 4; ++m) _Pragma("unroll") for (int k = 0; k < 2; ++k) dst[m][k] = *(const LAS bf16x8*)(lds + PG8_SA(b, h) + aoff + m * 2048 + k * 1024); } while (0)
; #define PG8_LDB(dst, b, h) do { _Pragma("unroll") for (int n = 0; n < 2; ++n) _Pragma("unroll") for (int k = 0; k < 2; ++k) dst[n][k] = *(const LAS bf16x8*)(lds + PG8_SB(b, h) + boff + n * 2048 + k * 1024); } while (0)
; #define PG8_WAIT_V(n) asm volatile("s_waitcnt vmcnt(" #n ")" ::: "memory")
; #define PG8_WAIT_L(n) asm volatile("s_waitcnt lgkmcnt(" #n ")" ::: "memory")
; template <class Epi>
; __device__ __forceinline__ void gemm_phase(LAS unsigned char* lds, const Gemm g, const Sched& S, const Epi& E, const int tid) {
;     ...
;         for (int t = 0; t < nt; t += 2) {
;             const bool last = (t == nt - 2);
;             const char* a1 = cA + (size_t)(t + 1) * kstep;
;             const char* a2 = last ? nA : cA + (size_t)(t + 2) * kstep; const char* b2 = last ? nB : cB + (size_t)(t + 2) * kstep;
;             const char* a3 = a2 + kstep; const char* b3 = b2 + kstep;
;             PG8_LDB(B0, 0, 0); PG8_LDB(B1, 0, 1); PG8_SCHED; PG8_LDA(At, 0, 0); PG8_STAGE(PG8_SA(1, 1), a1 + hA, voffA);
;             PG8_WAIT_V(8); PG8_WAIT_L(0); PG8_BAR; PG8_MMA(0, 0, At, B0); PG8_MMA(0, 1, At, B1); PG8_BAR; PG8_SCHED;
;             PG8_LDA(At, 0, 1); PG8_STAGE(PG8_SB(0, 0), b2, voffB); PG8_STAGE(PG8_SB(0, 1), b2 + hB, voffB); PG8_STAGE(PG8_SA(0, 0), a2, voffA);
;             PG8_WAIT_V(8); PG8_WAIT_L(0); PG8_BAR; PG8_MMA(1, 0, At, B0); PG8_MMA(1, 1, At, B1); PG8_BAR; PG8_SCHED;
;             PG8_LDB(B0, 1, 0); PG8_LDB(B1, 1, 1); PG8_SCHED; PG8_LDA(At, 1, 0); PG8_STAGE(PG8_SA(0, 1), a2 + hA, voffA);
;             PG8_WAIT_V(8); PG8_WAIT_L(0); PG8_BAR; PG8_MMA(0, 0, At, B0); PG8_MMA(0, 1, At, B1); PG8_BAR; PG8_SCHED;
;             PG8_LDA(At, 1, 1); PG8_STAGE(PG8_SB(1, 0), b3, voffB); PG8_STAGE(PG8_SB(1, 1), b3 + hB, voffB); PG8_STAGE(PG8_SA(1, 0), a3, voffA);
;             PG8_WAIT_V(8); PG8_WAIT_L(0); PG8_BAR; PG8_MMA(1, 0, At, B0); PG8_MMA(1, 1, At, B1); PG8_BAR; PG8_SCHED;
	s_add_i32 s43, s43, s35
	v_lshl_add_u64 v[138:139], v[138:139], 0, s[94:95]
	s_mov_b32 m0, s43
	ds_read_b128 v[176:179], v143 offset:49152
	ds_read_b128 v[180:183], v143 offset:50176
	ds_read_b128 v[184:187], v143 offset:51200
	ds_read_b128 v[188:191], v143 offset:52224
	ds_read_b128 v[194:197], v143 offset:53248
	ds_read_b128 v[198:201], v143 offset:54272
	ds_read_b128 v[204:207], v143 offset:55296
	ds_read_b128 v[208:211], v143 offset:56320
	global_load_lds_dwordx4 v[138:139], off
	s_add_i32 m0, s43, 0x2000
	s_add_u32 s22, s22, 0x40080
	v_lshl_add_u64 v[138:139], v[212:213], 0, s[94:95]
	s_addc_u32 s23, s23, 0
	s_add_i32 s43, s44, s35
	global_load_lds_dwordx4 v[138:139], off
	v_lshl_add_u64 v[138:139], s[22:23], 0, v[192:193]
	s_mov_b32 m0, s43
	s_nop 0
	global_load_lds_dwordx4 v[138:139], off
	v_lshl_add_u64 v[138:139], s[22:23], 0, v[128:129]
	s_add_i32 m0, s43, 0x2000
	s_nop 0
	global_load_lds_dwordx4 v[138:139], off
	v_lshl_add_u64 v[138:139], v[214:215], 0, s[94:95]
	s_mov_b32 m0, s47
	s_nop 0
	global_load_lds_dwordx4 v[138:139], off
	v_lshl_add_u64 v[138:139], v[216:217], 0, s[94:95]
	s_mov_b32 m0, s51
	s_nop 0
	global_load_lds_dwordx4 v[138:139], off
	s_waitcnt vmcnt(8)
	s_waitcnt lgkmcnt(0)
	s_barrier
	s_waitcnt lgkmcnt(0)
	v_mfma_f32_16x16x32_bf16 v[60:63], v[144:147], v[176:179], v[60:63]
	v_mfma_f32_16x16x32_bf16 v[56:59], v[152:155], v[176:179], v[56:59]
	v_mfma_f32_16x16x32_bf16 v[44:47], v[144:147], v[184:187], v[44:47]
	v_mfma_f32_16x16x32_bf16 v[40:43], v[152:155], v[184:187], v[40:43]
	v_mfma_f32_16x16x32_bf16 v[28:31], v[144:147], v[194:197], v[28:31]
	v_mfma_f32_16x16x32_bf16 v[24:27], v[152:155], v[194:197], v[24:27]
	v_mfma_f32_16x16x32_bf16 v[12:15], v[144:147], v[204:207], v[12:15]
	v_mfma_f32_16x16x32_bf16 v[8:11], v[152:155], v[204:207], v[8:11]
	v_mfma_f32_16x16x32_bf16 v[60:63], v[148:151], v[180:183], v[60:63]
	v_mfma_f32_16x16x32_bf16 v[56:59], v[156:159], v[180:183], v[56:59]
	v_mfma_f32_16x16x32_bf16 v[44:47], v[148:151], v[188:191], v[44:47]
	v_mfma_f32_16x16x32_bf16 v[40:43], v[156:159], v[188:191], v[40:43]
	v_mfma_f32_16x16x32_bf16 v[28:31], v[148:151], v[198:201], v[28:31]
	v_mfma_f32_16x16x32_bf16 v[24:27], v[156:159], v[198:201], v[24:27]
	v_mfma_f32_16x16x32_bf16 v[12:15], v[148:151], v[208:211], v[12:15]
	v_mfma_f32_16x16x32_bf16 v[8:11], v[156:159], v[208:211], v[8:11]
	v_mfma_f32_16x16x32_bf16 v[52:55], v[160:163], v[176:179], v[52:55]
	v_mfma_f32_16x16x32_bf16 v[48:51], v[168:171], v[176:179], v[48:51]
	v_mfma_f32_16x16x32_bf16 v[36:39], v[160:163], v[184:187], v[36:39]
	v_mfma_f32_16x16x32_bf16 v[32:35], v[168:171], v[184:187], v[32:35]
	v_mfma_f32_16x16x32_bf16 v[20:23], v[160:163], v[194:197], v[20:23]
	v_mfma_f32_16x16x32_bf16 v[16:19], v[168:171], v[194:197], v[16:19]
	v_mfma_f32_16x16x32_bf16 v[4:7], v[160:163], v[204:207], v[4:7]
	v_mfma_f32_16x16x32_bf16 v[0:3], v[168:171], v[204:207], v[0:3]
	v_mfma_f32_16x16x32_bf16 v[52:55], v[164:167], v[180:183], v[52:55]
	v_mfma_f32_16x16x32_bf16 v[48:51], v[172:175], v[180:183], v[48:51]
	v_mfma_f32_16x16x32_bf16 v[36:39], v[164:167], v[188:191], v[36:39]
	v_mfma_f32_16x16x32_bf16 v[32:35], v[172:175], v[188:191], v[32:35]
	v_mfma_f32_16x16x32_bf16 v[20:23], v[164:167], v[198:201], v[20:23]
	v_mfma_f32_16x16x32_bf16 v[16:19], v[172:175], v[198:201], v[16:19]
	v_mfma_f32_16x16x32_bf16 v[4:7], v[164:167], v[208:211], v[4:7]
	v_mfma_f32_16x16x32_bf16 v[0:3], v[172:175], v[208:211], v[0:3]
	s_barrier
	s_add_i32 s42, s42, 2
	s_add_u32 s20, s20, 0x100
	s_addc_u32 s21, s21, 0
	s_add_u32 s13, s13, 0x100
	s_addc_u32 s15, s15, 0
	s_cmp_gt_u32 s42, 13
	s_cbranch_scc1 .Lgk_exit_4
.LBB0_1336:
	s_add_u32 s22, s20, 0xfffc0080
	s_addc_u32 s23, s21, -1
	s_add_i32 s43, 0, 0x10000
	s_cmp_eq_u32 s42, 12
	s_cselect_b32 s73, s7, s23
	s_cselect_b32 s72, s6, s22
	v_add_u32_e32 v138, s43, v141
	s_cselect_b32 s23, s17, s15
	s_cselect_b32 s22, s16, s13
	s_add_i32 s44, 0, 0x14000
	ds_read_b128 v[144:147], v138
	ds_read_b128 v[148:151], v138 offset:1024
	ds_read_b128 v[152:155], v138 offset:2048
	ds_read_b128 v[156:159], v138 offset:3072
	v_add_u32_e32 v138, s44, v141
	ds_read_b128 v[160:163], v138
	ds_read_b128 v[164:167], v138 offset:1024
	ds_read_b128 v[168:171], v138 offset:2048
	ds_read_b128 v[172:175], v138 offset:3072
	v_lshl_add_u64 v[138:139], s[20:21], 0, v[134:135]
	s_add_i32 m0, s19, 0xc000
	ds_read_b128 v[176:179], v143
	ds_read_b128 v[180:183], v143 offset:1024
	ds_read_b128 v[184:187], v143 offset:2048
	ds_read_b128 v[188:191], v143 offset:3072
	ds_read_b128 v[194:197], v143 offset:4096
	ds_read_b128 v[198:201], v143 offset:5120
	ds_read_b128 v[204:207], v143 offset:6144
	ds_read_b128 v[208:211], v143 offset:7168
	global_load_lds_dwordx4 v[138:139], off
	v_lshl_add_u64 v[138:139], s[20:21], 0, v[136:137]
	s_add_i32 m0, s19, 0xe000
	s_nop 0
	global_load_lds_dwordx4 v[138:139], off
	s_waitcnt vmcnt(8)
	s_waitcnt lgkmcnt(0)
	s_barrier
; #define PG8_STAGE(bufoff, gbase, voff) do { _Pragma("unroll") for (int _i = 0; _i < 2; ++_i) \
;         __builtin_amdgcn_global_load_lds((const unsigned*)((const char*)(gbase) + (voff)[_i]), (LAS unsigned*)(lds + (bufoff) + ldsw + _i * 8192), 16, 0, 0); } while (0)
; #define PG8_LDA(dst, b, h) do { _Pragma("unroll") for (int m = 0; m < 4; ++m) _Pragma("unroll") for (int k = 0; k < 2; ++k) dst[m][k] = *(const LAS bf16x8*)(lds + PG8_SA(b, h) + aoff + m * 2048 + k * 1024); } while (0)
; #define PG8_MMA(ai, bj, At, Bt) do { __builtin_amdgcn_s_setprio(1); _Pragma("unroll") for (int m = 0; m < 4; ++m) _Pragma("unroll") for (int n = 0; n < 2; ++n) _Pragma("unroll") for (int k = 0; k < 2; ++k) \
;         acc[ai][bj][m][n] = __builtin_amdgcn_mfma_f32_16x16x32_bf16(Bt[n][k], At[m][k], acc[ai][bj][m][n], 0, 0, 0); __builtin_amdgcn_s_setprio(0); } while (0)
; #define PG8_WAIT_V(n) asm volatile("s_waitcnt vmcnt(" #n ")" ::: "memory")
; #define PG8_WAIT_L(n) asm volatile("s_waitcnt lgkmcnt(" #n ")" ::: "memory")
; #define PG8_BAR __builtin_amdgcn_s_barrier()
; #define PG8_SCHED __builtin_amdgcn_sched_barrier(0)
; template <class Epi>
; __device__ __forceinline__ void gemm_phase(LAS unsigned char* lds, const Gemm g, const Sched& S, const Epi& E, const int tid) {
;     ...
;             PG8_WAIT_V(8); PG8_WAIT_L(0); PG8_BAR; PG8_MMA(0, 0, At, B0); PG8_MMA(0, 1, At, B1); PG8_BAR; PG8_SCHED;
;             PG8_LDA(At, 0, 1); PG8_STAGE(PG8_SB(0, 0), b2, voffB); PG8_STAGE(PG8_SB(0, 1), b2 + hB, voffB); PG8_STAGE(PG8_SA(0, 0), a2, voffA);
;             PG8_WAIT_V(8); PG8_WAIT_L(0); PG8_BAR; PG8_MMA(1, 0, At, B0); PG8_MMA(1, 1, At, B1); PG8_BAR; PG8_SCHED;
	s_waitcnt lgkmcnt(0)
	v_mfma_f32_16x16x32_bf16 v[124:127], v[144:147], v[176:179], v[124:127]
	v_mfma_f32_16x16x32_bf16 v[120:123], v[152:155], v[176:179], v[120:123]
	v_mfma_f32_16x16x32_bf16 v[108:111], v[144:147], v[184:187], v[108:111]
	v_mfma_f32_16x16x32_bf16 v[104:107], v[152:155], v[184:187], v[104:107]
	v_mfma_f32_16x16x32_bf16 v[92:95], v[144:147], v[194:197], v[92:95]
	v_mfma_f32_16x16x32_bf16 v[88:91], v[152:155], v[194:197], v[88:91]
	v_mfma_f32_16x16x32_bf16 v[76:79], v[144:147], v[204:207], v[76:79]
	v_mfma_f32_16x16x32_bf16 v[72:75], v[152:155], v[204:207], v[72:75]
	v_mfma_f32_16x16x32_bf16 v[124:127], v[148:151], v[180:183], v[124:127]
	v_mfma_f32_16x16x32_bf16 v[120:123], v[156:159], v[180:183], v[120:123]
	v_mfma_f32_16x16x32_bf16 v[108:111], v[148:151], v[188:191], v[108:111]
	v_mfma_f32_16x16x32_bf16 v[104:107], v[156:159], v[188:191], v[104:107]
	v_mfma_f32_16x16x32_bf16 v[92:95], v[148:151], v[198:201], v[92:95]
	v_mfma_f32_16x16x32_bf16 v[88:91], v[156:159], v[198:201], v[88:91]
	v_mfma_f32_16x16x32_bf16 v[76:79], v[148:151], v[208:211], v[76:79]
	v_mfma_f32_16x16x32_bf16 v[72:75], v[156:159], v[208:211], v[72:75]
	v_mfma_f32_16x16x32_bf16 v[116:119], v[160:163], v[176:179], v[116:119]
	v_mfma_f32_16x16x32_bf16 v[112:115], v[168:171], v[176:179], v[112:115]
	v_mfma_f32_16x16x32_bf16 v[100:103], v[160:163], v[184:187], v[100:103]
	v_mfma_f32_16x16x32_bf16 v[96:99], v[168:171], v[184:187], v[96:99]
	v_mfma_f32_16x16x32_bf16 v[84:87], v[160:163], v[194:197], v[84:87]
	v_mfma_f32_16x16x32_bf16 v[80:83], v[168:171], v[194:197], v[80:83]
	v_mfma_f32_16x16x32_bf16 v[68:71], v[160:163], v[204:207], v[68:71]
	v_mfma_f32_16x16x32_bf16 v[64:67], v[168:171], v[204:207], v[64:67]
	v_mfma_f32_16x16x32_bf16 v[116:119], v[164:167], v[180:183], v[116:119]
	v_mfma_f32_16x16x32_bf16 v[112:115], v[172:175], v[180:183], v[112:115]
	v_mfma_f32_16x16x32_bf16 v[100:103], v[164:167], v[188:191], v[100:103]
	v_mfma_f32_16x16x32_bf16 v[96:99], v[172:175], v[188:191], v[96:99]
	v_mfma_f32_16x16x32_bf16 v[84:87], v[164:167], v[198:201], v[84:87]
	v_mfma_f32_16x16x32_bf16 v[80:83], v[172:175], v[198:201], v[80:83]
	v_mfma_f32_16x16x32_bf16 v[68:71], v[164:167], v[208:211], v[68:71]
	v_mfma_f32_16x16x32_bf16 v[64:67], v[172:175], v[208:211], v[64:67]
	s_barrier
	s_add_i32 s43, s43, s35
	v_lshl_add_u64 v[138:139], s[22:23], 0, v[192:193]
	s_mov_b32 m0, s43
	ds_read_b128 v[176:179], v143 offset:16384
	ds_read_b128 v[180:183], v143 offset:17408
	ds_read_b128 v[184:187], v143 offset:18432
	ds_read_b128 v[188:191], v143 offset:19456
	ds_read_b128 v[194:197], v143 offset:20480
	ds_read_b128 v[198:201], v143 offset:21504
	ds_read_b128 v[204:207], v143 offset:22528
	ds_read_b128 v[208:211], v143 offset:23552
	global_load_lds_dwordx4 v[138:139], off
	s_add_i32 m0, s43, 0x2000
	s_add_u32 s76, s22, 0x40000
	v_lshl_add_u64 v[212:213], s[22:23], 0, v[128:129]
	s_addc_u32 s77, s23, 0
	s_add_i32 s43, s44, s35
	global_load_lds_dwordx4 v[212:213], off
	v_lshl_add_u64 v[214:215], s[76:77], 0, v[192:193]
	s_mov_b32 m0, s43
	v_lshl_add_u64 v[216:217], s[72:73], 0, v[130:131]
	global_load_lds_dwordx4 v[214:215], off
	v_lshl_add_u64 v[214:215], s[76:77], 0, v[128:129]
	s_add_i32 m0, s43, 0x2000
	s_nop 0
	global_load_lds_dwordx4 v[214:215], off
	v_lshl_add_u64 v[214:215], s[72:73], 0, v[132:133]
	s_mov_b32 m0, s19
	s_nop 0
	global_load_lds_dwordx4 v[214:215], off
	s_mov_b32 m0, s39
	s_nop 0
	global_load_lds_dwordx4 v[216:217], off
	s_waitcnt vmcnt(8)
	s_waitcnt lgkmcnt(0)
	s_barrier
	s_waitcnt lgkmcnt(0)
	v_mfma_f32_16x16x32_bf16 v[60:63], v[144:147], v[176:179], v[60:63]
	v_mfma_f32_16x16x32_bf16 v[56:59], v[152:155], v[176:179], v[56:59]
	v_mfma_f32_16x16x32_bf16 v[44:47], v[144:147], v[184:187], v[44:47]
	v_mfma_f32_16x16x32_bf16 v[40:43], v[152:155], v[184:187], v[40:43]
	v_mfma_f32_16x16x32_bf16 v[28:31], v[144:147], v[194:197], v[28:31]
	v_mfma_f32_16x16x32_bf16 v[24:27], v[152:155], v[194:197], v[24:27]
	v_mfma_f32_16x16x32_bf16 v[12:15], v[144:147], v[204:207], v[12:15]
	v_mfma_f32_16x16x32_bf16 v[8:11], v[152:155], v[204:207], v[8:11]
	v_mfma_f32_16x16x32_bf16 v[60:63], v[148:151], v[180:183], v[60:63]
	v_mfma_f32_16x16x32_bf16 v[56:59], v[156:159], v[180:183], v[56:59]
	v_mfma_f32_16x16x32_bf16 v[44:47], v[148:151], v[188:191], v[44:47]
	v_mfma_f32_16x16x32_bf16 v[40:43], v[156:159], v[188:191], v[40:43]
	v_mfma_f32_16x16x32_bf16 v[28:31], v[148:151], v[198:201], v[28:31]
	v_mfma_f32_16x16x32_bf16 v[24:27], v[156:159], v[198:201], v[24:27]
	v_mfma_f32_16x16x32_bf16 v[12:15], v[148:151], v[208:211], v[12:15]
	v_mfma_f32_16x16x32_bf16 v[8:11], v[156:159], v[208:211], v[8:11]
	v_mfma_f32_16x16x32_bf16 v[52:55], v[160:163], v[176:179], v[52:55]
	v_mfma_f32_16x16x32_bf16 v[48:51], v[168:171], v[176:179], v[48:51]
	v_mfma_f32_16x16x32_bf16 v[36:39], v[160:163], v[184:187], v[36:39]
	v_mfma_f32_16x16x32_bf16 v[32:35], v[168:171], v[184:187], v[32:35]
	v_mfma_f32_16x16x32_bf16 v[20:23], v[160:163], v[194:197], v[20:23]
	v_mfma_f32_16x16x32_bf16 v[16:19], v[168:171], v[194:197], v[16:19]
	v_mfma_f32_16x16x32_bf16 v[4:7], v[160:163], v[204:207], v[4:7]
	v_mfma_f32_16x16x32_bf16 v[0:3], v[168:171], v[204:207], v[0:3]
	v_mfma_f32_16x16x32_bf16 v[52:55], v[164:167], v[180:183], v[52:55]
	v_mfma_f32_16x16x32_bf16 v[48:51], v[172:175], v[180:183], v[48:51]
	v_mfma_f32_16x16x32_bf16 v[36:39], v[164:167], v[188:191], v[36:39]
	v_mfma_f32_16x16x32_bf16 v[32:35], v[172:175], v[188:191], v[32:35]
	v_mfma_f32_16x16x32_bf16 v[20:23], v[164:167], v[198:201], v[20:23]
	v_mfma_f32_16x16x32_bf16 v[16:19], v[172:175], v[198:201], v[16:19]
	v_mfma_f32_16x16x32_bf16 v[4:7], v[164:167], v[208:211], v[4:7]
	v_mfma_f32_16x16x32_bf16 v[0:3], v[172:175], v[208:211], v[0:3]
	s_barrier
; #define PG8_STAGE(bufoff, gbase, voff) do { _Pragma("unroll") for (int _i = 0; _i < 2; ++_i) \
;         __builtin_amdgcn_global_load_lds((const unsigned*)((const char*)(gbase) + (voff)[_i]), (LAS unsigned*)(lds + (bufoff) + ldsw + _i * 8192), 16, 0, 0); } while (0)
; #define PG8_LDA(dst, b, h) do { _Pragma("unroll") for (int m = 0; m < 4; ++m) _Pragma("unroll") for (int k = 0; k < 2; ++k) dst[m][k] = *(const LAS bf16x8*)(lds + PG8_SA(b, h) + aoff + m * 2048 + k * 1024); } while (0)
; #define PG8_LDB(dst, b, h) do { _Pragma("unroll") for (int n = 0; n < 2; ++n) _Pragma("unroll") for (int k = 0; k < 2; ++k) dst[n][k] = *(const LAS bf16x8*)(lds + PG8_SB(b, h) + boff + n * 2048 + k * 1024); } while (0)
; #define PG8_MMA(ai, bj, At, Bt) do { __builtin_amdgcn_s_setprio(1); _Pragma("unroll") for (int m = 0; m < 4; ++m) _Pragma("unroll") for (int n = 0; n < 2; ++n) _Pragma("unroll") for (int k = 0; k < 2; ++k) \
;         acc[ai][bj][m][n] = __builtin_amdgcn_mfma_f32_16x16x32_bf16(Bt[n][k], At[m][k], acc[ai][bj][m][n], 0, 0, 0); __builtin_amdgcn_s_setprio(0); } while (0)
; #define PG8_WAIT_V(n) asm volatile("s_waitcnt vmcnt(" #n ")" ::: "memory")
; #define PG8_WAIT_L(n) asm volatile("s_waitcnt lgkmcnt(" #n ")" ::: "memory")
; #define PG8_BAR __builtin_amdgcn_s_barrier()
; #define PG8_SCHED __builtin_amdgcn_sched_barrier(0)
; template <class Epi>
; __device__ __forceinline__ void gemm_phase(LAS unsigned char* lds, const Gemm g, const Sched& S, const Epi& E, const int tid) {
;     ...
;             PG8_LDB(B0, 1, 0); PG8_LDB(B1, 1, 1); PG8_SCHED; PG8_LDA(At, 1, 0); PG8_STAGE(PG8_SA(0, 1), a2 + hA, voffA);
;             PG8_WAIT_V(8); PG8_WAIT_L(0); PG8_BAR; PG8_MMA(0, 0, At, B0); PG8_MMA(0, 1, At, B1); PG8_BAR; PG8_SCHED;
	s_add_i32 s43, 0, 0x18000
	s_add_i32 s44, 0, 0x1c000
	v_add_u32_e32 v156, s43, v141
	v_add_u32_e32 v172, s44, v141
	ds_read_b128 v[144:147], v156
	ds_read_b128 v[148:151], v156 offset:1024
	ds_read_b128 v[152:155], v156 offset:2048
	ds_read_b128 v[156:159], v156 offset:3072
	ds_read_b128 v[160:163], v172
	ds_read_b128 v[164:167], v172 offset:1024
	ds_read_b128 v[168:171], v172 offset:2048
	ds_read_b128 v[172:175], v172 offset:3072
	s_add_u32 s72, s72, 0x40000
	s_addc_u32 s73, s73, 0
	s_mov_b32 m0, s40
	v_lshl_add_u64 v[218:219], s[72:73], 0, v[132:133]
	ds_read_b128 v[176:179], v143 offset:32768
	ds_read_b128 v[180:183], v143 offset:33792
	ds_read_b128 v[184:187], v143 offset:34816
	ds_read_b128 v[188:191], v143 offset:35840
	ds_read_b128 v[194:197], v143 offset:36864
	ds_read_b128 v[198:201], v143 offset:37888
	ds_read_b128 v[204:207], v143 offset:38912
	ds_read_b128 v[208:211], v143 offset:39936
	global_load_lds_dwordx4 v[218:219], off
	v_lshl_add_u64 v[218:219], s[72:73], 0, v[130:131]
	s_mov_b32 m0, s45
	s_nop 0
	global_load_lds_dwordx4 v[218:219], off
	s_waitcnt vmcnt(8)
	s_waitcnt lgkmcnt(0)
	s_barrier
	s_waitcnt lgkmcnt(0)
	v_mfma_f32_16x16x32_bf16 v[124:127], v[144:147], v[176:179], v[124:127]
	v_mfma_f32_16x16x32_bf16 v[120:123], v[152:155], v[176:179], v[120:123]
	v_mfma_f32_16x16x32_bf16 v[108:111], v[144:147], v[184:187], v[108:111]
	v_mfma_f32_16x16x32_bf16 v[104:107], v[152:155], v[184:187], v[104:107]
	v_mfma_f32_16x16x32_bf16 v[92:95], v[144:147], v[194:197], v[92:95]
	v_mfma_f32_16x16x32_bf16 v[88:91], v[152:155], v[194:197], v[88:91]
	v_mfma_f32_16x16x32_bf16 v[76:79], v[144:147], v[204:207], v[76:79]
	v_mfma_f32_16x16x32_bf16 v[72:75], v[152:155], v[204:207], v[72:75]
	v_mfma_f32_16x16x32_bf16 v[124:127], v[148:151], v[180:183], v[124:127]
	v_mfma_f32_16x16x32_bf16 v[120:123], v[156:159], v[180:183], v[120:123]
	v_mfma_f32_16x16x32_bf16 v[108:111], v[148:151], v[188:191], v[108:111]
	v_mfma_f32_16x16x32_bf16 v[104:107], v[156:159], v[188:191], v[104:107]
	v_mfma_f32_16x16x32_bf16 v[92:95], v[148:151], v[198:201], v[92:95]
	v_mfma_f32_16x16x32_bf16 v[88:91], v[156:159], v[198:201], v[88:91]
	v_mfma_f32_16x16x32_bf16 v[76:79], v[148:151], v[208:211], v[76:79]
	v_mfma_f32_16x16x32_bf16 v[72:75], v[156:159], v[208:211], v[72:75]
	v_mfma_f32_16x16x32_bf16 v[116:119], v[160:163], v[176:179], v[116:119]
	v_mfma_f32_16x16x32_bf16 v[112:115], v[168:171], v[176:179], v[112:115]
	v_mfma_f32_16x16x32_bf16 v[100:103], v[160:163], v[184:187], v[100:103]
	v_mfma_f32_16x16x32_bf16 v[96:99], v[168:171], v[184:187], v[96:99]
	v_mfma_f32_16x16x32_bf16 v[84:87], v[160:163], v[194:197], v[84:87]
	v_mfma_f32_16x16x32_bf16 v[80:83], v[168:171], v[194:197], v[80:83]
	v_mfma_f32_16x16x32_bf16 v[68:71], v[160:163], v[204:207], v[68:71]
	v_mfma_f32_16x16x32_bf16 v[64:67], v[168:171], v[204:207], v[64:67]
	v_mfma_f32_16x16x32_bf16 v[116:119], v[164:167], v[180:183], v[116:119]
	v_mfma_f32_16x16x32_bf16 v[112:115], v[172:175], v[180:183], v[112:115]
	v_mfma_f32_16x16x32_bf16 v[100:103], v[164:167], v[188:191], v[100:103]
	v_mfma_f32_16x16x32_bf16 v[96:99], v[172:175], v[188:191], v[96:99]
	v_mfma_f32_16x16x32_bf16 v[84:87], v[164:167], v[198:201], v[84:87]
	v_mfma_f32_16x16x32_bf16 v[80:83], v[172:175], v[198:201], v[80:83]
	v_mfma_f32_16x16x32_bf16 v[68:71], v[164:167], v[208:211], v[68:71]
	v_mfma_f32_16x16x32_bf16 v[64:67], v[172:175], v[208:211], v[64:67]
	s_barrier
; #define PG8_STAGE(bufoff, gbase, voff) do { _Pragma("unroll") for (int _i = 0; _i < 2; ++_i) \
;         __builtin_amdgcn_global_load_lds((const unsigned*)((const char*)(gbase) + (voff)[_i]), (LAS unsigned*)(lds + (bufoff) + ldsw + _i * 8192), 16, 0, 0); } while (0)
; #define PG8_LDA(dst, b, h) do { _Pragma("unroll") for (int m = 0; m < 4; ++m) _Pragma("unroll") for (int k = 0; k < 2; ++k) dst[m][k] = *(const LAS bf16x8*)(lds + PG8_SA(b, h) + aoff + m * 2048 + k * 1024); } while (0)
; #define PG8_MMA(ai, bj, At, Bt) do { __builtin_amdgcn_s_setprio(1); _Pragma("unroll") for (int m = 0; m < 4; ++m) _Pragma("unroll") for (int n = 0; n < 2; ++n) _Pragma("unroll") for (int k = 0; k < 2; ++k) \
;         acc[ai][bj][m][n] = __builtin_amdgcn_mfma_f32_16x16x32_bf16(Bt[n][k], At[m][k], acc[ai][bj][m][n], 0, 0, 0); __builtin_amdgcn_s_setprio(0); } while (0)
; #define PG8_WAIT_V(n) asm volatile("s_waitcnt vmcnt(" #n ")" ::: "memory")
; #define PG8_WAIT_L(n) asm volatile("s_waitcnt lgkmcnt(" #n ")" ::: "memory")
; #define PG8_BAR __builtin_amdgcn_s_barrier()
; #define PG8_SCHED __builtin_amdgcn_sched_barrier(0)
; template <class Epi>
; __device__ __forceinline__ void gemm_phase(LAS unsigned char* lds, const Gemm g, const Sched& S, const Epi& E, const int tid) {
;     ...
;             PG8_LDA(At, 1, 1); PG8_STAGE(PG8_SB(1, 0), b3, voffB); PG8_STAGE(PG8_SB(1, 1), b3 + hB, voffB); PG8_STAGE(PG8_SA(1, 0), a3, voffA);
;             PG8_WAIT_V(8); PG8_WAIT_L(0); PG8_BAR; PG8_MMA(1, 0, At, B0); PG8_MMA(1, 1, At, B1); PG8_BAR; PG8_SCHED;
	s_add_i32 s43, s43, s35
	v_lshl_add_u64 v[138:139], v[138:139], 0, s[94:95]
	s_mov_b32 m0, s43
	ds_read_b128 v[176:179], v143 offset:49152
	ds_read_b128 v[180:183], v143 offset:50176
	ds_read_b128 v[184:187], v143 offset:51200
	ds_read_b128 v[188:191], v143 offset:52224
	ds_read_b128 v[194:197], v143 offset:53248
	ds_read_b128 v[198:201], v143 offset:54272
	ds_read_b128 v[204:207], v143 offset:55296
	ds_read_b128 v[208:211], v143 offset:56320
	global_load_lds_dwordx4 v[138:139], off
	s_add_i32 m0, s43, 0x2000
	s_add_u32 s22, s22, 0x40080
	v_lshl_add_u64 v[138:139], v[212:213], 0, s[94:95]
	s_addc_u32 s23, s23, 0
	s_add_i32 s43, s44, s35
	global_load_lds_dwordx4 v[138:139], off
	v_lshl_add_u64 v[138:139], s[22:23], 0, v[192:193]
	s_mov_b32 m0, s43
	s_nop 0
	global_load_lds_dwordx4 v[138:139], off
	v_lshl_add_u64 v[138:139], s[22:23], 0, v[128:129]
	s_add_i32 m0, s43, 0x2000
	s_nop 0
	global_load_lds_dwordx4 v[138:139], off
	v_lshl_add_u64 v[138:139], v[214:215], 0, s[94:95]
	s_mov_b32 m0, s47
	s_nop 0
	global_load_lds_dwordx4 v[138:139], off
	v_lshl_add_u64 v[138:139], v[216:217], 0, s[94:95]
	s_mov_b32 m0, s51
	s_nop 0
	global_load_lds_dwordx4 v[138:139], off
	s_waitcnt vmcnt(8)
	s_waitcnt lgkmcnt(0)
	s_barrier
	s_waitcnt lgkmcnt(0)
	v_mfma_f32_16x16x32_bf16 v[60:63], v[144:147], v[176:179], v[60:63]
	v_mfma_f32_16x16x32_bf16 v[56:59], v[152:155], v[176:179], v[56:59]
	v_mfma_f32_16x16x32_bf16 v[44:47], v[144:147], v[184:187], v[44:47]
	v_mfma_f32_16x16x32_bf16 v[40:43], v[152:155], v[184:187], v[40:43]
	v_mfma_f32_16x16x32_bf16 v[28:31], v[144:147], v[194:197], v[28:31]
	v_mfma_f32_16x16x32_bf16 v[24:27], v[152:155], v[194:197], v[24:27]
	v_mfma_f32_16x16x32_bf16 v[12:15], v[144:147], v[204:207], v[12:15]
	v_mfma_f32_16x16x32_bf16 v[8:11], v[152:155], v[204:207], v[8:11]
	v_mfma_f32_16x16x32_bf16 v[60:63], v[148:151], v[180:183], v[60:63]
	v_mfma_f32_16x16x32_bf16 v[56:59], v[156:159], v[180:183], v[56:59]
	v_mfma_f32_16x16x32_bf16 v[44:47], v[148:151], v[188:191], v[44:47]
	v_mfma_f32_16x16x32_bf16 v[40:43], v[156:159], v[188:191], v[40:43]
	v_mfma_f32_16x16x32_bf16 v[28:31], v[148:151], v[198:201], v[28:31]
	v_mfma_f32_16x16x32_bf16 v[24:27], v[156:159], v[198:201], v[24:27]
	v_mfma_f32_16x16x32_bf16 v[12:15], v[148:151], v[208:211], v[12:15]
	v_mfma_f32_16x16x32_bf16 v[8:11], v[156:159], v[208:211], v[8:11]
	v_mfma_f32_16x16x32_bf16 v[52:55], v[160:163], v[176:179], v[52:55]
	v_mfma_f32_16x16x32_bf16 v[48:51], v[168:171], v[176:179], v[48:51]
	v_mfma_f32_16x16x32_bf16 v[36:39], v[160:163], v[184:187], v[36:39]
	v_mfma_f32_16x16x32_bf16 v[32:35], v[168:171], v[184:187], v[32:35]
	v_mfma_f32_16x16x32_bf16 v[20:23], v[160:163], v[194:197], v[20:23]
	v_mfma_f32_16x16x32_bf16 v[16:19], v[168:171], v[194:197], v[16:19]
	v_mfma_f32_16x16x32_bf16 v[4:7], v[160:163], v[204:207], v[4:7]
	v_mfma_f32_16x16x32_bf16 v[0:3], v[168:171], v[204:207], v[0:3]
	v_mfma_f32_16x16x32_bf16 v[52:55], v[164:167], v[180:183], v[52:55]
	v_mfma_f32_16x16x32_bf16 v[48:51], v[172:175], v[180:183], v[48:51]
	v_mfma_f32_16x16x32_bf16 v[36:39], v[164:167], v[188:191], v[36:39]
	v_mfma_f32_16x16x32_bf16 v[32:35], v[172:175], v[188:191], v[32:35]
	v_mfma_f32_16x16x32_bf16 v[20:23], v[164:167], v[198:201], v[20:23]
	v_mfma_f32_16x16x32_bf16 v[16:19], v[172:175], v[198:201], v[16:19]
	v_mfma_f32_16x16x32_bf16 v[4:7], v[164:167], v[208:211], v[4:7]
	v_mfma_f32_16x16x32_bf16 v[0:3], v[172:175], v[208:211], v[0:3]
	s_barrier
	s_add_i32 s42, s42, 2
	s_add_u32 s20, s20, 0x100
	s_addc_u32 s21, s21, 0
	s_add_u32 s13, s13, 0x100
	s_addc_u32 s15, s15, 0
	s_cmp_gt_u32 s42, 13
	s_cbranch_scc0 .LBB0_1336

; #define PG8_STAGE(bufoff, gbase, voff) do { _Pragma("unroll") for (int _i = 0; _i < 2; ++_i) \
;         __builtin_amdgcn_global_load_lds((const unsigned*)((const char*)(gbase) + (voff)[_i]), (LAS unsigned*)(lds + (bufoff) + ldsw + _i * 8192), 16, 0, 0); } while (0)
; #define PG8_LDA(dst, b, h) do { _Pragma("unroll") for (int m = 0; m < 4; ++m) _Pragma("unroll") for (int k = 0; k < 2; ++k) dst[m][k] = *(const LAS bf16x8*)(lds + PG8_SA(b, h) + aoff + m * 2048 + k * 1024); } while (0)
; #define PG8_LDB(dst, b, h) do { _Pragma("unroll") for (int n = 0; n < 2; ++n) _Pragma("unroll") for (int k = 0; k < 2; ++k) dst[n][k] = *(const LAS bf16x8*)(lds + PG8_SB(b, h) + boff + n * 2048 + k * 1024); } while (0)
; #define PG8_MMA(ai, bj, At, Bt) do { __builtin_amdgcn_s_setprio(1); _Pragma("unroll") for (int m = 0; m < 4; ++m) _Pragma("unroll") for (int n = 0; n < 2; ++n) _Pragma("unroll") for (int k = 0; k < 2; ++k) \
;         acc[ai][bj][m][n] = __builtin_amdgcn_mfma_f32_16x16x32_bf16(Bt[n][k], At[m][k], acc[ai][bj][m][n], 0, 0, 0); __builtin_amdgcn_s_setprio(0); } while (0)
; #define PG8_WAIT_V(n) asm volatile("s_waitcnt vmcnt(" #n ")" ::: "memory")
; #define PG8_WAIT_L(n) asm volatile("s_waitcnt lgkmcnt(" #n ")" ::: "memory")
; #define PG8_BAR __builtin_amdgcn_s_barrier()
; #define PG8_SCHED __builtin_amdgcn_sched_barrier(0)
; template <class Epi>
; __device__ __forceinline__ void gemm_phase(LAS unsigned char* lds, const Gemm g, const Sched& S, const Epi& E, const int tid) {
;     ...
;         const char* nA = cA; const char* nB = cB; if (has_next) S.ptrs(nxt, nA, nB);
;         for (int t = 0; t < nt; t += 2) {
;             const bool last = (t == nt - 2);
;             const char* a1 = cA + (size_t)(t + 1) * kstep;
;             const char* a2 = last ? nA : cA + (size_t)(t + 2) * kstep; const char* b2 = last ? nB : cB + (size_t)(t + 2) * kstep;
;             const char* a3 = a2 + kstep; const char* b3 = b2 + kstep;
;             PG8_LDB(B0, 0, 0); PG8_LDB(B1, 0, 1); PG8_SCHED; PG8_LDA(At, 0, 0); PG8_STAGE(PG8_SA(1, 1), a1 + hA, voffA);
;             PG8_WAIT_V(8); PG8_WAIT_L(0); PG8_BAR; PG8_MMA(0, 0, At, B0); PG8_MMA(0, 1, At, B1); PG8_BAR; PG8_SCHED;
;             PG8_LDA(At, 0, 1); PG8_STAGE(PG8_SB(0, 0), b2, voffB); PG8_STAGE(PG8_SB(0, 1), b2 + hB, voffB); PG8_STAGE(PG8_SA(0, 0), a2, voffA);
.LBB0_1410:
	s_add_u32 s80, s18, 0x100
	s_addc_u32 s81, s19, 0
	s_mov_b32 vcc_lo, -2
	s_add_u32 s18, s16, 0x100
	s_addc_u32 s19, s17, 0
	s_add_i32 s43, 0, 0x10000
	s_cmp_eq_u32 vcc_lo, 40
	s_cselect_b32 s23, s7, s19
	s_cselect_b32 s22, s6, s18
	s_cselect_b32 s21, s15, s81
	s_cselect_b32 s20, s14, s80
	s_add_i32 s44, 0, 0x14000
	v_add_u32_e32 v92, s43, v157
	v_add_u32_e32 v154, s44, v157
	ds_read_b128 v[64:67], v92
	ds_read_b128 v[68:71], v92 offset:1024
	ds_read_b128 v[80:83], v92 offset:2048
	ds_read_b128 v[92:95], v92 offset:3072
	ds_read_b128 v[160:163], v154
	ds_read_b128 v[164:167], v154 offset:1024
	ds_read_b128 v[168:171], v154 offset:2048
	ds_read_b128 v[172:175], v154 offset:3072
	v_lshl_add_u64 v[154:155], s[16:17], 0, v[150:151]
	s_add_i32 m0, s40, 0xc000
	ds_read_b128 v[176:179], v159
	ds_read_b128 v[180:183], v159 offset:1024
	ds_read_b128 v[184:187], v159 offset:2048
	ds_read_b128 v[188:191], v159 offset:3072
	ds_read_b128 v[194:197], v159 offset:4096
	ds_read_b128 v[198:201], v159 offset:5120
	ds_read_b128 v[204:207], v159 offset:6144
	ds_read_b128 v[208:211], v159 offset:7168
	global_load_lds_dwordx4 v[154:155], off
	v_lshl_add_u64 v[154:155], s[16:17], 0, v[152:153]
	s_add_i32 m0, s40, 0xe000
	s_nop 0
	global_load_lds_dwordx4 v[154:155], off
	s_waitcnt vmcnt(8)
	s_waitcnt lgkmcnt(0)
	s_barrier
	s_waitcnt lgkmcnt(0)
	v_mfma_f32_16x16x32_bf16 v[140:143], v[64:67], v[176:179], 0
	v_mfma_f32_16x16x32_bf16 v[136:139], v[80:83], v[176:179], 0
	v_mfma_f32_16x16x32_bf16 v[132:135], v[64:67], v[184:187], 0
	v_mfma_f32_16x16x32_bf16 v[128:131], v[80:83], v[184:187], 0
	v_mfma_f32_16x16x32_bf16 v[108:111], v[64:67], v[194:197], 0
	v_mfma_f32_16x16x32_bf16 v[104:107], v[80:83], v[194:197], 0
	v_mfma_f32_16x16x32_bf16 v[100:103], v[64:67], v[204:207], 0
	v_mfma_f32_16x16x32_bf16 v[96:99], v[80:83], v[204:207], 0
	v_mfma_f32_16x16x32_bf16 v[140:143], v[68:71], v[180:183], v[140:143]
	v_mfma_f32_16x16x32_bf16 v[136:139], v[92:95], v[180:183], v[136:139]
	v_mfma_f32_16x16x32_bf16 v[132:135], v[68:71], v[188:191], v[132:135]
	v_mfma_f32_16x16x32_bf16 v[128:131], v[92:95], v[188:191], v[128:131]
	v_mfma_f32_16x16x32_bf16 v[108:111], v[68:71], v[198:201], v[108:111]
	v_mfma_f32_16x16x32_bf16 v[104:107], v[92:95], v[198:201], v[104:107]
	v_mfma_f32_16x16x32_bf16 v[100:103], v[68:71], v[208:211], v[100:103]
	v_mfma_f32_16x16x32_bf16 v[96:99], v[92:95], v[208:211], v[96:99]
	v_mfma_f32_16x16x32_bf16 v[124:127], v[160:163], v[176:179], 0
	v_mfma_f32_16x16x32_bf16 v[120:123], v[168:171], v[176:179], 0
	v_mfma_f32_16x16x32_bf16 v[116:119], v[160:163], v[184:187], 0
	v_mfma_f32_16x16x32_bf16 v[112:115], v[168:171], v[184:187], 0
	v_mfma_f32_16x16x32_bf16 v[88:91], v[160:163], v[194:197], 0
	v_mfma_f32_16x16x32_bf16 v[84:87], v[168:171], v[194:197], 0
	v_mfma_f32_16x16x32_bf16 v[76:79], v[160:163], v[204:207], 0
	v_mfma_f32_16x16x32_bf16 v[72:75], v[168:171], v[204:207], 0
	v_mfma_f32_16x16x32_bf16 v[124:127], v[164:167], v[180:183], v[124:127]
	v_mfma_f32_16x16x32_bf16 v[120:123], v[172:175], v[180:183], v[120:123]
	v_mfma_f32_16x16x32_bf16 v[116:119], v[164:167], v[188:191], v[116:119]
	v_mfma_f32_16x16x32_bf16 v[112:115], v[172:175], v[188:191], v[112:115]
	v_mfma_f32_16x16x32_bf16 v[88:91], v[164:167], v[198:201], v[88:91]
	v_mfma_f32_16x16x32_bf16 v[84:87], v[172:175], v[198:201], v[84:87]
	v_mfma_f32_16x16x32_bf16 v[76:79], v[164:167], v[208:211], v[76:79]
	v_mfma_f32_16x16x32_bf16 v[72:75], v[172:175], v[208:211], v[72:75]
	s_barrier
	s_add_i32 s16, s43, s39
	v_lshl_add_u64 v[154:155], s[20:21], 0, v[192:193]
	s_mov_b32 m0, s16
	ds_read_b128 v[176:179], v159 offset:16384
	ds_read_b128 v[180:183], v159 offset:17408
	ds_read_b128 v[184:187], v159 offset:18432
	ds_read_b128 v[188:191], v159 offset:19456
	ds_read_b128 v[194:197], v159 offset:20480
	ds_read_b128 v[198:201], v159 offset:21504
	ds_read_b128 v[204:207], v159 offset:22528
	ds_read_b128 v[208:211], v159 offset:23552
	global_load_lds_dwordx4 v[154:155], off
	s_add_i32 m0, s16, 0x2000
	s_add_u32 s16, s20, 0xb0000
	v_lshl_add_u64 v[212:213], s[20:21], 0, v[144:145]
	s_addc_u32 s17, s21, 0
	s_add_i32 s43, s44, s39
	global_load_lds_dwordx4 v[212:213], off
	v_lshl_add_u64 v[214:215], s[16:17], 0, v[192:193]
	s_mov_b32 m0, s43
	v_lshl_add_u64 v[216:217], s[22:23], 0, v[146:147]
	global_load_lds_dwordx4 v[214:215], off
	v_lshl_add_u64 v[214:215], s[16:17], 0, v[144:145]
	s_add_i32 m0, s43, 0x2000
	s_nop 0
	global_load_lds_dwordx4 v[214:215], off
	v_lshl_add_u64 v[214:215], s[22:23], 0, v[148:149]
	s_mov_b32 m0, s40
	s_nop 0
	global_load_lds_dwordx4 v[214:215], off
	s_mov_b32 m0, s73
	s_nop 0
	global_load_lds_dwordx4 v[216:217], off
	s_waitcnt vmcnt(8)
	s_waitcnt lgkmcnt(0)
	s_barrier
; #define PG8_STAGE(bufoff, gbase, voff) do { _Pragma("unroll") for (int _i = 0; _i < 2; ++_i) \
;         __builtin_amdgcn_global_load_lds((const unsigned*)((const char*)(gbase) + (voff)[_i]), (LAS unsigned*)(lds + (bufoff) + ldsw + _i * 8192), 16, 0, 0); } while (0)
; #define PG8_LDA(dst, b, h) do { _Pragma("unroll") for (int m = 0; m < 4; ++m) _Pragma("unroll") for (int k = 0; k < 2; ++k) dst[m][k] = *(const LAS bf16x8*)(lds + PG8_SA(b, h) + aoff + m * 2048 + k * 1024); } while (0)
; #define PG8_LDB(dst, b, h) do { _Pragma("unroll") for (int n = 0; n < 2; ++n) _Pragma("unroll") for (int k = 0; k < 2; ++k) dst[n][k] = *(const LAS bf16x8*)(lds + PG8_SB(b, h) + boff + n * 2048 + k * 1024); } while (0)
; #define PG8_MMA(ai, bj, At, Bt) do { __builtin_amdgcn_s_setprio(1); _Pragma("unroll") for (int m = 0; m < 4; ++m) _Pragma("unroll") for (int n = 0; n < 2; ++n) _Pragma("unroll") for (int k = 0; k < 2; ++k) \
;         acc[ai][bj][m][n] = __builtin_amdgcn_mfma_f32_16x16x32_bf16(Bt[n][k], At[m][k], acc[ai][bj][m][n], 0, 0, 0); __builtin_amdgcn_s_setprio(0); } while (0)
; #define PG8_WAIT_V(n) asm volatile("s_waitcnt vmcnt(" #n ")" ::: "memory")
; #define PG8_WAIT_L(n) asm volatile("s_waitcnt lgkmcnt(" #n ")" ::: "memory")
; #define PG8_BAR __builtin_amdgcn_s_barrier()
; #define PG8_SCHED __builtin_amdgcn_sched_barrier(0)
; template <class Epi>
; __device__ __forceinline__ void gemm_phase(LAS unsigned char* lds, const Gemm g, const Sched& S, const Epi& E, const int tid) {
;     ...
;             PG8_WAIT_V(8); PG8_WAIT_L(0); PG8_BAR; PG8_MMA(1, 0, At, B0); PG8_MMA(1, 1, At, B1); PG8_BAR; PG8_SCHED;
;             PG8_LDB(B0, 1, 0); PG8_LDB(B1, 1, 1); PG8_SCHED; PG8_LDA(At, 1, 0); PG8_STAGE(PG8_SA(0, 1), a2 + hA, voffA);
;             PG8_WAIT_V(8); PG8_WAIT_L(0); PG8_BAR; PG8_MMA(0, 0, At, B0); PG8_MMA(0, 1, At, B1); PG8_BAR; PG8_SCHED;
	s_waitcnt lgkmcnt(0)
	v_mfma_f32_16x16x32_bf16 v[60:63], v[64:67], v[176:179], 0
	v_mfma_f32_16x16x32_bf16 v[56:59], v[80:83], v[176:179], 0
	v_mfma_f32_16x16x32_bf16 v[52:55], v[64:67], v[184:187], 0
	v_mfma_f32_16x16x32_bf16 v[48:51], v[80:83], v[184:187], 0
	v_mfma_f32_16x16x32_bf16 v[28:31], v[64:67], v[194:197], 0
	v_mfma_f32_16x16x32_bf16 v[24:27], v[80:83], v[194:197], 0
	v_mfma_f32_16x16x32_bf16 v[16:19], v[64:67], v[204:207], 0
	v_mfma_f32_16x16x32_bf16 v[8:11], v[80:83], v[204:207], 0
	v_mfma_f32_16x16x32_bf16 v[60:63], v[68:71], v[180:183], v[60:63]
	v_mfma_f32_16x16x32_bf16 v[56:59], v[92:95], v[180:183], v[56:59]
	v_mfma_f32_16x16x32_bf16 v[52:55], v[68:71], v[188:191], v[52:55]
	v_mfma_f32_16x16x32_bf16 v[48:51], v[92:95], v[188:191], v[48:51]
	v_mfma_f32_16x16x32_bf16 v[28:31], v[68:71], v[198:201], v[28:31]
	v_mfma_f32_16x16x32_bf16 v[24:27], v[92:95], v[198:201], v[24:27]
	v_mfma_f32_16x16x32_bf16 v[16:19], v[68:71], v[208:211], v[16:19]
	v_mfma_f32_16x16x32_bf16 v[8:11], v[92:95], v[208:211], v[8:11]
	v_mfma_f32_16x16x32_bf16 v[44:47], v[160:163], v[176:179], 0
	v_mfma_f32_16x16x32_bf16 v[40:43], v[168:171], v[176:179], 0
	v_mfma_f32_16x16x32_bf16 v[36:39], v[160:163], v[184:187], 0
	v_mfma_f32_16x16x32_bf16 v[32:35], v[168:171], v[184:187], 0
	v_mfma_f32_16x16x32_bf16 v[20:23], v[160:163], v[194:197], 0
	v_mfma_f32_16x16x32_bf16 v[12:15], v[168:171], v[194:197], 0
	v_mfma_f32_16x16x32_bf16 v[4:7], v[160:163], v[204:207], 0
	v_mfma_f32_16x16x32_bf16 v[0:3], v[168:171], v[204:207], 0
	v_mfma_f32_16x16x32_bf16 v[44:47], v[164:167], v[180:183], v[44:47]
	v_mfma_f32_16x16x32_bf16 v[40:43], v[172:175], v[180:183], v[40:43]
	v_mfma_f32_16x16x32_bf16 v[36:39], v[164:167], v[188:191], v[36:39]
	v_mfma_f32_16x16x32_bf16 v[32:35], v[172:175], v[188:191], v[32:35]
	v_mfma_f32_16x16x32_bf16 v[20:23], v[164:167], v[198:201], v[20:23]
	v_mfma_f32_16x16x32_bf16 v[12:15], v[172:175], v[198:201], v[12:15]
	v_mfma_f32_16x16x32_bf16 v[4:7], v[164:167], v[208:211], v[4:7]
	v_mfma_f32_16x16x32_bf16 v[0:3], v[172:175], v[208:211], v[0:3]
	s_barrier
	s_add_i32 s43, 0, 0x18000
	s_add_i32 s44, 0, 0x1c000
	v_add_u32_e32 v92, s43, v157
	v_add_u32_e32 v172, s44, v157
	ds_read_b128 v[64:67], v92
	ds_read_b128 v[68:71], v92 offset:1024
	ds_read_b128 v[80:83], v92 offset:2048
	ds_read_b128 v[92:95], v92 offset:3072
	ds_read_b128 v[160:163], v172
	ds_read_b128 v[164:167], v172 offset:1024
	ds_read_b128 v[168:171], v172 offset:2048
	ds_read_b128 v[172:175], v172 offset:3072
	s_add_u32 s16, s22, 0xb0000
	s_addc_u32 s17, s23, 0
	s_mov_b32 m0, s74
	v_lshl_add_u64 v[218:219], s[16:17], 0, v[148:149]
	ds_read_b128 v[176:179], v159 offset:32768
	ds_read_b128 v[180:183], v159 offset:33792
	ds_read_b128 v[184:187], v159 offset:34816
	ds_read_b128 v[188:191], v159 offset:35840
	ds_read_b128 v[194:197], v159 offset:36864
	ds_read_b128 v[198:201], v159 offset:37888
	ds_read_b128 v[204:207], v159 offset:38912
	ds_read_b128 v[208:211], v159 offset:39936
	global_load_lds_dwordx4 v[218:219], off
	v_lshl_add_u64 v[218:219], s[16:17], 0, v[146:147]
	s_mov_b32 m0, s75
	s_nop 0
	global_load_lds_dwordx4 v[218:219], off
	s_waitcnt vmcnt(8)
	s_waitcnt lgkmcnt(0)
	s_barrier
	s_waitcnt lgkmcnt(0)
	v_mfma_f32_16x16x32_bf16 v[140:143], v[64:67], v[176:179], v[140:143]
	v_mfma_f32_16x16x32_bf16 v[136:139], v[80:83], v[176:179], v[136:139]
	v_mfma_f32_16x16x32_bf16 v[132:135], v[64:67], v[184:187], v[132:135]
	v_mfma_f32_16x16x32_bf16 v[128:131], v[80:83], v[184:187], v[128:131]
	v_mfma_f32_16x16x32_bf16 v[108:111], v[64:67], v[194:197], v[108:111]
	v_mfma_f32_16x16x32_bf16 v[104:107], v[80:83], v[194:197], v[104:107]
	v_mfma_f32_16x16x32_bf16 v[100:103], v[64:67], v[204:207], v[100:103]
	v_mfma_f32_16x16x32_bf16 v[96:99], v[80:83], v[204:207], v[96:99]
	v_mfma_f32_16x16x32_bf16 v[140:143], v[68:71], v[180:183], v[140:143]
	v_mfma_f32_16x16x32_bf16 v[136:139], v[92:95], v[180:183], v[136:139]
	v_mfma_f32_16x16x32_bf16 v[132:135], v[68:71], v[188:191], v[132:135]
	v_mfma_f32_16x16x32_bf16 v[128:131], v[92:95], v[188:191], v[128:131]
	v_mfma_f32_16x16x32_bf16 v[108:111], v[68:71], v[198:201], v[108:111]
	v_mfma_f32_16x16x32_bf16 v[104:107], v[92:95], v[198:201], v[104:107]
	v_mfma_f32_16x16x32_bf16 v[100:103], v[68:71], v[208:211], v[100:103]
	v_mfma_f32_16x16x32_bf16 v[96:99], v[92:95], v[208:211], v[96:99]
	v_mfma_f32_16x16x32_bf16 v[124:127], v[160:163], v[176:179], v[124:127]
	v_mfma_f32_16x16x32_bf16 v[120:123], v[168:171], v[176:179], v[120:123]
	v_mfma_f32_16x16x32_bf16 v[116:119], v[160:163], v[184:187], v[116:119]
	v_mfma_f32_16x16x32_bf16 v[112:115], v[168:171], v[184:187], v[112:115]
	v_mfma_f32_16x16x32_bf16 v[88:91], v[160:163], v[194:197], v[88:91]
	v_mfma_f32_16x16x32_bf16 v[84:87], v[168:171], v[194:197], v[84:87]
	v_mfma_f32_16x16x32_bf16 v[76:79], v[160:163], v[204:207], v[76:79]
	v_mfma_f32_16x16x32_bf16 v[72:75], v[168:171], v[204:207], v[72:75]
	v_mfma_f32_16x16x32_bf16 v[124:127], v[164:167], v[180:183], v[124:127]
	v_mfma_f32_16x16x32_bf16 v[120:123], v[172:175], v[180:183], v[120:123]
	v_mfma_f32_16x16x32_bf16 v[116:119], v[164:167], v[188:191], v[116:119]
	v_mfma_f32_16x16x32_bf16 v[112:115], v[172:175], v[188:191], v[112:115]
	v_mfma_f32_16x16x32_bf16 v[88:91], v[164:167], v[198:201], v[88:91]
	v_mfma_f32_16x16x32_bf16 v[84:87], v[172:175], v[198:201], v[84:87]
	v_mfma_f32_16x16x32_bf16 v[76:79], v[164:167], v[208:211], v[76:79]
	v_mfma_f32_16x16x32_bf16 v[72:75], v[172:175], v[208:211], v[72:75]
	s_barrier
; #define PG8_STAGE(bufoff, gbase, voff) do { _Pragma("unroll") for (int _i = 0; _i < 2; ++_i) \
;         __builtin_amdgcn_global_load_lds((const unsigned*)((const char*)(gbase) + (voff)[_i]), (LAS unsigned*)(lds + (bufoff) + ldsw + _i * 8192), 16, 0, 0); } while (0)
; #define PG8_LDA(dst, b, h) do { _Pragma("unroll") for (int m = 0; m < 4; ++m) _Pragma("unroll") for (int k = 0; k < 2; ++k) dst[m][k] = *(const LAS bf16x8*)(lds + PG8_SA(b, h) + aoff + m * 2048 + k * 1024); } while (0)
; #define PG8_LDB(dst, b, h) do { _Pragma("unroll") for (int n = 0; n < 2; ++n) _Pragma("unroll") for (int k = 0; k < 2; ++k) dst[n][k] = *(const LAS bf16x8*)(lds + PG8_SB(b, h) + boff + n * 2048 + k * 1024); } while (0)
; #define PG8_WAIT_V(n) asm volatile("s_waitcnt vmcnt(" #n ")" ::: "memory")
; #define PG8_WAIT_L(n) asm volatile("s_waitcnt lgkmcnt(" #n ")" ::: "memory")
; template <class Epi>
; __device__ __forceinline__ void gemm_phase(LAS unsigned char* lds, const Gemm g, const Sched& S, const Epi& E, const int tid) {
;     ...
;         for (int t = 0; t < nt; t += 2) {
;             const bool last = (t == nt - 2);
;             const char* a1 = cA + (size_t)(t + 1) * kstep;
;             const char* a2 = last ? nA : cA + (size_t)(t + 2) * kstep; const char* b2 = last ? nB : cB + (size_t)(t + 2) * kstep;
;             const char* a3 = a2 + kstep; const char* b3 = b2 + kstep;
;             PG8_LDB(B0, 0, 0); PG8_LDB(B1, 0, 1); PG8_SCHED; PG8_LDA(At, 0, 0); PG8_STAGE(PG8_SA(1, 1), a1 + hA, voffA);
;             PG8_WAIT_V(8); PG8_WAIT_L(0); PG8_BAR; PG8_MMA(0, 0, At, B0); PG8_MMA(0, 1, At, B1); PG8_BAR; PG8_SCHED;
;             PG8_LDA(At, 0, 1); PG8_STAGE(PG8_SB(0, 0), b2, voffB); PG8_STAGE(PG8_SB(0, 1), b2 + hB, voffB); PG8_STAGE(PG8_SA(0, 0), a2, voffA);
;             PG8_WAIT_V(8); PG8_WAIT_L(0); PG8_BAR; PG8_MMA(1, 0, At, B0); PG8_MMA(1, 1, At, B1); PG8_BAR; PG8_SCHED;
;             PG8_LDB(B0, 1, 0); PG8_LDB(B1, 1, 1); PG8_SCHED; PG8_LDA(At, 1, 0); PG8_STAGE(PG8_SA(0, 1), a2 + hA, voffA);
;             PG8_WAIT_V(8); PG8_WAIT_L(0); PG8_BAR; PG8_MMA(0, 0, At, B0); PG8_MMA(0, 1, At, B1); PG8_BAR; PG8_SCHED;
;             PG8_LDA(At, 1, 1); PG8_STAGE(PG8_SB(1, 0), b3, voffB); PG8_STAGE(PG8_SB(1, 1), b3 + hB, voffB); PG8_STAGE(PG8_SA(1, 0), a3, voffA);
;             PG8_WAIT_V(8); PG8_WAIT_L(0); PG8_BAR; PG8_MMA(1, 0, At, B0); PG8_MMA(1, 1, At, B1); PG8_BAR; PG8_SCHED;
	s_add_i32 s16, s43, s39
	v_lshl_add_u64 v[154:155], v[154:155], 0, s[94:95]
	s_mov_b32 m0, s16
	ds_read_b128 v[176:179], v159 offset:49152
	ds_read_b128 v[180:183], v159 offset:50176
	ds_read_b128 v[184:187], v159 offset:51200
	ds_read_b128 v[188:191], v159 offset:52224
	ds_read_b128 v[194:197], v159 offset:53248
	ds_read_b128 v[198:201], v159 offset:54272
	ds_read_b128 v[204:207], v159 offset:55296
	ds_read_b128 v[208:211], v159 offset:56320
	global_load_lds_dwordx4 v[154:155], off
	s_add_i32 m0, s16, 0x2000
	s_add_u32 s16, s20, 0xb0080
	v_lshl_add_u64 v[154:155], v[212:213], 0, s[94:95]
	s_addc_u32 s17, s21, 0
	s_add_i32 s20, s44, s39
	global_load_lds_dwordx4 v[154:155], off
	v_lshl_add_u64 v[154:155], s[16:17], 0, v[192:193]
	s_mov_b32 m0, s20
	s_nop 0
	global_load_lds_dwordx4 v[154:155], off
	v_lshl_add_u64 v[154:155], s[16:17], 0, v[144:145]
	s_add_i32 m0, s20, 0x2000
	s_nop 0
	global_load_lds_dwordx4 v[154:155], off
	v_lshl_add_u64 v[154:155], v[214:215], 0, s[94:95]
	s_mov_b32 m0, s51
	s_nop 0
	global_load_lds_dwordx4 v[154:155], off
	v_lshl_add_u64 v[154:155], v[216:217], 0, s[94:95]
	s_mov_b32 m0, s76
	s_nop 0
	global_load_lds_dwordx4 v[154:155], off
	s_waitcnt vmcnt(8)
	s_waitcnt lgkmcnt(0)
	s_barrier
	s_waitcnt lgkmcnt(0)
	v_mfma_f32_16x16x32_bf16 v[60:63], v[64:67], v[176:179], v[60:63]
	v_mfma_f32_16x16x32_bf16 v[56:59], v[80:83], v[176:179], v[56:59]
	v_mfma_f32_16x16x32_bf16 v[52:55], v[64:67], v[184:187], v[52:55]
	v_mfma_f32_16x16x32_bf16 v[48:51], v[80:83], v[184:187], v[48:51]
	v_mfma_f32_16x16x32_bf16 v[28:31], v[64:67], v[194:197], v[28:31]
	v_mfma_f32_16x16x32_bf16 v[24:27], v[80:83], v[194:197], v[24:27]
	v_mfma_f32_16x16x32_bf16 v[16:19], v[64:67], v[204:207], v[16:19]
	v_mfma_f32_16x16x32_bf16 v[8:11], v[80:83], v[204:207], v[8:11]
	v_mfma_f32_16x16x32_bf16 v[60:63], v[68:71], v[180:183], v[60:63]
	v_mfma_f32_16x16x32_bf16 v[56:59], v[92:95], v[180:183], v[56:59]
	v_mfma_f32_16x16x32_bf16 v[52:55], v[68:71], v[188:191], v[52:55]
	v_mfma_f32_16x16x32_bf16 v[48:51], v[92:95], v[188:191], v[48:51]
	v_mfma_f32_16x16x32_bf16 v[28:31], v[68:71], v[198:201], v[28:31]
	v_mfma_f32_16x16x32_bf16 v[24:27], v[92:95], v[198:201], v[24:27]
	v_mfma_f32_16x16x32_bf16 v[16:19], v[68:71], v[208:211], v[16:19]
	v_mfma_f32_16x16x32_bf16 v[8:11], v[92:95], v[208:211], v[8:11]
	v_mfma_f32_16x16x32_bf16 v[44:47], v[160:163], v[176:179], v[44:47]
	v_mfma_f32_16x16x32_bf16 v[40:43], v[168:171], v[176:179], v[40:43]
	v_mfma_f32_16x16x32_bf16 v[36:39], v[160:163], v[184:187], v[36:39]
	v_mfma_f32_16x16x32_bf16 v[32:35], v[168:171], v[184:187], v[32:35]
	v_mfma_f32_16x16x32_bf16 v[20:23], v[160:163], v[194:197], v[20:23]
	v_mfma_f32_16x16x32_bf16 v[12:15], v[168:171], v[194:197], v[12:15]
	v_mfma_f32_16x16x32_bf16 v[4:7], v[160:163], v[204:207], v[4:7]
	v_mfma_f32_16x16x32_bf16 v[0:3], v[168:171], v[204:207], v[0:3]
	v_mfma_f32_16x16x32_bf16 v[44:47], v[164:167], v[180:183], v[44:47]
	v_mfma_f32_16x16x32_bf16 v[40:43], v[172:175], v[180:183], v[40:43]
	v_mfma_f32_16x16x32_bf16 v[36:39], v[164:167], v[188:191], v[36:39]
	v_mfma_f32_16x16x32_bf16 v[32:35], v[172:175], v[188:191], v[32:35]
	v_mfma_f32_16x16x32_bf16 v[20:23], v[164:167], v[198:201], v[20:23]
	v_mfma_f32_16x16x32_bf16 v[12:15], v[172:175], v[198:201], v[12:15]
	v_mfma_f32_16x16x32_bf16 v[4:7], v[164:167], v[208:211], v[4:7]
	v_mfma_f32_16x16x32_bf16 v[0:3], v[172:175], v[208:211], v[0:3]
	s_barrier
	s_add_i32 vcc_lo, vcc_lo, 2
	s_add_u32 s80, s80, 0x100
	s_addc_u32 s81, s81, 0
	s_cmp_gt_u32 vcc_lo, 41
	s_mov_b64 s[16:17], s[18:19]
	s_cbranch_scc1 .Lgk_exit_5
.LBB0_1411:
	s_add_u32 s18, s16, 0x100
	s_addc_u32 s19, s17, 0
	s_add_i32 s43, 0, 0x10000
	s_cmp_eq_u32 vcc_lo, 40
	s_cselect_b32 s23, s7, s19
	s_cselect_b32 s22, s6, s18
	s_cselect_b32 s21, s15, s81
	s_cselect_b32 s20, s14, s80
	s_add_i32 s44, 0, 0x14000
	v_add_u32_e32 v92, s43, v157
	v_add_u32_e32 v154, s44, v157
	ds_read_b128 v[64:67], v92
	ds_read_b128 v[68:71], v92 offset:1024
	ds_read_b128 v[80:83], v92 offset:2048
	ds_read_b128 v[92:95], v92 offset:3072
	ds_read_b128 v[160:163], v154
	ds_read_b128 v[164:167], v154 offset:1024
	ds_read_b128 v[168:171], v154 offset:2048
	ds_read_b128 v[172:175], v154 offset:3072
	v_lshl_add_u64 v[154:155], s[16:17], 0, v[150:151]
	s_add_i32 m0, s40, 0xc000
	ds_read_b128 v[176:179], v159
	ds_read_b128 v[180:183], v159 offset:1024
	ds_read_b128 v[184:187], v159 offset:2048
	ds_read_b128 v[188:191], v159 offset:3072
	ds_read_b128 v[194:197], v159 offset:4096
	ds_read_b128 v[198:201], v159 offset:5120
	ds_read_b128 v[204:207], v159 offset:6144
	ds_read_b128 v[208:211], v159 offset:7168
	global_load_lds_dwordx4 v[154:155], off
	v_lshl_add_u64 v[154:155], s[16:17], 0, v[152:153]
	s_add_i32 m0, s40, 0xe000
	s_nop 0
	global_load_lds_dwordx4 v[154:155], off
	s_waitcnt vmcnt(8)
	s_waitcnt lgkmcnt(0)
	s_barrier
; #define PG8_STAGE(bufoff, gbase, voff) do { _Pragma("unroll") for (int _i = 0; _i < 2; ++_i) \
;         __builtin_amdgcn_global_load_lds((const unsigned*)((const char*)(gbase) + (voff)[_i]), (LAS unsigned*)(lds + (bufoff) + ldsw + _i * 8192), 16, 0, 0); } while (0)
; #define PG8_LDA(dst, b, h) do { _Pragma("unroll") for (int m = 0; m < 4; ++m) _Pragma("unroll") for (int k = 0; k < 2; ++k) dst[m][k] = *(const LAS bf16x8*)(lds + PG8_SA(b, h) + aoff + m * 2048 + k * 1024); } while (0)
; #define PG8_MMA(ai, bj, At, Bt) do { __builtin_amdgcn_s_setprio(1); _Pragma("unroll") for (int m = 0; m < 4; ++m) _Pragma("unroll") for (int n = 0; n < 2; ++n) _Pragma("unroll") for (int k = 0; k < 2; ++k) \
;         acc[ai][bj][m][n] = __builtin_amdgcn_mfma_f32_16x16x32_bf16(Bt[n][k], At[m][k], acc[ai][bj][m][n], 0, 0, 0); __builtin_amdgcn_s_setprio(0); } while (0)
; #define PG8_WAIT_V(n) asm volatile("s_waitcnt vmcnt(" #n ")" ::: "memory")
; #define PG8_WAIT_L(n) asm volatile("s_waitcnt lgkmcnt(" #n ")" ::: "memory")
; #define PG8_BAR __builtin_amdgcn_s_barrier()
; #define PG8_SCHED __builtin_amdgcn_sched_barrier(0)
; template <class Epi>
; __device__ __forceinline__ void gemm_phase(LAS unsigned char* lds, const Gemm g, const Sched& S, const Epi& E, const int tid) {
;     ...
;             PG8_WAIT_V(8); PG8_WAIT_L(0); PG8_BAR; PG8_MMA(0, 0, At, B0); PG8_MMA(0, 1, At, B1); PG8_BAR; PG8_SCHED;
;             PG8_LDA(At, 0, 1); PG8_STAGE(PG8_SB(0, 0), b2, voffB); PG8_STAGE(PG8_SB(0, 1), b2 + hB, voffB); PG8_STAGE(PG8_SA(0, 0), a2, voffA);
;             PG8_WAIT_V(8); PG8_WAIT_L(0); PG8_BAR; PG8_MMA(1, 0, At, B0); PG8_MMA(1, 1, At, B1); PG8_BAR; PG8_SCHED;
	s_waitcnt lgkmcnt(0)
	v_mfma_f32_16x16x32_bf16 v[140:143], v[64:67], v[176:179], v[140:143]
	v_mfma_f32_16x16x32_bf16 v[136:139], v[80:83], v[176:179], v[136:139]
	v_mfma_f32_16x16x32_bf16 v[132:135], v[64:67], v[184:187], v[132:135]
	v_mfma_f32_16x16x32_bf16 v[128:131], v[80:83], v[184:187], v[128:131]
	v_mfma_f32_16x16x32_bf16 v[108:111], v[64:67], v[194:197], v[108:111]
	v_mfma_f32_16x16x32_bf16 v[104:107], v[80:83], v[194:197], v[104:107]
	v_mfma_f32_16x16x32_bf16 v[100:103], v[64:67], v[204:207], v[100:103]
	v_mfma_f32_16x16x32_bf16 v[96:99], v[80:83], v[204:207], v[96:99]
	v_mfma_f32_16x16x32_bf16 v[140:143], v[68:71], v[180:183], v[140:143]
	v_mfma_f32_16x16x32_bf16 v[136:139], v[92:95], v[180:183], v[136:139]
	v_mfma_f32_16x16x32_bf16 v[132:135], v[68:71], v[188:191], v[132:135]
	v_mfma_f32_16x16x32_bf16 v[128:131], v[92:95], v[188:191], v[128:131]
	v_mfma_f32_16x16x32_bf16 v[108:111], v[68:71], v[198:201], v[108:111]
	v_mfma_f32_16x16x32_bf16 v[104:107], v[92:95], v[198:201], v[104:107]
	v_mfma_f32_16x16x32_bf16 v[100:103], v[68:71], v[208:211], v[100:103]
	v_mfma_f32_16x16x32_bf16 v[96:99], v[92:95], v[208:211], v[96:99]
	v_mfma_f32_16x16x32_bf16 v[124:127], v[160:163], v[176:179], v[124:127]
	v_mfma_f32_16x16x32_bf16 v[120:123], v[168:171], v[176:179], v[120:123]
	v_mfma_f32_16x16x32_bf16 v[116:119], v[160:163], v[184:187], v[116:119]
	v_mfma_f32_16x16x32_bf16 v[112:115], v[168:171], v[184:187], v[112:115]
	v_mfma_f32_16x16x32_bf16 v[88:91], v[160:163], v[194:197], v[88:91]
	v_mfma_f32_16x16x32_bf16 v[84:87], v[168:171], v[194:197], v[84:87]
	v_mfma_f32_16x16x32_bf16 v[76:79], v[160:163], v[204:207], v[76:79]
	v_mfma_f32_16x16x32_bf16 v[72:75], v[168:171], v[204:207], v[72:75]
	v_mfma_f32_16x16x32_bf16 v[124:127], v[164:167], v[180:183], v[124:127]
	v_mfma_f32_16x16x32_bf16 v[120:123], v[172:175], v[180:183], v[120:123]
	v_mfma_f32_16x16x32_bf16 v[116:119], v[164:167], v[188:191], v[116:119]
	v_mfma_f32_16x16x32_bf16 v[112:115], v[172:175], v[188:191], v[112:115]
	v_mfma_f32_16x16x32_bf16 v[88:91], v[164:167], v[198:201], v[88:91]
	v_mfma_f32_16x16x32_bf16 v[84:87], v[172:175], v[198:201], v[84:87]
	v_mfma_f32_16x16x32_bf16 v[76:79], v[164:167], v[208:211], v[76:79]
	v_mfma_f32_16x16x32_bf16 v[72:75], v[172:175], v[208:211], v[72:75]
	s_barrier
	s_add_i32 s16, s43, s39
	v_lshl_add_u64 v[154:155], s[20:21], 0, v[192:193]
	s_mov_b32 m0, s16
	ds_read_b128 v[176:179], v159 offset:16384
	ds_read_b128 v[180:183], v159 offset:17408
	ds_read_b128 v[184:187], v159 offset:18432
	ds_read_b128 v[188:191], v159 offset:19456
	ds_read_b128 v[194:197], v159 offset:20480
	ds_read_b128 v[198:201], v159 offset:21504
	ds_read_b128 v[204:207], v159 offset:22528
	ds_read_b128 v[208:211], v159 offset:23552
	global_load_lds_dwordx4 v[154:155], off
	s_add_i32 m0, s16, 0x2000
	s_add_u32 s16, s20, 0xb0000
	v_lshl_add_u64 v[212:213], s[20:21], 0, v[144:145]
	s_addc_u32 s17, s21, 0
	s_add_i32 s43, s44, s39
	global_load_lds_dwordx4 v[212:213], off
	v_lshl_add_u64 v[214:215], s[16:17], 0, v[192:193]
	s_mov_b32 m0, s43
	v_lshl_add_u64 v[216:217], s[22:23], 0, v[146:147]
	global_load_lds_dwordx4 v[214:215], off
	v_lshl_add_u64 v[214:215], s[16:17], 0, v[144:145]
	s_add_i32 m0, s43, 0x2000
	s_nop 0
	global_load_lds_dwordx4 v[214:215], off
	v_lshl_add_u64 v[214:215], s[22:23], 0, v[148:149]
	s_mov_b32 m0, s40
	s_nop 0
	global_load_lds_dwordx4 v[214:215], off
	s_mov_b32 m0, s73
	s_nop 0
	global_load_lds_dwordx4 v[216:217], off
	s_waitcnt vmcnt(8)
	s_waitcnt lgkmcnt(0)
	s_barrier
	s_waitcnt lgkmcnt(0)
	v_mfma_f32_16x16x32_bf16 v[60:63], v[64:67], v[176:179], v[60:63]
	v_mfma_f32_16x16x32_bf16 v[56:59], v[80:83], v[176:179], v[56:59]
	v_mfma_f32_16x16x32_bf16 v[52:55], v[64:67], v[184:187], v[52:55]
	v_mfma_f32_16x16x32_bf16 v[48:51], v[80:83], v[184:187], v[48:51]
	v_mfma_f32_16x16x32_bf16 v[28:31], v[64:67], v[194:197], v[28:31]
	v_mfma_f32_16x16x32_bf16 v[24:27], v[80:83], v[194:197], v[24:27]
	v_mfma_f32_16x16x32_bf16 v[16:19], v[64:67], v[204:207], v[16:19]
	v_mfma_f32_16x16x32_bf16 v[8:11], v[80:83], v[204:207], v[8:11]
	v_mfma_f32_16x16x32_bf16 v[60:63], v[68:71], v[180:183], v[60:63]
	v_mfma_f32_16x16x32_bf16 v[56:59], v[92:95], v[180:183], v[56:59]
	v_mfma_f32_16x16x32_bf16 v[52:55], v[68:71], v[188:191], v[52:55]
	v_mfma_f32_16x16x32_bf16 v[48:51], v[92:95], v[188:191], v[48:51]
	v_mfma_f32_16x16x32_bf16 v[28:31], v[68:71], v[198:201], v[28:31]
	v_mfma_f32_16x16x32_bf16 v[24:27], v[92:95], v[198:201], v[24:27]
	v_mfma_f32_16x16x32_bf16 v[16:19], v[68:71], v[208:211], v[16:19]
	v_mfma_f32_16x16x32_bf16 v[8:11], v[92:95], v[208:211], v[8:11]
	v_mfma_f32_16x16x32_bf16 v[44:47], v[160:163], v[176:179], v[44:47]
	v_mfma_f32_16x16x32_bf16 v[40:43], v[168:171], v[176:179], v[40:43]
	v_mfma_f32_16x16x32_bf16 v[36:39], v[160:163], v[184:187], v[36:39]
	v_mfma_f32_16x16x32_bf16 v[32:35], v[168:171], v[184:187], v[32:35]
	v_mfma_f32_16x16x32_bf16 v[20:23], v[160:163], v[194:197], v[20:23]
	v_mfma_f32_16x16x32_bf16 v[12:15], v[168:171], v[194:197], v[12:15]
	v_mfma_f32_16x16x32_bf16 v[4:7], v[160:163], v[204:207], v[4:7]
	v_mfma_f32_16x16x32_bf16 v[0:3], v[168:171], v[204:207], v[0:3]
	v_mfma_f32_16x16x32_bf16 v[44:47], v[164:167], v[180:183], v[44:47]
	v_mfma_f32_16x16x32_bf16 v[40:43], v[172:175], v[180:183], v[40:43]
	v_mfma_f32_16x16x32_bf16 v[36:39], v[164:167], v[188:191], v[36:39]
	v_mfma_f32_16x16x32_bf16 v[32:35], v[172:175], v[188:191], v[32:35]
	v_mfma_f32_16x16x32_bf16 v[20:23], v[164:167], v[198:201], v[20:23]
	v_mfma_f32_16x16x32_bf16 v[12:15], v[172:175], v[198:201], v[12:15]
	v_mfma_f32_16x16x32_bf16 v[4:7], v[164:167], v[208:211], v[4:7]
	v_mfma_f32_16x16x32_bf16 v[0:3], v[172:175], v[208:211], v[0:3]
	s_barrier
; #define PG8_STAGE(bufoff, gbase, voff) do { _Pragma("unroll") for (int _i = 0; _i < 2; ++_i) \
;         __builtin_amdgcn_global_load_lds((const unsigned*)((const char*)(gbase) + (voff)[_i]), (LAS unsigned*)(lds + (bufoff) + ldsw + _i * 8192), 16, 0, 0); } while (0)
; #define PG8_LDA(dst, b, h) do { _Pragma("unroll") for (int m = 0; m < 4; ++m) _Pragma("unroll") for (int k = 0; k < 2; ++k) dst[m][k] = *(const LAS bf16x8*)(lds + PG8_SA(b, h) + aoff + m * 2048 + k * 1024); } while (0)
; #define PG8_LDB(dst, b, h) do { _Pragma("unroll") for (int n = 0; n < 2; ++n) _Pragma("unroll") for (int k = 0; k < 2; ++k) dst[n][k] = *(const LAS bf16x8*)(lds + PG8_SB(b, h) + boff + n * 2048 + k * 1024); } while (0)
; #define PG8_MMA(ai, bj, At, Bt) do { __builtin_amdgcn_s_setprio(1); _Pragma("unroll") for (int m = 0; m < 4; ++m) _Pragma("unroll") for (int n = 0; n < 2; ++n) _Pragma("unroll") for (int k = 0; k < 2; ++k) \
;         acc[ai][bj][m][n] = __builtin_amdgcn_mfma_f32_16x16x32_bf16(Bt[n][k], At[m][k], acc[ai][bj][m][n], 0, 0, 0); __builtin_amdgcn_s_setprio(0); } while (0)
; #define PG8_WAIT_V(n) asm volatile("s_waitcnt vmcnt(" #n ")" ::: "memory")
; #define PG8_WAIT_L(n) asm volatile("s_waitcnt lgkmcnt(" #n ")" ::: "memory")
; #define PG8_BAR __builtin_amdgcn_s_barrier()
; #define PG8_SCHED __builtin_amdgcn_sched_barrier(0)
; template <class Epi>
; __device__ __forceinline__ void gemm_phase(LAS unsigned char* lds, const Gemm g, const Sched& S, const Epi& E, const int tid) {
;     ...
;             PG8_LDB(B0, 1, 0); PG8_LDB(B1, 1, 1); PG8_SCHED; PG8_LDA(At, 1, 0); PG8_STAGE(PG8_SA(0, 1), a2 + hA, voffA);
;             PG8_WAIT_V(8); PG8_WAIT_L(0); PG8_BAR; PG8_MMA(0, 0, At, B0); PG8_MMA(0, 1, At, B1); PG8_BAR; PG8_SCHED;
;             PG8_LDA(At, 1, 1); PG8_STAGE(PG8_SB(1, 0), b3, voffB); PG8_STAGE(PG8_SB(1, 1), b3 + hB, voffB); PG8_STAGE(PG8_SA(1, 0), a3, voffA);
;             PG8_WAIT_V(8); PG8_WAIT_L(0); PG8_BAR; PG8_MMA(1, 0, At, B0); PG8_MMA(1, 1, At, B1); PG8_BAR; PG8_SCHED;
	s_add_i32 s43, 0, 0x18000
	s_add_i32 s44, 0, 0x1c000
	v_add_u32_e32 v92, s43, v157
	v_add_u32_e32 v172, s44, v157
	ds_read_b128 v[64:67], v92
	ds_read_b128 v[68:71], v92 offset:1024
	ds_read_b128 v[80:83], v92 offset:2048
	ds_read_b128 v[92:95], v92 offset:3072
	ds_read_b128 v[160:163], v172
	ds_read_b128 v[164:167], v172 offset:1024
	ds_read_b128 v[168:171], v172 offset:2048
	ds_read_b128 v[172:175], v172 offset:3072
	s_add_u32 s16, s22, 0xb0000
	s_addc_u32 s17, s23, 0
	s_mov_b32 m0, s74
	v_lshl_add_u64 v[218:219], s[16:17], 0, v[148:149]
	ds_read_b128 v[176:179], v159 offset:32768
	ds_read_b128 v[180:183], v159 offset:33792
	ds_read_b128 v[184:187], v159 offset:34816
	ds_read_b128 v[188:191], v159 offset:35840
	ds_read_b128 v[194:197], v159 offset:36864
	ds_read_b128 v[198:201], v159 offset:37888
	ds_read_b128 v[204:207], v159 offset:38912
	ds_read_b128 v[208:211], v159 offset:39936
	global_load_lds_dwordx4 v[218:219], off
	v_lshl_add_u64 v[218:219], s[16:17], 0, v[146:147]
	s_mov_b32 m0, s75
	s_nop 0
	global_load_lds_dwordx4 v[218:219], off
	s_waitcnt vmcnt(8)
	s_waitcnt lgkmcnt(0)
	s_barrier
	s_waitcnt lgkmcnt(0)
	v_mfma_f32_16x16x32_bf16 v[140:143], v[64:67], v[176:179], v[140:143]
	v_mfma_f32_16x16x32_bf16 v[136:139], v[80:83], v[176:179], v[136:139]
	v_mfma_f32_16x16x32_bf16 v[132:135], v[64:67], v[184:187], v[132:135]
	v_mfma_f32_16x16x32_bf16 v[128:131], v[80:83], v[184:187], v[128:131]
	v_mfma_f32_16x16x32_bf16 v[108:111], v[64:67], v[194:197], v[108:111]
	v_mfma_f32_16x16x32_bf16 v[104:107], v[80:83], v[194:197], v[104:107]
	v_mfma_f32_16x16x32_bf16 v[100:103], v[64:67], v[204:207], v[100:103]
	v_mfma_f32_16x16x32_bf16 v[96:99], v[80:83], v[204:207], v[96:99]
	v_mfma_f32_16x16x32_bf16 v[140:143], v[68:71], v[180:183], v[140:143]
	v_mfma_f32_16x16x32_bf16 v[136:139], v[92:95], v[180:183], v[136:139]
	v_mfma_f32_16x16x32_bf16 v[132:135], v[68:71], v[188:191], v[132:135]
	v_mfma_f32_16x16x32_bf16 v[128:131], v[92:95], v[188:191], v[128:131]
	v_mfma_f32_16x16x32_bf16 v[108:111], v[68:71], v[198:201], v[108:111]
	v_mfma_f32_16x16x32_bf16 v[104:107], v[92:95], v[198:201], v[104:107]
	v_mfma_f32_16x16x32_bf16 v[100:103], v[68:71], v[208:211], v[100:103]
	v_mfma_f32_16x16x32_bf16 v[96:99], v[92:95], v[208:211], v[96:99]
	v_mfma_f32_16x16x32_bf16 v[124:127], v[160:163], v[176:179], v[124:127]
	v_mfma_f32_16x16x32_bf16 v[120:123], v[168:171], v[176:179], v[120:123]
	v_mfma_f32_16x16x32_bf16 v[116:119], v[160:163], v[184:187], v[116:119]
	v_mfma_f32_16x16x32_bf16 v[112:115], v[168:171], v[184:187], v[112:115]
	v_mfma_f32_16x16x32_bf16 v[88:91], v[160:163], v[194:197], v[88:91]
	v_mfma_f32_16x16x32_bf16 v[84:87], v[168:171], v[194:197], v[84:87]
	v_mfma_f32_16x16x32_bf16 v[76:79], v[160:163], v[204:207], v[76:79]
	v_mfma_f32_16x16x32_bf16 v[72:75], v[168:171], v[204:207], v[72:75]
	v_mfma_f32_16x16x32_bf16 v[124:127], v[164:167], v[180:183], v[124:127]
	v_mfma_f32_16x16x32_bf16 v[120:123], v[172:175], v[180:183], v[120:123]
	v_mfma_f32_16x16x32_bf16 v[116:119], v[164:167], v[188:191], v[116:119]
	v_mfma_f32_16x16x32_bf16 v[112:115], v[172:175], v[188:191], v[112:115]
	v_mfma_f32_16x16x32_bf16 v[88:91], v[164:167], v[198:201], v[88:91]
	v_mfma_f32_16x16x32_bf16 v[84:87], v[172:175], v[198:201], v[84:87]
	v_mfma_f32_16x16x32_bf16 v[76:79], v[164:167], v[208:211], v[76:79]
	v_mfma_f32_16x16x32_bf16 v[72:75], v[172:175], v[208:211], v[72:75]
	s_barrier
	s_add_i32 s16, s43, s39
	v_lshl_add_u64 v[154:155], v[154:155], 0, s[94:95]
	s_mov_b32 m0, s16
	ds_read_b128 v[176:179], v159 offset:49152
	ds_read_b128 v[180:183], v159 offset:50176
	ds_read_b128 v[184:187], v159 offset:51200
	ds_read_b128 v[188:191], v159 offset:52224
	ds_read_b128 v[194:197], v159 offset:53248
	ds_read_b128 v[198:201], v159 offset:54272
	ds_read_b128 v[204:207], v159 offset:55296
	ds_read_b128 v[208:211], v159 offset:56320
	global_load_lds_dwordx4 v[154:155], off
	s_add_i32 m0, s16, 0x2000
	s_add_u32 s16, s20, 0xb0080
	v_lshl_add_u64 v[154:155], v[212:213], 0, s[94:95]
	s_addc_u32 s17, s21, 0
	s_add_i32 s20, s44, s39
	global_load_lds_dwordx4 v[154:155], off
	v_lshl_add_u64 v[154:155], s[16:17], 0, v[192:193]
	s_mov_b32 m0, s20
	s_nop 0
	global_load_lds_dwordx4 v[154:155], off
	v_lshl_add_u64 v[154:155], s[16:17], 0, v[144:145]
	s_add_i32 m0, s20, 0x2000
	s_nop 0
	global_load_lds_dwordx4 v[154:155], off
	v_lshl_add_u64 v[154:155], v[214:215], 0, s[94:95]
	s_mov_b32 m0, s51
	s_nop 0
	global_load_lds_dwordx4 v[154:155], off
	v_lshl_add_u64 v[154:155], v[216:217], 0, s[94:95]
	s_mov_b32 m0, s76
	s_nop 0
	global_load_lds_dwordx4 v[154:155], off
	s_waitcnt vmcnt(8)
	s_waitcnt lgkmcnt(0)
	s_barrier
	s_waitcnt lgkmcnt(0)
	v_mfma_f32_16x16x32_bf16 v[60:63], v[64:67], v[176:179], v[60:63]
	v_mfma_f32_16x16x32_bf16 v[56:59], v[80:83], v[176:179], v[56:59]
	v_mfma_f32_16x16x32_bf16 v[52:55], v[64:67], v[184:187], v[52:55]
	v_mfma_f32_16x16x32_bf16 v[48:51], v[80:83], v[184:187], v[48:51]
	v_mfma_f32_16x16x32_bf16 v[28:31], v[64:67], v[194:197], v[28:31]
	v_mfma_f32_16x16x32_bf16 v[24:27], v[80:83], v[194:197], v[24:27]
	v_mfma_f32_16x16x32_bf16 v[16:19], v[64:67], v[204:207], v[16:19]
	v_mfma_f32_16x16x32_bf16 v[8:11], v[80:83], v[204:207], v[8:11]
	v_mfma_f32_16x16x32_bf16 v[60:63], v[68:71], v[180:183], v[60:63]
	v_mfma_f32_16x16x32_bf16 v[56:59], v[92:95], v[180:183], v[56:59]
	v_mfma_f32_16x16x32_bf16 v[52:55], v[68:71], v[188:191], v[52:55]
	v_mfma_f32_16x16x32_bf16 v[48:51], v[92:95], v[188:191], v[48:51]
	v_mfma_f32_16x16x32_bf16 v[28:31], v[68:71], v[198:201], v[28:31]
	v_mfma_f32_16x16x32_bf16 v[24:27], v[92:95], v[198:201], v[24:27]
	v_mfma_f32_16x16x32_bf16 v[16:19], v[68:71], v[208:211], v[16:19]
	v_mfma_f32_16x16x32_bf16 v[8:11], v[92:95], v[208:211], v[8:11]
	v_mfma_f32_16x16x32_bf16 v[44:47], v[160:163], v[176:179], v[44:47]
	v_mfma_f32_16x16x32_bf16 v[40:43], v[168:171], v[176:179], v[40:43]
	v_mfma_f32_16x16x32_bf16 v[36:39], v[160:163], v[184:187], v[36:39]
	v_mfma_f32_16x16x32_bf16 v[32:35], v[168:171], v[184:187], v[32:35]
	v_mfma_f32_16x16x32_bf16 v[20:23], v[160:163], v[194:197], v[20:23]
	v_mfma_f32_16x16x32_bf16 v[12:15], v[168:171], v[194:197], v[12:15]
	v_mfma_f32_16x16x32_bf16 v[4:7], v[160:163], v[204:207], v[4:7]
	v_mfma_f32_16x16x32_bf16 v[0:3], v[168:171], v[204:207], v[0:3]
	v_mfma_f32_16x16x32_bf16 v[44:47], v[164:167], v[180:183], v[44:47]
	v_mfma_f32_16x16x32_bf16 v[40:43], v[172:175], v[180:183], v[40:43]
	v_mfma_f32_16x16x32_bf16 v[36:39], v[164:167], v[188:191], v[36:39]
	v_mfma_f32_16x16x32_bf16 v[32:35], v[172:175], v[188:191], v[32:35]
	v_mfma_f32_16x16x32_bf16 v[20:23], v[164:167], v[198:201], v[20:23]
	v_mfma_f32_16x16x32_bf16 v[12:15], v[172:175], v[198:201], v[12:15]
	v_mfma_f32_16x16x32_bf16 v[4:7], v[164:167], v[208:211], v[4:7]
	v_mfma_f32_16x16x32_bf16 v[0:3], v[172:175], v[208:211], v[0:3]
	s_barrier
	s_add_i32 vcc_lo, vcc_lo, 2
	s_add_u32 s80, s80, 0x100
	s_addc_u32 s81, s81, 0
	s_cmp_gt_u32 vcc_lo, 41
	s_mov_b64 s[16:17], s[18:19]
	s_cbranch_scc0 .LBB0_1411
